# v21 + in the 16-read load segments the LDS-DMA group between the 8th and 9th ds_read moved behind the 16th (all fragment reads first), 5 GEMM loops
# baseline (speedup 1.0000x reference)
;     __device__ __forceinline__ bool next(int i, Unit& u) const { if (i >= 2) return false; const int xcd = c & 7, off = c >> 3; u.pm = 16 * i + 4 * (xcd >> 1) + (off & 3); u.pn = 8 * (xcd & 1) + (off >> 2); return true; }
; #define PG8_STAGE(bufoff, gbase, voff) do { _Pragma("unroll") for (int _i = 0; _i < 2; ++_i) \
;         __builtin_amdgcn_global_load_lds((const unsigned*)((const char*)(gbase) + (voff)[_i]), (PG8_LAS unsigned*)(lds + (bufoff) + ldsw + _i * 8192), 16, 0, 0); } while (0)
; #define PG8_LDA(dst, b, h) do { _Pragma("unroll") for (int m = 0; m < 4; ++m) _Pragma("unroll") for (int k = 0; k < 2; ++k) dst[m][k] = *(const PG8_LAS bf16x8*)(lds + PG8_SA(b, h) + aoff + m * 2048 + k * 1024); } while (0)
; #define PG8_WAIT_V(n) asm volatile("s_waitcnt vmcnt(" #n ")" ::: "memory")
; #define PG8_BAR __builtin_amdgcn_s_barrier()
; template <class Epi, class Sched, bool ALIGN_EPI = false, bool SP2 = false>
; __device__ __forceinline__ void gemm_phase(PG8_LAS unsigned char* lds, const Gemm g, const Sched& S, const Epi& E) {
;     ...
;         const bool has_next = S.next(ui + 1, nxt);
;         const char* nA = has_next ? (const char*)g.A + (size_t)nxt.pm * tstep : cA; const char* nB = has_next ? (const char*)g.Bt + (size_t)nxt.pn * tstep : cB;
;         constexpr int NSEG = Epi::HAS_MID ? 2 : 1; int t = 0;
; #pragma unroll
;         for (int seg = 0; seg < NSEG; ++seg) { const int tend = (seg + 1 < NSEG) ? (nt >> 1) : nt;
;         for (; t < tend; t += 2) {
;             const bool last = (t == nt - 2);
;             const char* a1 = cA + (size_t)(t + 1) * kstep;
;             const char* a2 = last ? nA : cA + (size_t)(t + 2) * kstep; const char* b2 = last ? nB : cB + (size_t)(t + 2) * kstep;
;             const char* a3 = a2 + kstep; const char* b3 = b2 + kstep;
;             if (last && has_next) S.a_ready(nxt);
;             if constexpr (SP2) {
;             PG8_LDB(B0, 0, 0); PG8_LDB(B1, 0, 1); PG8_SCHED; PG8_LDA(At, 0, 0); PG8_STAGE(PG8_SA(1, 1), a1 + hstep, voffA);
;             PG8_WAIT_V(8); PG8_WAIT_L(0); PG8_BAR; PG8_MMA(0, 0, At, B0); PG8_MMA(0, 1, At, B1); PG8_BAR; PG8_SCHED;
;             PG8_LDA(At, 0, 1); PG8_STAGE(PG8_SB(0, 0), b2, voffB); PG8_STAGE(PG8_SB(0, 1), b2 + hstep, voffB); PG8_STAGE(PG8_SA(0, 0), a2, voffA);
;             PG8_WAIT_V(8); PG8_WAIT_L(0); PG8_BAR; PG8_MMA(1, 0, At, B0); PG8_MMA(1, 1, At, B1); PG8_BAR; PG8_SCHED;
.LBB0_114:
	s_ashr_i32 s25, s24, 31
	s_lshl_b64 s[42:43], s[24:25], 21
	s_add_u32 s42, s66, s42
	s_addc_u32 s43, s67, s43
	s_and_b64 s[44:45], s[0:1], exec
	s_cselect_b32 s25, s43, s49
	s_cselect_b32 s64, s42, s48
	s_ashr_i32 s19, s18, 31
	s_lshl_b64 s[44:45], s[18:19], 21
	s_add_u32 s44, s4, s44
	s_addc_u32 s45, s5, s45
	s_and_b64 s[68:69], s[0:1], exec
	s_cselect_b32 s19, s45, s51
	s_cselect_b32 s65, s44, s50
	s_add_u32 s48, s48, 0xc000
	s_addc_u32 s49, s49, 0
	s_add_u32 s68, s50, 0x10000
	s_addc_u32 s69, s51, 0
	s_mov_b32 s76, -2
	s_nop 3
	s_add_u32 s50, s48, 0x4000
	s_addc_u32 s51, s49, 0
	s_cmp_eq_u32 s76, 60
	s_cselect_b32 s74, s64, s50
	s_cselect_b32 s75, s25, s51
	s_cselect_b32 s72, s65, s68
	s_cselect_b32 s73, s19, s69
	s_add_u32 s50, s74, 0x8000
	s_addc_u32 s51, s75, 0
	s_sub_u32 s50, s48, 0x4000
	s_subb_u32 s51, s49, 0
	ds_read_b128 v[154:157], v150
	ds_read_b128 v[158:161], v150 offset:1024
	ds_read_b128 v[162:165], v150 offset:2048
	ds_read_b128 v[166:169], v150 offset:3072
	ds_read_b128 v[170:173], v151
	ds_read_b128 v[174:177], v151 offset:1024
	ds_read_b128 v[180:183], v151 offset:2048
	ds_read_b128 v[184:187], v151 offset:3072
	ds_read_b128 v[188:191], v152
	ds_read_b128 v[196:199], v152 offset:1024
	ds_read_b128 v[200:203], v152 offset:2048
	ds_read_b128 v[204:207], v152 offset:3072
	ds_read_b128 v[208:211], v152 offset:4096
	ds_read_b128 v[212:215], v152 offset:5120
	ds_read_b128 v[216:219], v152 offset:6144
	ds_read_b128 v[220:223], v152 offset:7168
	s_mov_b32 m0, s58
	s_nop 0
	global_load_lds_dwordx4 v130, s[50:51]
	s_mov_b32 m0, s59
	s_nop 0
	global_load_lds_dwordx4 v134, s[50:51]
	s_add_i32 m0, s28, 0xc000
	s_nop 0
	global_load_lds_dwordx4 v140, s[48:49]
	s_add_i32 m0, s28, 0xe000
	s_nop 0
	global_load_lds_dwordx4 v142, s[48:49]
	s_waitcnt vmcnt(8)
	s_waitcnt lgkmcnt(0)
	s_barrier
	s_waitcnt lgkmcnt(0)
	v_mfma_f32_16x16x32_bf16 v[126:129], v[154:157], v[188:191], 0
	v_mfma_f32_16x16x32_bf16 v[126:129], v[158:161], v[196:199], v[126:129]
	v_mfma_f32_16x16x32_bf16 v[110:113], v[158:161], v[204:207], 0
	v_mfma_f32_16x16x32_bf16 v[110:113], v[154:157], v[200:203], v[110:113]
	v_mfma_f32_16x16x32_bf16 v[94:97], v[154:157], v[208:211], 0
	v_mfma_f32_16x16x32_bf16 v[94:97], v[158:161], v[212:215], v[94:97]
	v_mfma_f32_16x16x32_bf16 v[78:81], v[158:161], v[220:223], 0
	v_mfma_f32_16x16x32_bf16 v[78:81], v[154:157], v[216:219], v[78:81]
	v_mfma_f32_16x16x32_bf16 v[70:73], v[162:165], v[216:219], 0
	v_mfma_f32_16x16x32_bf16 v[70:73], v[166:169], v[220:223], v[70:73]
	v_mfma_f32_16x16x32_bf16 v[86:89], v[166:169], v[212:215], 0
	v_mfma_f32_16x16x32_bf16 v[86:89], v[162:165], v[208:211], v[86:89]
	v_mfma_f32_16x16x32_bf16 v[102:105], v[162:165], v[200:203], 0
	v_mfma_f32_16x16x32_bf16 v[102:105], v[166:169], v[204:207], v[102:105]
	v_mfma_f32_16x16x32_bf16 v[118:121], v[166:169], v[196:199], 0
	v_mfma_f32_16x16x32_bf16 v[118:121], v[162:165], v[188:191], v[118:121]
	v_mfma_f32_16x16x32_bf16 v[122:125], v[170:173], v[188:191], 0
	v_mfma_f32_16x16x32_bf16 v[122:125], v[174:177], v[196:199], v[122:125]
	v_mfma_f32_16x16x32_bf16 v[106:109], v[174:177], v[204:207], 0
	v_mfma_f32_16x16x32_bf16 v[106:109], v[170:173], v[200:203], v[106:109]
	v_mfma_f32_16x16x32_bf16 v[90:93], v[170:173], v[208:211], 0
	v_mfma_f32_16x16x32_bf16 v[90:93], v[174:177], v[212:215], v[90:93]
	v_mfma_f32_16x16x32_bf16 v[74:77], v[174:177], v[220:223], 0
	v_mfma_f32_16x16x32_bf16 v[74:77], v[170:173], v[216:219], v[74:77]
	v_mfma_f32_16x16x32_bf16 v[66:69], v[180:183], v[216:219], 0
	v_mfma_f32_16x16x32_bf16 v[66:69], v[184:187], v[220:223], v[66:69]
	v_mfma_f32_16x16x32_bf16 v[82:85], v[184:187], v[212:215], 0
	v_mfma_f32_16x16x32_bf16 v[82:85], v[180:183], v[208:211], v[82:85]
	v_mfma_f32_16x16x32_bf16 v[98:101], v[180:183], v[200:203], 0
	v_mfma_f32_16x16x32_bf16 v[98:101], v[184:187], v[204:207], v[98:101]
	v_mfma_f32_16x16x32_bf16 v[114:117], v[184:187], v[196:199], 0
	v_mfma_f32_16x16x32_bf16 v[114:117], v[180:183], v[188:191], v[114:117]
	s_barrier
	s_add_i32 s77, s61, s3
	s_mov_b32 m0, s77
	ds_read_b128 v[188:191], v152 offset:16384
	ds_read_b128 v[196:199], v152 offset:17408
	ds_read_b128 v[200:203], v152 offset:18432
	ds_read_b128 v[204:207], v152 offset:19456
	ds_read_b128 v[208:211], v152 offset:20480
	ds_read_b128 v[212:215], v152 offset:21504
	ds_read_b128 v[216:219], v152 offset:22528
	ds_read_b128 v[220:223], v152 offset:23552
	global_load_lds_dwordx4 v132, s[72:73]
	s_add_i32 m0, s77, 0x2000
	s_add_u32 s78, s72, 0x4000
	s_addc_u32 s79, s73, 0
	s_add_i32 s77, s62, s3
	global_load_lds_dwordx4 v136, s[72:73]
	s_mov_b32 m0, s77
	s_nop 0
	global_load_lds_dwordx4 v132, s[78:79]
	s_add_i32 m0, s77, 0x2000
	s_nop 0
	global_load_lds_dwordx4 v136, s[78:79]
	s_waitcnt vmcnt(6)
	s_waitcnt lgkmcnt(0)
	s_barrier
; #define PG8_STAGE(bufoff, gbase, voff) do { _Pragma("unroll") for (int _i = 0; _i < 2; ++_i) \
;         __builtin_amdgcn_global_load_lds((const unsigned*)((const char*)(gbase) + (voff)[_i]), (PG8_LAS unsigned*)(lds + (bufoff) + ldsw + _i * 8192), 16, 0, 0); } while (0)
; #define PG8_LDA(dst, b, h) do { _Pragma("unroll") for (int m = 0; m < 4; ++m) _Pragma("unroll") for (int k = 0; k < 2; ++k) dst[m][k] = *(const PG8_LAS bf16x8*)(lds + PG8_SA(b, h) + aoff + m * 2048 + k * 1024); } while (0)
; #define PG8_LDB(dst, b, h) do { _Pragma("unroll") for (int n = 0; n < 2; ++n) _Pragma("unroll") for (int k = 0; k < 2; ++k) dst[n][k] = *(const PG8_LAS bf16x8*)(lds + PG8_SB(b, h) + boff + n * 2048 + k * 1024); } while (0)
; #define PG8_MMA(ai, bj, At, Bt) do { __builtin_amdgcn_s_setprio(1); _Pragma("unroll") for (int m = 0; m < 4; ++m) _Pragma("unroll") for (int n = 0; n < 2; ++n) _Pragma("unroll") for (int k = 0; k < 2; ++k) \
;         acc[ai][bj][m][n] = __builtin_amdgcn_mfma_f32_16x16x32_bf16(Bt[n][k], At[m][k], acc[ai][bj][m][n], 0, 0, 0); __builtin_amdgcn_s_setprio(0); } while (0)
; #define PG8_WAIT_V(n) asm volatile("s_waitcnt vmcnt(" #n ")" ::: "memory")
; #define PG8_WAIT_L(n) asm volatile("s_waitcnt lgkmcnt(" #n ")" ::: "memory")
; #define PG8_BAR __builtin_amdgcn_s_barrier()
; #define PG8_SCHED __builtin_amdgcn_sched_barrier(0)
; template <class Epi, class Sched, bool ALIGN_EPI = false, bool SP2 = false>
; __device__ __forceinline__ void gemm_phase(PG8_LAS unsigned char* lds, const Gemm g, const Sched& S, const Epi& E) {
;     ...
;             PG8_WAIT_V(8); PG8_WAIT_L(0); PG8_BAR; PG8_MMA(1, 0, At, B0); PG8_MMA(1, 1, At, B1); PG8_BAR; PG8_SCHED;
;             PG8_LDB(B0, 1, 0); PG8_LDB(B1, 1, 1); PG8_SCHED; PG8_LDA(At, 1, 0); PG8_STAGE(PG8_SA(0, 1), a2 + hstep, voffA);
;             PG8_WAIT_V(8); PG8_WAIT_L(0); PG8_BAR; PG8_MMA(0, 0, At, B0); PG8_MMA(0, 1, At, B1); PG8_BAR; PG8_SCHED;
	s_waitcnt lgkmcnt(0)
	v_mfma_f32_16x16x32_bf16 v[62:65], v[154:157], v[188:191], 0
	v_mfma_f32_16x16x32_bf16 v[62:65], v[158:161], v[196:199], v[62:65]
	v_mfma_f32_16x16x32_bf16 v[46:49], v[158:161], v[204:207], 0
	v_mfma_f32_16x16x32_bf16 v[46:49], v[154:157], v[200:203], v[46:49]
	v_mfma_f32_16x16x32_bf16 v[30:33], v[154:157], v[208:211], 0
	v_mfma_f32_16x16x32_bf16 v[30:33], v[158:161], v[212:215], v[30:33]
	v_mfma_f32_16x16x32_bf16 v[14:17], v[158:161], v[220:223], 0
	v_mfma_f32_16x16x32_bf16 v[14:17], v[154:157], v[216:219], v[14:17]
	v_mfma_f32_16x16x32_bf16 v[6:9], v[162:165], v[216:219], 0
	v_mfma_f32_16x16x32_bf16 v[6:9], v[166:169], v[220:223], v[6:9]
	v_mfma_f32_16x16x32_bf16 v[22:25], v[166:169], v[212:215], 0
	v_mfma_f32_16x16x32_bf16 v[22:25], v[162:165], v[208:211], v[22:25]
	v_mfma_f32_16x16x32_bf16 v[38:41], v[162:165], v[200:203], 0
	v_mfma_f32_16x16x32_bf16 v[38:41], v[166:169], v[204:207], v[38:41]
	v_mfma_f32_16x16x32_bf16 v[54:57], v[166:169], v[196:199], 0
	v_mfma_f32_16x16x32_bf16 v[54:57], v[162:165], v[188:191], v[54:57]
	v_mfma_f32_16x16x32_bf16 v[58:61], v[170:173], v[188:191], 0
	v_mfma_f32_16x16x32_bf16 v[58:61], v[174:177], v[196:199], v[58:61]
	v_mfma_f32_16x16x32_bf16 v[42:45], v[174:177], v[204:207], 0
	v_mfma_f32_16x16x32_bf16 v[42:45], v[170:173], v[200:203], v[42:45]
	v_mfma_f32_16x16x32_bf16 v[26:29], v[170:173], v[208:211], 0
	v_mfma_f32_16x16x32_bf16 v[26:29], v[174:177], v[212:215], v[26:29]
	v_mfma_f32_16x16x32_bf16 v[10:13], v[174:177], v[220:223], 0
	v_mfma_f32_16x16x32_bf16 v[10:13], v[170:173], v[216:219], v[10:13]
	v_mfma_f32_16x16x32_bf16 v[2:5], v[180:183], v[216:219], 0
	v_mfma_f32_16x16x32_bf16 v[2:5], v[184:187], v[220:223], v[2:5]
	v_mfma_f32_16x16x32_bf16 v[18:21], v[184:187], v[212:215], 0
	v_mfma_f32_16x16x32_bf16 v[18:21], v[180:183], v[208:211], v[18:21]
	v_mfma_f32_16x16x32_bf16 v[34:37], v[180:183], v[200:203], 0
	v_mfma_f32_16x16x32_bf16 v[34:37], v[184:187], v[204:207], v[34:37]
	v_mfma_f32_16x16x32_bf16 v[50:53], v[184:187], v[196:199], 0
	v_mfma_f32_16x16x32_bf16 v[50:53], v[180:183], v[188:191], v[50:53]
	s_barrier
	s_add_i32 s77, 0, 0x18000
	v_add_u32_e32 v138, s77, v148
	s_add_i32 s78, 0, 0x1c000
	ds_read_b128 v[154:157], v138
	ds_read_b128 v[158:161], v138 offset:1024
	ds_read_b128 v[162:165], v138 offset:2048
	ds_read_b128 v[166:169], v138 offset:3072
	v_add_u32_e32 v138, s78, v148
	ds_read_b128 v[170:173], v138
	ds_read_b128 v[174:177], v138 offset:1024
	ds_read_b128 v[180:183], v138 offset:2048
	ds_read_b128 v[184:187], v138 offset:3072
	ds_read_b128 v[188:191], v152 offset:32768
	ds_read_b128 v[196:199], v152 offset:33792
	ds_read_b128 v[200:203], v152 offset:34816
	ds_read_b128 v[204:207], v152 offset:35840
	ds_read_b128 v[208:211], v152 offset:36864
	ds_read_b128 v[212:215], v152 offset:37888
	ds_read_b128 v[216:219], v152 offset:38912
	ds_read_b128 v[220:223], v152 offset:39936
	s_mov_b32 m0, s28
	s_nop 0
	global_load_lds_dwordx4 v130, s[74:75]
	s_mov_b32 m0, s29
	s_nop 0
	global_load_lds_dwordx4 v134, s[74:75]
	s_add_u32 s74, s74, 0x4000
	s_addc_u32 s75, s75, 0
	s_mov_b32 m0, s30
	s_nop 0
	global_load_lds_dwordx4 v130, s[74:75]
	s_mov_b32 m0, s31
	s_nop 0
	global_load_lds_dwordx4 v134, s[74:75]
	s_waitcnt vmcnt(8)
	s_waitcnt lgkmcnt(0)
	s_barrier
	s_waitcnt lgkmcnt(0)
	v_mfma_f32_16x16x32_bf16 v[126:129], v[154:157], v[188:191], v[126:129]
	v_mfma_f32_16x16x32_bf16 v[126:129], v[158:161], v[196:199], v[126:129]
	v_mfma_f32_16x16x32_bf16 v[110:113], v[158:161], v[204:207], v[110:113]
	v_mfma_f32_16x16x32_bf16 v[110:113], v[154:157], v[200:203], v[110:113]
	v_mfma_f32_16x16x32_bf16 v[94:97], v[154:157], v[208:211], v[94:97]
	v_mfma_f32_16x16x32_bf16 v[94:97], v[158:161], v[212:215], v[94:97]
	v_mfma_f32_16x16x32_bf16 v[78:81], v[158:161], v[220:223], v[78:81]
	v_mfma_f32_16x16x32_bf16 v[78:81], v[154:157], v[216:219], v[78:81]
	v_mfma_f32_16x16x32_bf16 v[70:73], v[162:165], v[216:219], v[70:73]
	v_mfma_f32_16x16x32_bf16 v[70:73], v[166:169], v[220:223], v[70:73]
	v_mfma_f32_16x16x32_bf16 v[86:89], v[166:169], v[212:215], v[86:89]
	v_mfma_f32_16x16x32_bf16 v[86:89], v[162:165], v[208:211], v[86:89]
	v_mfma_f32_16x16x32_bf16 v[102:105], v[162:165], v[200:203], v[102:105]
	v_mfma_f32_16x16x32_bf16 v[102:105], v[166:169], v[204:207], v[102:105]
	v_mfma_f32_16x16x32_bf16 v[118:121], v[166:169], v[196:199], v[118:121]
	v_mfma_f32_16x16x32_bf16 v[118:121], v[162:165], v[188:191], v[118:121]
	v_mfma_f32_16x16x32_bf16 v[122:125], v[170:173], v[188:191], v[122:125]
	v_mfma_f32_16x16x32_bf16 v[122:125], v[174:177], v[196:199], v[122:125]
	v_mfma_f32_16x16x32_bf16 v[106:109], v[174:177], v[204:207], v[106:109]
	v_mfma_f32_16x16x32_bf16 v[106:109], v[170:173], v[200:203], v[106:109]
	v_mfma_f32_16x16x32_bf16 v[90:93], v[170:173], v[208:211], v[90:93]
	v_mfma_f32_16x16x32_bf16 v[90:93], v[174:177], v[212:215], v[90:93]
	v_mfma_f32_16x16x32_bf16 v[74:77], v[174:177], v[220:223], v[74:77]
	v_mfma_f32_16x16x32_bf16 v[74:77], v[170:173], v[216:219], v[74:77]
	v_mfma_f32_16x16x32_bf16 v[66:69], v[180:183], v[216:219], v[66:69]
	v_mfma_f32_16x16x32_bf16 v[66:69], v[184:187], v[220:223], v[66:69]
	v_mfma_f32_16x16x32_bf16 v[82:85], v[184:187], v[212:215], v[82:85]
	v_mfma_f32_16x16x32_bf16 v[82:85], v[180:183], v[208:211], v[82:85]
	v_mfma_f32_16x16x32_bf16 v[98:101], v[180:183], v[200:203], v[98:101]
	v_mfma_f32_16x16x32_bf16 v[98:101], v[184:187], v[204:207], v[98:101]
	v_mfma_f32_16x16x32_bf16 v[114:117], v[184:187], v[196:199], v[114:117]
	v_mfma_f32_16x16x32_bf16 v[114:117], v[180:183], v[188:191], v[114:117]
	s_barrier
; #define PG8_STAGE(bufoff, gbase, voff) do { _Pragma("unroll") for (int _i = 0; _i < 2; ++_i) \
;         __builtin_amdgcn_global_load_lds((const unsigned*)((const char*)(gbase) + (voff)[_i]), (PG8_LAS unsigned*)(lds + (bufoff) + ldsw + _i * 8192), 16, 0, 0); } while (0)
; #define PG8_LDA(dst, b, h) do { _Pragma("unroll") for (int m = 0; m < 4; ++m) _Pragma("unroll") for (int k = 0; k < 2; ++k) dst[m][k] = *(const PG8_LAS bf16x8*)(lds + PG8_SA(b, h) + aoff + m * 2048 + k * 1024); } while (0)
; #define PG8_LDB(dst, b, h) do { _Pragma("unroll") for (int n = 0; n < 2; ++n) _Pragma("unroll") for (int k = 0; k < 2; ++k) dst[n][k] = *(const PG8_LAS bf16x8*)(lds + PG8_SB(b, h) + boff + n * 2048 + k * 1024); } while (0)
; template <class Epi, class Sched, bool ALIGN_EPI = false, bool SP2 = false>
; __device__ __forceinline__ void gemm_phase(PG8_LAS unsigned char* lds, const Gemm g, const Sched& S, const Epi& E) {
;     ...
;         for (; t < tend; t += 2) {
;             const bool last = (t == nt - 2);
;             const char* a1 = cA + (size_t)(t + 1) * kstep;
;             const char* a2 = last ? nA : cA + (size_t)(t + 2) * kstep; const char* b2 = last ? nB : cB + (size_t)(t + 2) * kstep;
;             const char* a3 = a2 + kstep; const char* b3 = b2 + kstep;
;             if (last && has_next) S.a_ready(nxt);
;             if constexpr (SP2) {
;             PG8_LDB(B0, 0, 0); PG8_LDB(B1, 0, 1); PG8_SCHED; PG8_LDA(At, 0, 0); PG8_STAGE(PG8_SA(1, 1), a1 + hstep, voffA);
;             PG8_WAIT_V(8); PG8_WAIT_L(0); PG8_BAR; PG8_MMA(0, 0, At, B0); PG8_MMA(0, 1, At, B1); PG8_BAR; PG8_SCHED;
;             PG8_LDA(At, 0, 1); PG8_STAGE(PG8_SB(0, 0), b2, voffB); PG8_STAGE(PG8_SB(0, 1), b2 + hstep, voffB); PG8_STAGE(PG8_SA(0, 0), a2, voffA);
;             PG8_WAIT_V(8); PG8_WAIT_L(0); PG8_BAR; PG8_MMA(1, 0, At, B0); PG8_MMA(1, 1, At, B1); PG8_BAR; PG8_SCHED;
;             PG8_LDB(B0, 1, 0); PG8_LDB(B1, 1, 1); PG8_SCHED; PG8_LDA(At, 1, 0); PG8_STAGE(PG8_SA(0, 1), a2 + hstep, voffA);
;             PG8_WAIT_V(8); PG8_WAIT_L(0); PG8_BAR; PG8_MMA(0, 0, At, B0); PG8_MMA(0, 1, At, B1); PG8_BAR; PG8_SCHED;
;             PG8_LDA(At, 1, 1); PG8_STAGE(PG8_SB(1, 0), b3, voffB); PG8_STAGE(PG8_SB(1, 1), b3 + hstep, voffB); PG8_STAGE(PG8_SA(1, 0), a3, voffA);
;             PG8_WAIT_V(8); PG8_WAIT_L(0); PG8_BAR; PG8_MMA(1, 0, At, B0); PG8_MMA(1, 1, At, B1); PG8_BAR; PG8_SCHED;
	s_add_u32 s74, s72, 0x8000
	s_addc_u32 s75, s73, 0
	s_add_i32 s77, s77, s3
	s_mov_b32 m0, s77
	ds_read_b128 v[188:191], v152 offset:49152
	ds_read_b128 v[196:199], v152 offset:50176
	ds_read_b128 v[200:203], v152 offset:51200
	ds_read_b128 v[204:207], v152 offset:52224
	ds_read_b128 v[208:211], v152 offset:53248
	ds_read_b128 v[212:215], v152 offset:54272
	ds_read_b128 v[216:219], v152 offset:55296
	ds_read_b128 v[220:223], v152 offset:56320
	global_load_lds_dwordx4 v132, s[74:75]
	s_add_i32 m0, s77, 0x2000
	s_add_u32 s72, s72, 0xc000
	v_lshl_add_u64 v[224:225], s[74:75], 0, v[136:137]
	s_addc_u32 s73, s73, 0
	s_add_i32 s74, s78, s3
	global_load_lds_dwordx4 v[224:225], off
	s_mov_b32 m0, s74
	s_nop 0
	global_load_lds_dwordx4 v132, s[72:73]
	s_add_i32 m0, s74, 0x2000
	s_nop 0
	global_load_lds_dwordx4 v136, s[72:73]
	s_add_i32 s76, s76, 2
	s_add_u32 s48, s48, 0x10000
	s_addc_u32 s49, s49, 0
	s_add_u32 s68, s68, 0x10000
	s_addc_u32 s69, s69, 0
	s_add_u32 s50, s48, 0x4000
	s_addc_u32 s51, s49, 0
	s_cmp_eq_u32 s76, 60
	s_cselect_b32 s74, s64, s50
	s_cselect_b32 s75, s25, s51
	s_cselect_b32 s72, s65, s68
	s_cselect_b32 s73, s19, s69
	s_add_u32 s50, s74, 0x8000
	s_addc_u32 s51, s75, 0
	s_sub_u32 s50, s48, 0x4000
	s_subb_u32 s51, s49, 0
	s_cmp_gt_u32 s76, 61
	s_waitcnt vmcnt(6)
	s_waitcnt lgkmcnt(0)
	s_barrier
	s_waitcnt lgkmcnt(0)
	v_mfma_f32_16x16x32_bf16 v[62:65], v[154:157], v[188:191], v[62:65]
	v_mfma_f32_16x16x32_bf16 v[62:65], v[158:161], v[196:199], v[62:65]
	v_mfma_f32_16x16x32_bf16 v[46:49], v[158:161], v[204:207], v[46:49]
	v_mfma_f32_16x16x32_bf16 v[46:49], v[154:157], v[200:203], v[46:49]
	v_mfma_f32_16x16x32_bf16 v[30:33], v[154:157], v[208:211], v[30:33]
	v_mfma_f32_16x16x32_bf16 v[30:33], v[158:161], v[212:215], v[30:33]
	v_mfma_f32_16x16x32_bf16 v[14:17], v[158:161], v[220:223], v[14:17]
	v_mfma_f32_16x16x32_bf16 v[14:17], v[154:157], v[216:219], v[14:17]
	v_mfma_f32_16x16x32_bf16 v[6:9], v[162:165], v[216:219], v[6:9]
	v_mfma_f32_16x16x32_bf16 v[6:9], v[166:169], v[220:223], v[6:9]
	v_mfma_f32_16x16x32_bf16 v[22:25], v[166:169], v[212:215], v[22:25]
	v_mfma_f32_16x16x32_bf16 v[22:25], v[162:165], v[208:211], v[22:25]
	v_mfma_f32_16x16x32_bf16 v[38:41], v[162:165], v[200:203], v[38:41]
	v_mfma_f32_16x16x32_bf16 v[38:41], v[166:169], v[204:207], v[38:41]
	v_mfma_f32_16x16x32_bf16 v[54:57], v[166:169], v[196:199], v[54:57]
	v_mfma_f32_16x16x32_bf16 v[54:57], v[162:165], v[188:191], v[54:57]
	v_mfma_f32_16x16x32_bf16 v[58:61], v[170:173], v[188:191], v[58:61]
	v_mfma_f32_16x16x32_bf16 v[58:61], v[174:177], v[196:199], v[58:61]
	v_mfma_f32_16x16x32_bf16 v[42:45], v[174:177], v[204:207], v[42:45]
	v_mfma_f32_16x16x32_bf16 v[42:45], v[170:173], v[200:203], v[42:45]
	v_mfma_f32_16x16x32_bf16 v[26:29], v[170:173], v[208:211], v[26:29]
	v_mfma_f32_16x16x32_bf16 v[26:29], v[174:177], v[212:215], v[26:29]
	v_mfma_f32_16x16x32_bf16 v[10:13], v[174:177], v[220:223], v[10:13]
	v_mfma_f32_16x16x32_bf16 v[10:13], v[170:173], v[216:219], v[10:13]
	v_mfma_f32_16x16x32_bf16 v[2:5], v[180:183], v[216:219], v[2:5]
	v_mfma_f32_16x16x32_bf16 v[2:5], v[184:187], v[220:223], v[2:5]
	v_mfma_f32_16x16x32_bf16 v[18:21], v[184:187], v[212:215], v[18:21]
	v_mfma_f32_16x16x32_bf16 v[18:21], v[180:183], v[208:211], v[18:21]
	v_mfma_f32_16x16x32_bf16 v[34:37], v[180:183], v[200:203], v[34:37]
	v_mfma_f32_16x16x32_bf16 v[34:37], v[184:187], v[204:207], v[34:37]
	v_mfma_f32_16x16x32_bf16 v[50:53], v[184:187], v[196:199], v[50:53]
	v_mfma_f32_16x16x32_bf16 v[50:53], v[180:183], v[188:191], v[50:53]
	s_barrier
.LBB0_115:
	ds_read_b128 v[154:157], v150
	ds_read_b128 v[158:161], v150 offset:1024
	ds_read_b128 v[162:165], v150 offset:2048
	ds_read_b128 v[166:169], v150 offset:3072
	ds_read_b128 v[170:173], v151
	ds_read_b128 v[174:177], v151 offset:1024
	ds_read_b128 v[180:183], v151 offset:2048
	ds_read_b128 v[184:187], v151 offset:3072
	ds_read_b128 v[188:191], v152
	ds_read_b128 v[196:199], v152 offset:1024
	ds_read_b128 v[200:203], v152 offset:2048
	ds_read_b128 v[204:207], v152 offset:3072
	ds_read_b128 v[208:211], v152 offset:4096
	ds_read_b128 v[212:215], v152 offset:5120
	ds_read_b128 v[216:219], v152 offset:6144
	ds_read_b128 v[220:223], v152 offset:7168
	s_mov_b32 m0, s58
	s_nop 0
	global_load_lds_dwordx4 v130, s[50:51]
	s_mov_b32 m0, s59
	s_nop 0
	global_load_lds_dwordx4 v134, s[50:51]
	s_add_i32 m0, s28, 0xc000
	s_nop 0
	global_load_lds_dwordx4 v140, s[48:49]
	s_add_i32 m0, s28, 0xe000
	s_nop 0
	global_load_lds_dwordx4 v142, s[48:49]
	s_waitcnt vmcnt(8)
	s_waitcnt lgkmcnt(0)
	s_barrier
; #define PG8_STAGE(bufoff, gbase, voff) do { _Pragma("unroll") for (int _i = 0; _i < 2; ++_i) \
;         __builtin_amdgcn_global_load_lds((const unsigned*)((const char*)(gbase) + (voff)[_i]), (PG8_LAS unsigned*)(lds + (bufoff) + ldsw + _i * 8192), 16, 0, 0); } while (0)
; #define PG8_LDA(dst, b, h) do { _Pragma("unroll") for (int m = 0; m < 4; ++m) _Pragma("unroll") for (int k = 0; k < 2; ++k) dst[m][k] = *(const PG8_LAS bf16x8*)(lds + PG8_SA(b, h) + aoff + m * 2048 + k * 1024); } while (0)
; #define PG8_MMA(ai, bj, At, Bt) do { __builtin_amdgcn_s_setprio(1); _Pragma("unroll") for (int m = 0; m < 4; ++m) _Pragma("unroll") for (int n = 0; n < 2; ++n) _Pragma("unroll") for (int k = 0; k < 2; ++k) \
;         acc[ai][bj][m][n] = __builtin_amdgcn_mfma_f32_16x16x32_bf16(Bt[n][k], At[m][k], acc[ai][bj][m][n], 0, 0, 0); __builtin_amdgcn_s_setprio(0); } while (0)
; #define PG8_WAIT_V(n) asm volatile("s_waitcnt vmcnt(" #n ")" ::: "memory")
; #define PG8_WAIT_L(n) asm volatile("s_waitcnt lgkmcnt(" #n ")" ::: "memory")
; #define PG8_BAR __builtin_amdgcn_s_barrier()
; #define PG8_SCHED __builtin_amdgcn_sched_barrier(0)
; template <class Epi, class Sched, bool ALIGN_EPI = false, bool SP2 = false>
; __device__ __forceinline__ void gemm_phase(PG8_LAS unsigned char* lds, const Gemm g, const Sched& S, const Epi& E) {
;     ...
;             PG8_WAIT_V(8); PG8_WAIT_L(0); PG8_BAR; PG8_MMA(0, 0, At, B0); PG8_MMA(0, 1, At, B1); PG8_BAR; PG8_SCHED;
;             PG8_LDA(At, 0, 1); PG8_STAGE(PG8_SB(0, 0), b2, voffB); PG8_STAGE(PG8_SB(0, 1), b2 + hstep, voffB); PG8_STAGE(PG8_SA(0, 0), a2, voffA);
;             PG8_WAIT_V(8); PG8_WAIT_L(0); PG8_BAR; PG8_MMA(1, 0, At, B0); PG8_MMA(1, 1, At, B1); PG8_BAR; PG8_SCHED;
	s_waitcnt lgkmcnt(0)
	v_mfma_f32_16x16x32_bf16 v[126:129], v[154:157], v[188:191], v[126:129]
	v_mfma_f32_16x16x32_bf16 v[126:129], v[158:161], v[196:199], v[126:129]
	v_mfma_f32_16x16x32_bf16 v[110:113], v[158:161], v[204:207], v[110:113]
	v_mfma_f32_16x16x32_bf16 v[110:113], v[154:157], v[200:203], v[110:113]
	v_mfma_f32_16x16x32_bf16 v[94:97], v[154:157], v[208:211], v[94:97]
	v_mfma_f32_16x16x32_bf16 v[94:97], v[158:161], v[212:215], v[94:97]
	v_mfma_f32_16x16x32_bf16 v[78:81], v[158:161], v[220:223], v[78:81]
	v_mfma_f32_16x16x32_bf16 v[78:81], v[154:157], v[216:219], v[78:81]
	v_mfma_f32_16x16x32_bf16 v[70:73], v[162:165], v[216:219], v[70:73]
	v_mfma_f32_16x16x32_bf16 v[70:73], v[166:169], v[220:223], v[70:73]
	v_mfma_f32_16x16x32_bf16 v[86:89], v[166:169], v[212:215], v[86:89]
	v_mfma_f32_16x16x32_bf16 v[86:89], v[162:165], v[208:211], v[86:89]
	v_mfma_f32_16x16x32_bf16 v[102:105], v[162:165], v[200:203], v[102:105]
	v_mfma_f32_16x16x32_bf16 v[102:105], v[166:169], v[204:207], v[102:105]
	v_mfma_f32_16x16x32_bf16 v[118:121], v[166:169], v[196:199], v[118:121]
	v_mfma_f32_16x16x32_bf16 v[118:121], v[162:165], v[188:191], v[118:121]
	v_mfma_f32_16x16x32_bf16 v[122:125], v[170:173], v[188:191], v[122:125]
	v_mfma_f32_16x16x32_bf16 v[122:125], v[174:177], v[196:199], v[122:125]
	v_mfma_f32_16x16x32_bf16 v[106:109], v[174:177], v[204:207], v[106:109]
	v_mfma_f32_16x16x32_bf16 v[106:109], v[170:173], v[200:203], v[106:109]
	v_mfma_f32_16x16x32_bf16 v[90:93], v[170:173], v[208:211], v[90:93]
	v_mfma_f32_16x16x32_bf16 v[90:93], v[174:177], v[212:215], v[90:93]
	v_mfma_f32_16x16x32_bf16 v[74:77], v[174:177], v[220:223], v[74:77]
	v_mfma_f32_16x16x32_bf16 v[74:77], v[170:173], v[216:219], v[74:77]
	v_mfma_f32_16x16x32_bf16 v[66:69], v[180:183], v[216:219], v[66:69]
	v_mfma_f32_16x16x32_bf16 v[66:69], v[184:187], v[220:223], v[66:69]
	v_mfma_f32_16x16x32_bf16 v[82:85], v[184:187], v[212:215], v[82:85]
	v_mfma_f32_16x16x32_bf16 v[82:85], v[180:183], v[208:211], v[82:85]
	v_mfma_f32_16x16x32_bf16 v[98:101], v[180:183], v[200:203], v[98:101]
	v_mfma_f32_16x16x32_bf16 v[98:101], v[184:187], v[204:207], v[98:101]
	v_mfma_f32_16x16x32_bf16 v[114:117], v[184:187], v[196:199], v[114:117]
	v_mfma_f32_16x16x32_bf16 v[114:117], v[180:183], v[188:191], v[114:117]
	s_barrier
	s_add_i32 s77, s61, s3
	s_mov_b32 m0, s77
	ds_read_b128 v[188:191], v152 offset:16384
	ds_read_b128 v[196:199], v152 offset:17408
	ds_read_b128 v[200:203], v152 offset:18432
	ds_read_b128 v[204:207], v152 offset:19456
	ds_read_b128 v[208:211], v152 offset:20480
	ds_read_b128 v[212:215], v152 offset:21504
	ds_read_b128 v[216:219], v152 offset:22528
	ds_read_b128 v[220:223], v152 offset:23552
	global_load_lds_dwordx4 v132, s[72:73]
	s_add_i32 m0, s77, 0x2000
	s_add_u32 s78, s72, 0x4000
	s_addc_u32 s79, s73, 0
	s_add_i32 s77, s62, s3
	global_load_lds_dwordx4 v136, s[72:73]
	s_mov_b32 m0, s77
	s_nop 0
	global_load_lds_dwordx4 v132, s[78:79]
	s_add_i32 m0, s77, 0x2000
	s_nop 0
	global_load_lds_dwordx4 v136, s[78:79]
	s_waitcnt vmcnt(6)
	s_waitcnt lgkmcnt(0)
	s_barrier
	s_waitcnt lgkmcnt(0)
	v_mfma_f32_16x16x32_bf16 v[62:65], v[154:157], v[188:191], v[62:65]
	v_mfma_f32_16x16x32_bf16 v[62:65], v[158:161], v[196:199], v[62:65]
	v_mfma_f32_16x16x32_bf16 v[46:49], v[158:161], v[204:207], v[46:49]
	v_mfma_f32_16x16x32_bf16 v[46:49], v[154:157], v[200:203], v[46:49]
	v_mfma_f32_16x16x32_bf16 v[30:33], v[154:157], v[208:211], v[30:33]
	v_mfma_f32_16x16x32_bf16 v[30:33], v[158:161], v[212:215], v[30:33]
	v_mfma_f32_16x16x32_bf16 v[14:17], v[158:161], v[220:223], v[14:17]
	v_mfma_f32_16x16x32_bf16 v[14:17], v[154:157], v[216:219], v[14:17]
	v_mfma_f32_16x16x32_bf16 v[6:9], v[162:165], v[216:219], v[6:9]
	v_mfma_f32_16x16x32_bf16 v[6:9], v[166:169], v[220:223], v[6:9]
	v_mfma_f32_16x16x32_bf16 v[22:25], v[166:169], v[212:215], v[22:25]
	v_mfma_f32_16x16x32_bf16 v[22:25], v[162:165], v[208:211], v[22:25]
	v_mfma_f32_16x16x32_bf16 v[38:41], v[162:165], v[200:203], v[38:41]
	v_mfma_f32_16x16x32_bf16 v[38:41], v[166:169], v[204:207], v[38:41]
	v_mfma_f32_16x16x32_bf16 v[54:57], v[166:169], v[196:199], v[54:57]
	v_mfma_f32_16x16x32_bf16 v[54:57], v[162:165], v[188:191], v[54:57]
	v_mfma_f32_16x16x32_bf16 v[58:61], v[170:173], v[188:191], v[58:61]
	v_mfma_f32_16x16x32_bf16 v[58:61], v[174:177], v[196:199], v[58:61]
	v_mfma_f32_16x16x32_bf16 v[42:45], v[174:177], v[204:207], v[42:45]
	v_mfma_f32_16x16x32_bf16 v[42:45], v[170:173], v[200:203], v[42:45]
	v_mfma_f32_16x16x32_bf16 v[26:29], v[170:173], v[208:211], v[26:29]
	v_mfma_f32_16x16x32_bf16 v[26:29], v[174:177], v[212:215], v[26:29]
	v_mfma_f32_16x16x32_bf16 v[10:13], v[174:177], v[220:223], v[10:13]
	v_mfma_f32_16x16x32_bf16 v[10:13], v[170:173], v[216:219], v[10:13]
	v_mfma_f32_16x16x32_bf16 v[2:5], v[180:183], v[216:219], v[2:5]
	v_mfma_f32_16x16x32_bf16 v[2:5], v[184:187], v[220:223], v[2:5]
	v_mfma_f32_16x16x32_bf16 v[18:21], v[184:187], v[212:215], v[18:21]
	v_mfma_f32_16x16x32_bf16 v[18:21], v[180:183], v[208:211], v[18:21]
	v_mfma_f32_16x16x32_bf16 v[34:37], v[180:183], v[200:203], v[34:37]
	v_mfma_f32_16x16x32_bf16 v[34:37], v[184:187], v[204:207], v[34:37]
	v_mfma_f32_16x16x32_bf16 v[50:53], v[184:187], v[196:199], v[50:53]
	v_mfma_f32_16x16x32_bf16 v[50:53], v[180:183], v[188:191], v[50:53]
	s_barrier
; #define PG8_STAGE(bufoff, gbase, voff) do { _Pragma("unroll") for (int _i = 0; _i < 2; ++_i) \
;         __builtin_amdgcn_global_load_lds((const unsigned*)((const char*)(gbase) + (voff)[_i]), (PG8_LAS unsigned*)(lds + (bufoff) + ldsw + _i * 8192), 16, 0, 0); } while (0)
; #define PG8_LDA(dst, b, h) do { _Pragma("unroll") for (int m = 0; m < 4; ++m) _Pragma("unroll") for (int k = 0; k < 2; ++k) dst[m][k] = *(const PG8_LAS bf16x8*)(lds + PG8_SA(b, h) + aoff + m * 2048 + k * 1024); } while (0)
; #define PG8_LDB(dst, b, h) do { _Pragma("unroll") for (int n = 0; n < 2; ++n) _Pragma("unroll") for (int k = 0; k < 2; ++k) dst[n][k] = *(const PG8_LAS bf16x8*)(lds + PG8_SB(b, h) + boff + n * 2048 + k * 1024); } while (0)
; #define PG8_MMA(ai, bj, At, Bt) do { __builtin_amdgcn_s_setprio(1); _Pragma("unroll") for (int m = 0; m < 4; ++m) _Pragma("unroll") for (int n = 0; n < 2; ++n) _Pragma("unroll") for (int k = 0; k < 2; ++k) \
;         acc[ai][bj][m][n] = __builtin_amdgcn_mfma_f32_16x16x32_bf16(Bt[n][k], At[m][k], acc[ai][bj][m][n], 0, 0, 0); __builtin_amdgcn_s_setprio(0); } while (0)
; #define PG8_WAIT_V(n) asm volatile("s_waitcnt vmcnt(" #n ")" ::: "memory")
; #define PG8_WAIT_L(n) asm volatile("s_waitcnt lgkmcnt(" #n ")" ::: "memory")
; #define PG8_BAR __builtin_amdgcn_s_barrier()
; #define PG8_SCHED __builtin_amdgcn_sched_barrier(0)
; template <class Epi, class Sched, bool ALIGN_EPI = false, bool SP2 = false>
; __device__ __forceinline__ void gemm_phase(PG8_LAS unsigned char* lds, const Gemm g, const Sched& S, const Epi& E) {
;     ...
;             PG8_LDB(B0, 1, 0); PG8_LDB(B1, 1, 1); PG8_SCHED; PG8_LDA(At, 1, 0); PG8_STAGE(PG8_SA(0, 1), a2 + hstep, voffA);
;             PG8_WAIT_V(8); PG8_WAIT_L(0); PG8_BAR; PG8_MMA(0, 0, At, B0); PG8_MMA(0, 1, At, B1); PG8_BAR; PG8_SCHED;
	s_add_i32 s77, 0, 0x18000
	v_add_u32_e32 v138, s77, v148
	s_add_i32 s78, 0, 0x1c000
	ds_read_b128 v[154:157], v138
	ds_read_b128 v[158:161], v138 offset:1024
	ds_read_b128 v[162:165], v138 offset:2048
	ds_read_b128 v[166:169], v138 offset:3072
	v_add_u32_e32 v138, s78, v148
	ds_read_b128 v[170:173], v138
	ds_read_b128 v[174:177], v138 offset:1024
	ds_read_b128 v[180:183], v138 offset:2048
	ds_read_b128 v[184:187], v138 offset:3072
	ds_read_b128 v[188:191], v152 offset:32768
	ds_read_b128 v[196:199], v152 offset:33792
	ds_read_b128 v[200:203], v152 offset:34816
	ds_read_b128 v[204:207], v152 offset:35840
	ds_read_b128 v[208:211], v152 offset:36864
	ds_read_b128 v[212:215], v152 offset:37888
	ds_read_b128 v[216:219], v152 offset:38912
	ds_read_b128 v[220:223], v152 offset:39936
	s_mov_b32 m0, s28
	s_nop 0
	global_load_lds_dwordx4 v130, s[74:75]
	s_mov_b32 m0, s29
	s_nop 0
	global_load_lds_dwordx4 v134, s[74:75]
	s_add_u32 s74, s74, 0x4000
	s_addc_u32 s75, s75, 0
	s_mov_b32 m0, s30
	s_nop 0
	global_load_lds_dwordx4 v130, s[74:75]
	s_mov_b32 m0, s31
	s_nop 0
	global_load_lds_dwordx4 v134, s[74:75]
	s_waitcnt vmcnt(8)
	s_waitcnt lgkmcnt(0)
	s_barrier
	s_waitcnt lgkmcnt(0)
	v_mfma_f32_16x16x32_bf16 v[126:129], v[154:157], v[188:191], v[126:129]
	v_mfma_f32_16x16x32_bf16 v[126:129], v[158:161], v[196:199], v[126:129]
	v_mfma_f32_16x16x32_bf16 v[110:113], v[158:161], v[204:207], v[110:113]
	v_mfma_f32_16x16x32_bf16 v[110:113], v[154:157], v[200:203], v[110:113]
	v_mfma_f32_16x16x32_bf16 v[94:97], v[154:157], v[208:211], v[94:97]
	v_mfma_f32_16x16x32_bf16 v[94:97], v[158:161], v[212:215], v[94:97]
	v_mfma_f32_16x16x32_bf16 v[78:81], v[158:161], v[220:223], v[78:81]
	v_mfma_f32_16x16x32_bf16 v[78:81], v[154:157], v[216:219], v[78:81]
	v_mfma_f32_16x16x32_bf16 v[70:73], v[162:165], v[216:219], v[70:73]
	v_mfma_f32_16x16x32_bf16 v[70:73], v[166:169], v[220:223], v[70:73]
	v_mfma_f32_16x16x32_bf16 v[86:89], v[166:169], v[212:215], v[86:89]
	v_mfma_f32_16x16x32_bf16 v[86:89], v[162:165], v[208:211], v[86:89]
	v_mfma_f32_16x16x32_bf16 v[102:105], v[162:165], v[200:203], v[102:105]
	v_mfma_f32_16x16x32_bf16 v[102:105], v[166:169], v[204:207], v[102:105]
	v_mfma_f32_16x16x32_bf16 v[118:121], v[166:169], v[196:199], v[118:121]
	v_mfma_f32_16x16x32_bf16 v[118:121], v[162:165], v[188:191], v[118:121]
	v_mfma_f32_16x16x32_bf16 v[122:125], v[170:173], v[188:191], v[122:125]
	v_mfma_f32_16x16x32_bf16 v[122:125], v[174:177], v[196:199], v[122:125]
	v_mfma_f32_16x16x32_bf16 v[106:109], v[174:177], v[204:207], v[106:109]
	v_mfma_f32_16x16x32_bf16 v[106:109], v[170:173], v[200:203], v[106:109]
	v_mfma_f32_16x16x32_bf16 v[90:93], v[170:173], v[208:211], v[90:93]
	v_mfma_f32_16x16x32_bf16 v[90:93], v[174:177], v[212:215], v[90:93]
	v_mfma_f32_16x16x32_bf16 v[74:77], v[174:177], v[220:223], v[74:77]
	v_mfma_f32_16x16x32_bf16 v[74:77], v[170:173], v[216:219], v[74:77]
	v_mfma_f32_16x16x32_bf16 v[66:69], v[180:183], v[216:219], v[66:69]
	v_mfma_f32_16x16x32_bf16 v[66:69], v[184:187], v[220:223], v[66:69]
	v_mfma_f32_16x16x32_bf16 v[82:85], v[184:187], v[212:215], v[82:85]
	v_mfma_f32_16x16x32_bf16 v[82:85], v[180:183], v[208:211], v[82:85]
	v_mfma_f32_16x16x32_bf16 v[98:101], v[180:183], v[200:203], v[98:101]
	v_mfma_f32_16x16x32_bf16 v[98:101], v[184:187], v[204:207], v[98:101]
	v_mfma_f32_16x16x32_bf16 v[114:117], v[184:187], v[196:199], v[114:117]
	v_mfma_f32_16x16x32_bf16 v[114:117], v[180:183], v[188:191], v[114:117]
	s_barrier
; #define PG8_STAGE(bufoff, gbase, voff) do { _Pragma("unroll") for (int _i = 0; _i < 2; ++_i) \
;         __builtin_amdgcn_global_load_lds((const unsigned*)((const char*)(gbase) + (voff)[_i]), (PG8_LAS unsigned*)(lds + (bufoff) + ldsw + _i * 8192), 16, 0, 0); } while (0)
; #define PG8_LDA(dst, b, h) do { _Pragma("unroll") for (int m = 0; m < 4; ++m) _Pragma("unroll") for (int k = 0; k < 2; ++k) dst[m][k] = *(const PG8_LAS bf16x8*)(lds + PG8_SA(b, h) + aoff + m * 2048 + k * 1024); } while (0)
; #define PG8_MMA(ai, bj, At, Bt) do { __builtin_amdgcn_s_setprio(1); _Pragma("unroll") for (int m = 0; m < 4; ++m) _Pragma("unroll") for (int n = 0; n < 2; ++n) _Pragma("unroll") for (int k = 0; k < 2; ++k) \
;         acc[ai][bj][m][n] = __builtin_amdgcn_mfma_f32_16x16x32_bf16(Bt[n][k], At[m][k], acc[ai][bj][m][n], 0, 0, 0); __builtin_amdgcn_s_setprio(0); } while (0)
; #define PG8_WAIT_V(n) asm volatile("s_waitcnt vmcnt(" #n ")" ::: "memory")
; #define PG8_WAIT_L(n) asm volatile("s_waitcnt lgkmcnt(" #n ")" ::: "memory")
; #define PG8_BAR __builtin_amdgcn_s_barrier()
; #define PG8_SCHED __builtin_amdgcn_sched_barrier(0)
; template <class Epi, class Sched, bool ALIGN_EPI = false, bool SP2 = false>
; __device__ __forceinline__ void gemm_phase(PG8_LAS unsigned char* lds, const Gemm g, const Sched& S, const Epi& E) {
;     ...
;         for (; t < tend; t += 2) {
;             const bool last = (t == nt - 2);
;             const char* a1 = cA + (size_t)(t + 1) * kstep;
;             const char* a2 = last ? nA : cA + (size_t)(t + 2) * kstep; const char* b2 = last ? nB : cB + (size_t)(t + 2) * kstep;
;             const char* a3 = a2 + kstep; const char* b3 = b2 + kstep;
;             if (last && has_next) S.a_ready(nxt);
;     ...
;             PG8_LDA(At, 1, 1); PG8_STAGE(PG8_SB(1, 0), b3, voffB); PG8_STAGE(PG8_SB(1, 1), b3 + hstep, voffB); PG8_STAGE(PG8_SA(1, 0), a3, voffA);
;             PG8_WAIT_V(8); PG8_WAIT_L(0); PG8_BAR; PG8_MMA(1, 0, At, B0); PG8_MMA(1, 1, At, B1); PG8_BAR; PG8_SCHED;
	s_add_u32 s74, s72, 0x8000
	s_addc_u32 s75, s73, 0
	s_add_i32 s77, s77, s3
	s_mov_b32 m0, s77
	ds_read_b128 v[188:191], v152 offset:49152
	ds_read_b128 v[196:199], v152 offset:50176
	ds_read_b128 v[200:203], v152 offset:51200
	ds_read_b128 v[204:207], v152 offset:52224
	ds_read_b128 v[208:211], v152 offset:53248
	ds_read_b128 v[212:215], v152 offset:54272
	ds_read_b128 v[216:219], v152 offset:55296
	ds_read_b128 v[220:223], v152 offset:56320
	global_load_lds_dwordx4 v132, s[74:75]
	s_add_i32 m0, s77, 0x2000
	s_add_u32 s72, s72, 0xc000
	v_lshl_add_u64 v[224:225], s[74:75], 0, v[136:137]
	s_addc_u32 s73, s73, 0
	s_add_i32 s74, s78, s3
	global_load_lds_dwordx4 v[224:225], off
	s_mov_b32 m0, s74
	s_nop 0
	global_load_lds_dwordx4 v132, s[72:73]
	s_add_i32 m0, s74, 0x2000
	s_nop 0
	global_load_lds_dwordx4 v136, s[72:73]
	s_add_i32 s76, s76, 2
	s_add_u32 s48, s48, 0x10000
	s_addc_u32 s49, s49, 0
	s_add_u32 s68, s68, 0x10000
	s_addc_u32 s69, s69, 0
	s_add_u32 s50, s48, 0x4000
	s_addc_u32 s51, s49, 0
	s_cmp_eq_u32 s76, 60
	s_cselect_b32 s74, s64, s50
	s_cselect_b32 s75, s25, s51
	s_cselect_b32 s72, s65, s68
	s_cselect_b32 s73, s19, s69
	s_add_u32 s50, s74, 0x8000
	s_addc_u32 s51, s75, 0
	s_sub_u32 s50, s48, 0x4000
	s_subb_u32 s51, s49, 0
	s_cmp_gt_u32 s76, 61
	s_waitcnt vmcnt(6)
	s_waitcnt lgkmcnt(0)
	s_barrier
	s_waitcnt lgkmcnt(0)
	v_mfma_f32_16x16x32_bf16 v[62:65], v[154:157], v[188:191], v[62:65]
	v_mfma_f32_16x16x32_bf16 v[62:65], v[158:161], v[196:199], v[62:65]
	v_mfma_f32_16x16x32_bf16 v[46:49], v[158:161], v[204:207], v[46:49]
	v_mfma_f32_16x16x32_bf16 v[46:49], v[154:157], v[200:203], v[46:49]
	v_mfma_f32_16x16x32_bf16 v[30:33], v[154:157], v[208:211], v[30:33]
	v_mfma_f32_16x16x32_bf16 v[30:33], v[158:161], v[212:215], v[30:33]
	v_mfma_f32_16x16x32_bf16 v[14:17], v[158:161], v[220:223], v[14:17]
	v_mfma_f32_16x16x32_bf16 v[14:17], v[154:157], v[216:219], v[14:17]
	v_mfma_f32_16x16x32_bf16 v[6:9], v[162:165], v[216:219], v[6:9]
	v_mfma_f32_16x16x32_bf16 v[6:9], v[166:169], v[220:223], v[6:9]
	v_mfma_f32_16x16x32_bf16 v[22:25], v[166:169], v[212:215], v[22:25]
	v_mfma_f32_16x16x32_bf16 v[22:25], v[162:165], v[208:211], v[22:25]
	v_mfma_f32_16x16x32_bf16 v[38:41], v[162:165], v[200:203], v[38:41]
	v_mfma_f32_16x16x32_bf16 v[38:41], v[166:169], v[204:207], v[38:41]
	v_mfma_f32_16x16x32_bf16 v[54:57], v[166:169], v[196:199], v[54:57]
	v_mfma_f32_16x16x32_bf16 v[54:57], v[162:165], v[188:191], v[54:57]
	v_mfma_f32_16x16x32_bf16 v[58:61], v[170:173], v[188:191], v[58:61]
	v_mfma_f32_16x16x32_bf16 v[58:61], v[174:177], v[196:199], v[58:61]
	v_mfma_f32_16x16x32_bf16 v[42:45], v[174:177], v[204:207], v[42:45]
	v_mfma_f32_16x16x32_bf16 v[42:45], v[170:173], v[200:203], v[42:45]
	v_mfma_f32_16x16x32_bf16 v[26:29], v[170:173], v[208:211], v[26:29]
	v_mfma_f32_16x16x32_bf16 v[26:29], v[174:177], v[212:215], v[26:29]
	v_mfma_f32_16x16x32_bf16 v[10:13], v[174:177], v[220:223], v[10:13]
	v_mfma_f32_16x16x32_bf16 v[10:13], v[170:173], v[216:219], v[10:13]
	v_mfma_f32_16x16x32_bf16 v[2:5], v[180:183], v[216:219], v[2:5]
	v_mfma_f32_16x16x32_bf16 v[2:5], v[184:187], v[220:223], v[2:5]
	v_mfma_f32_16x16x32_bf16 v[18:21], v[184:187], v[212:215], v[18:21]
	v_mfma_f32_16x16x32_bf16 v[18:21], v[180:183], v[208:211], v[18:21]
	v_mfma_f32_16x16x32_bf16 v[34:37], v[180:183], v[200:203], v[34:37]
	v_mfma_f32_16x16x32_bf16 v[34:37], v[184:187], v[204:207], v[34:37]
	v_mfma_f32_16x16x32_bf16 v[50:53], v[184:187], v[196:199], v[50:53]
	v_mfma_f32_16x16x32_bf16 v[50:53], v[180:183], v[188:191], v[50:53]
	s_barrier
	s_cbranch_scc0 .LBB0_115
	s_and_b64 vcc, exec, s[14:15]
	s_cbranch_vccz .LBB0_118
	s_barrier

; #define PG8_STAGE(bufoff, gbase, voff) do { _Pragma("unroll") for (int _i = 0; _i < 2; ++_i) \
;         __builtin_amdgcn_global_load_lds((const unsigned*)((const char*)(gbase) + (voff)[_i]), (PG8_LAS unsigned*)(lds + (bufoff) + ldsw + _i * 8192), 16, 0, 0); } while (0)
; #define PG8_LDA(dst, b, h) do { _Pragma("unroll") for (int m = 0; m < 4; ++m) _Pragma("unroll") for (int k = 0; k < 2; ++k) dst[m][k] = *(const PG8_LAS bf16x8*)(lds + PG8_SA(b, h) + aoff + m * 2048 + k * 1024); } while (0)
; #define PG8_LDB(dst, b, h) do { _Pragma("unroll") for (int n = 0; n < 2; ++n) _Pragma("unroll") for (int k = 0; k < 2; ++k) dst[n][k] = *(const PG8_LAS bf16x8*)(lds + PG8_SB(b, h) + boff + n * 2048 + k * 1024); } while (0)
; #define PG8_WAIT_V(n) asm volatile("s_waitcnt vmcnt(" #n ")" ::: "memory")
; #define PG8_WAIT_L(n) asm volatile("s_waitcnt lgkmcnt(" #n ")" ::: "memory")
; template <class Epi, class Sched, bool ALIGN_EPI = false, bool SP2 = false>
; __device__ __forceinline__ void gemm_phase(PG8_LAS unsigned char* lds, const Gemm g, const Sched& S, const Epi& E) {
;     ...
;         const char* nA = has_next ? (const char*)g.A + (size_t)nxt.pm * tstep : cA; const char* nB = has_next ? (const char*)g.Bt + (size_t)nxt.pn * tstep : cB;
;         constexpr int NSEG = Epi::HAS_MID ? 2 : 1; int t = 0;
; #pragma unroll
;         for (int seg = 0; seg < NSEG; ++seg) { const int tend = (seg + 1 < NSEG) ? (nt >> 1) : nt;
;         for (; t < tend; t += 2) {
;             const bool last = (t == nt - 2);
;             const char* a1 = cA + (size_t)(t + 1) * kstep;
;             const char* a2 = last ? nA : cA + (size_t)(t + 2) * kstep; const char* b2 = last ? nB : cB + (size_t)(t + 2) * kstep;
;             const char* a3 = a2 + kstep; const char* b3 = b2 + kstep;
;             if (last && has_next) S.a_ready(nxt);
;             if constexpr (SP2) {
;             PG8_LDB(B0, 0, 0); PG8_LDB(B1, 0, 1); PG8_SCHED; PG8_LDA(At, 0, 0); PG8_STAGE(PG8_SA(1, 1), a1 + hstep, voffA);
;             PG8_WAIT_V(8); PG8_WAIT_L(0); PG8_BAR; PG8_MMA(0, 0, At, B0); PG8_MMA(0, 1, At, B1); PG8_BAR; PG8_SCHED;
;             PG8_LDA(At, 0, 1); PG8_STAGE(PG8_SB(0, 0), b2, voffB); PG8_STAGE(PG8_SB(0, 1), b2 + hstep, voffB); PG8_STAGE(PG8_SA(0, 0), a2, voffA);
;             PG8_WAIT_V(8); PG8_WAIT_L(0); PG8_BAR; PG8_MMA(1, 0, At, B0); PG8_MMA(1, 1, At, B1); PG8_BAR; PG8_SCHED;
.LBB0_199:
	s_add_u32 s44, s44, 0xc000
	s_addc_u32 s45, s45, 0
	s_add_u32 s74, s46, 0x10000
	s_addc_u32 s75, s47, 0
	s_mov_b32 s76, -2
	s_waitcnt lgkmcnt(0)
	s_nop 3
	s_add_u32 s46, s44, 0x4000
	s_addc_u32 s47, s45, 0
	s_cmpk_eq_i32 s76, 0xa8
	s_cselect_b32 s50, s6, s46
	s_cselect_b32 s51, s7, s47
	s_cselect_b32 s48, s24, s74
	s_cselect_b32 s49, s25, s75
	s_add_u32 s46, s50, 0x8000
	s_addc_u32 s47, s51, 0
	s_sub_u32 s46, s44, 0x4000
	s_subb_u32 s47, s45, 0
	ds_read_b128 v[148:151], v154
	ds_read_b128 v[158:161], v154 offset:1024
	ds_read_b128 v[162:165], v154 offset:2048
	ds_read_b128 v[166:169], v154 offset:3072
	ds_read_b128 v[170:173], v155
	ds_read_b128 v[174:177], v155 offset:1024
	ds_read_b128 v[180:183], v155 offset:2048
	ds_read_b128 v[184:187], v155 offset:3072
	ds_read_b128 v[188:191], v156
	ds_read_b128 v[196:199], v156 offset:1024
	ds_read_b128 v[200:203], v156 offset:2048
	ds_read_b128 v[204:207], v156 offset:3072
	ds_read_b128 v[208:211], v156 offset:4096
	ds_read_b128 v[212:215], v156 offset:5120
	ds_read_b128 v[216:219], v156 offset:6144
	ds_read_b128 v[220:223], v156 offset:7168
	s_mov_b32 m0, s57
	s_nop 0
	global_load_lds_dwordx4 v130, s[46:47]
	s_mov_b32 m0, s58
	s_nop 0
	global_load_lds_dwordx4 v134, s[46:47]
	s_add_i32 m0, s26, 0xc000
	s_nop 0
	global_load_lds_dwordx4 v140, s[44:45]
	s_add_i32 m0, s26, 0xe000
	s_nop 0
	global_load_lds_dwordx4 v142, s[44:45]
	s_waitcnt vmcnt(8)
	s_waitcnt lgkmcnt(0)
	s_barrier
	s_waitcnt lgkmcnt(0)
	v_mfma_f32_16x16x32_bf16 v[126:129], v[148:151], v[188:191], 0
	v_mfma_f32_16x16x32_bf16 v[126:129], v[158:161], v[196:199], v[126:129]
	v_mfma_f32_16x16x32_bf16 v[110:113], v[158:161], v[204:207], 0
	v_mfma_f32_16x16x32_bf16 v[110:113], v[148:151], v[200:203], v[110:113]
	v_mfma_f32_16x16x32_bf16 v[94:97], v[148:151], v[208:211], 0
	v_mfma_f32_16x16x32_bf16 v[94:97], v[158:161], v[212:215], v[94:97]
	v_mfma_f32_16x16x32_bf16 v[78:81], v[158:161], v[220:223], 0
	v_mfma_f32_16x16x32_bf16 v[78:81], v[148:151], v[216:219], v[78:81]
	v_mfma_f32_16x16x32_bf16 v[74:77], v[162:165], v[216:219], 0
	v_mfma_f32_16x16x32_bf16 v[74:77], v[166:169], v[220:223], v[74:77]
	v_mfma_f32_16x16x32_bf16 v[90:93], v[166:169], v[212:215], 0
	v_mfma_f32_16x16x32_bf16 v[90:93], v[162:165], v[208:211], v[90:93]
	v_mfma_f32_16x16x32_bf16 v[106:109], v[162:165], v[200:203], 0
	v_mfma_f32_16x16x32_bf16 v[106:109], v[166:169], v[204:207], v[106:109]
	v_mfma_f32_16x16x32_bf16 v[122:125], v[166:169], v[196:199], 0
	v_mfma_f32_16x16x32_bf16 v[122:125], v[162:165], v[188:191], v[122:125]
	v_mfma_f32_16x16x32_bf16 v[118:121], v[170:173], v[188:191], 0
	v_mfma_f32_16x16x32_bf16 v[118:121], v[174:177], v[196:199], v[118:121]
	v_mfma_f32_16x16x32_bf16 v[102:105], v[174:177], v[204:207], 0
	v_mfma_f32_16x16x32_bf16 v[102:105], v[170:173], v[200:203], v[102:105]
	v_mfma_f32_16x16x32_bf16 v[86:89], v[170:173], v[208:211], 0
	v_mfma_f32_16x16x32_bf16 v[86:89], v[174:177], v[212:215], v[86:89]
	v_mfma_f32_16x16x32_bf16 v[70:73], v[174:177], v[220:223], 0
	v_mfma_f32_16x16x32_bf16 v[70:73], v[170:173], v[216:219], v[70:73]
	v_mfma_f32_16x16x32_bf16 v[66:69], v[180:183], v[216:219], 0
	v_mfma_f32_16x16x32_bf16 v[66:69], v[184:187], v[220:223], v[66:69]
	v_mfma_f32_16x16x32_bf16 v[82:85], v[184:187], v[212:215], 0
	v_mfma_f32_16x16x32_bf16 v[82:85], v[180:183], v[208:211], v[82:85]
	v_mfma_f32_16x16x32_bf16 v[98:101], v[180:183], v[200:203], 0
	v_mfma_f32_16x16x32_bf16 v[98:101], v[184:187], v[204:207], v[98:101]
	v_mfma_f32_16x16x32_bf16 v[114:117], v[184:187], v[196:199], 0
	v_mfma_f32_16x16x32_bf16 v[114:117], v[180:183], v[188:191], v[114:117]
	s_barrier
	s_add_i32 s77, s59, s3
	s_mov_b32 m0, s77
	ds_read_b128 v[188:191], v156 offset:16384
	ds_read_b128 v[196:199], v156 offset:17408
	ds_read_b128 v[200:203], v156 offset:18432
	ds_read_b128 v[204:207], v156 offset:19456
	ds_read_b128 v[208:211], v156 offset:20480
	ds_read_b128 v[212:215], v156 offset:21504
	ds_read_b128 v[216:219], v156 offset:22528
	ds_read_b128 v[220:223], v156 offset:23552
	global_load_lds_dwordx4 v132, s[48:49]
	s_add_i32 m0, s77, 0x2000
	s_add_u32 s78, s48, 0x4000
	s_addc_u32 s79, s49, 0
	s_add_i32 s77, s61, s3
	global_load_lds_dwordx4 v136, s[48:49]
	s_mov_b32 m0, s77
	s_nop 0
	global_load_lds_dwordx4 v132, s[78:79]
	s_add_i32 m0, s77, 0x2000
	s_nop 0
	global_load_lds_dwordx4 v136, s[78:79]
	s_waitcnt vmcnt(6)
	s_waitcnt lgkmcnt(0)
	s_barrier
	s_waitcnt lgkmcnt(0)
	v_mfma_f32_16x16x32_bf16 v[62:65], v[148:151], v[188:191], 0
	v_mfma_f32_16x16x32_bf16 v[62:65], v[158:161], v[196:199], v[62:65]
	v_mfma_f32_16x16x32_bf16 v[46:49], v[158:161], v[204:207], 0
	v_mfma_f32_16x16x32_bf16 v[46:49], v[148:151], v[200:203], v[46:49]
	v_mfma_f32_16x16x32_bf16 v[30:33], v[148:151], v[208:211], 0
	v_mfma_f32_16x16x32_bf16 v[30:33], v[158:161], v[212:215], v[30:33]
	v_mfma_f32_16x16x32_bf16 v[14:17], v[158:161], v[220:223], 0
	v_mfma_f32_16x16x32_bf16 v[14:17], v[148:151], v[216:219], v[14:17]
	v_mfma_f32_16x16x32_bf16 v[10:13], v[162:165], v[216:219], 0
	v_mfma_f32_16x16x32_bf16 v[10:13], v[166:169], v[220:223], v[10:13]
	v_mfma_f32_16x16x32_bf16 v[26:29], v[166:169], v[212:215], 0
	v_mfma_f32_16x16x32_bf16 v[26:29], v[162:165], v[208:211], v[26:29]
	v_mfma_f32_16x16x32_bf16 v[42:45], v[162:165], v[200:203], 0
	v_mfma_f32_16x16x32_bf16 v[42:45], v[166:169], v[204:207], v[42:45]
	v_mfma_f32_16x16x32_bf16 v[58:61], v[166:169], v[196:199], 0
	v_mfma_f32_16x16x32_bf16 v[58:61], v[162:165], v[188:191], v[58:61]
	v_mfma_f32_16x16x32_bf16 v[54:57], v[170:173], v[188:191], 0
	v_mfma_f32_16x16x32_bf16 v[54:57], v[174:177], v[196:199], v[54:57]
	v_mfma_f32_16x16x32_bf16 v[38:41], v[174:177], v[204:207], 0
	v_mfma_f32_16x16x32_bf16 v[38:41], v[170:173], v[200:203], v[38:41]
	v_mfma_f32_16x16x32_bf16 v[22:25], v[170:173], v[208:211], 0
	v_mfma_f32_16x16x32_bf16 v[22:25], v[174:177], v[212:215], v[22:25]
	v_mfma_f32_16x16x32_bf16 v[6:9], v[174:177], v[220:223], 0
	v_mfma_f32_16x16x32_bf16 v[6:9], v[170:173], v[216:219], v[6:9]
	v_mfma_f32_16x16x32_bf16 v[2:5], v[180:183], v[216:219], 0
	v_mfma_f32_16x16x32_bf16 v[2:5], v[184:187], v[220:223], v[2:5]
	v_mfma_f32_16x16x32_bf16 v[18:21], v[184:187], v[212:215], 0
	v_mfma_f32_16x16x32_bf16 v[18:21], v[180:183], v[208:211], v[18:21]
	v_mfma_f32_16x16x32_bf16 v[34:37], v[180:183], v[200:203], 0
	v_mfma_f32_16x16x32_bf16 v[34:37], v[184:187], v[204:207], v[34:37]
	v_mfma_f32_16x16x32_bf16 v[50:53], v[184:187], v[196:199], 0
	v_mfma_f32_16x16x32_bf16 v[50:53], v[180:183], v[188:191], v[50:53]
	s_barrier
; #define PG8_STAGE(bufoff, gbase, voff) do { _Pragma("unroll") for (int _i = 0; _i < 2; ++_i) \
;         __builtin_amdgcn_global_load_lds((const unsigned*)((const char*)(gbase) + (voff)[_i]), (PG8_LAS unsigned*)(lds + (bufoff) + ldsw + _i * 8192), 16, 0, 0); } while (0)
; #define PG8_LDA(dst, b, h) do { _Pragma("unroll") for (int m = 0; m < 4; ++m) _Pragma("unroll") for (int k = 0; k < 2; ++k) dst[m][k] = *(const PG8_LAS bf16x8*)(lds + PG8_SA(b, h) + aoff + m * 2048 + k * 1024); } while (0)
; #define PG8_LDB(dst, b, h) do { _Pragma("unroll") for (int n = 0; n < 2; ++n) _Pragma("unroll") for (int k = 0; k < 2; ++k) dst[n][k] = *(const PG8_LAS bf16x8*)(lds + PG8_SB(b, h) + boff + n * 2048 + k * 1024); } while (0)
; template <class Epi, class Sched, bool ALIGN_EPI = false, bool SP2 = false>
; __device__ __forceinline__ void gemm_phase(PG8_LAS unsigned char* lds, const Gemm g, const Sched& S, const Epi& E) {
;     ...
;         for (; t < tend; t += 2) {
;             const bool last = (t == nt - 2);
;             const char* a1 = cA + (size_t)(t + 1) * kstep;
;             const char* a2 = last ? nA : cA + (size_t)(t + 2) * kstep; const char* b2 = last ? nB : cB + (size_t)(t + 2) * kstep;
;             const char* a3 = a2 + kstep; const char* b3 = b2 + kstep;
;             if (last && has_next) S.a_ready(nxt);
;             if constexpr (SP2) {
;             PG8_LDB(B0, 0, 0); PG8_LDB(B1, 0, 1); PG8_SCHED; PG8_LDA(At, 0, 0); PG8_STAGE(PG8_SA(1, 1), a1 + hstep, voffA);
;             PG8_WAIT_V(8); PG8_WAIT_L(0); PG8_BAR; PG8_MMA(0, 0, At, B0); PG8_MMA(0, 1, At, B1); PG8_BAR; PG8_SCHED;
;             PG8_LDA(At, 0, 1); PG8_STAGE(PG8_SB(0, 0), b2, voffB); PG8_STAGE(PG8_SB(0, 1), b2 + hstep, voffB); PG8_STAGE(PG8_SA(0, 0), a2, voffA);
;             PG8_WAIT_V(8); PG8_WAIT_L(0); PG8_BAR; PG8_MMA(1, 0, At, B0); PG8_MMA(1, 1, At, B1); PG8_BAR; PG8_SCHED;
;             PG8_LDB(B0, 1, 0); PG8_LDB(B1, 1, 1); PG8_SCHED; PG8_LDA(At, 1, 0); PG8_STAGE(PG8_SA(0, 1), a2 + hstep, voffA);
;             PG8_WAIT_V(8); PG8_WAIT_L(0); PG8_BAR; PG8_MMA(0, 0, At, B0); PG8_MMA(0, 1, At, B1); PG8_BAR; PG8_SCHED;
;             PG8_LDA(At, 1, 1); PG8_STAGE(PG8_SB(1, 0), b3, voffB); PG8_STAGE(PG8_SB(1, 1), b3 + hstep, voffB); PG8_STAGE(PG8_SA(1, 0), a3, voffA);
;             PG8_WAIT_V(8); PG8_WAIT_L(0); PG8_BAR; PG8_MMA(1, 0, At, B0); PG8_MMA(1, 1, At, B1); PG8_BAR; PG8_SCHED;
	s_add_i32 s77, 0, 0x18000
	v_add_u32_e32 v138, s77, v153
	s_add_i32 s78, 0, 0x1c000
	ds_read_b128 v[148:151], v138
	ds_read_b128 v[158:161], v138 offset:1024
	ds_read_b128 v[162:165], v138 offset:2048
	ds_read_b128 v[166:169], v138 offset:3072
	v_add_u32_e32 v138, s78, v153
	ds_read_b128 v[170:173], v138
	ds_read_b128 v[174:177], v138 offset:1024
	ds_read_b128 v[180:183], v138 offset:2048
	ds_read_b128 v[184:187], v138 offset:3072
	ds_read_b128 v[188:191], v156 offset:32768
	ds_read_b128 v[196:199], v156 offset:33792
	ds_read_b128 v[200:203], v156 offset:34816
	ds_read_b128 v[204:207], v156 offset:35840
	ds_read_b128 v[208:211], v156 offset:36864
	ds_read_b128 v[212:215], v156 offset:37888
	ds_read_b128 v[216:219], v156 offset:38912
	ds_read_b128 v[220:223], v156 offset:39936
	s_mov_b32 m0, s26
	s_nop 0
	global_load_lds_dwordx4 v130, s[50:51]
	s_mov_b32 m0, s27
	s_nop 0
	global_load_lds_dwordx4 v134, s[50:51]
	s_add_u32 s50, s50, 0x4000
	s_addc_u32 s51, s51, 0
	s_mov_b32 m0, s28
	s_nop 0
	global_load_lds_dwordx4 v130, s[50:51]
	s_mov_b32 m0, s29
	s_nop 0
	global_load_lds_dwordx4 v134, s[50:51]
	s_waitcnt vmcnt(8)
	s_waitcnt lgkmcnt(0)
	s_barrier
	s_waitcnt lgkmcnt(0)
	v_mfma_f32_16x16x32_bf16 v[126:129], v[148:151], v[188:191], v[126:129]
	v_mfma_f32_16x16x32_bf16 v[126:129], v[158:161], v[196:199], v[126:129]
	v_mfma_f32_16x16x32_bf16 v[110:113], v[158:161], v[204:207], v[110:113]
	v_mfma_f32_16x16x32_bf16 v[110:113], v[148:151], v[200:203], v[110:113]
	v_mfma_f32_16x16x32_bf16 v[94:97], v[148:151], v[208:211], v[94:97]
	v_mfma_f32_16x16x32_bf16 v[94:97], v[158:161], v[212:215], v[94:97]
	v_mfma_f32_16x16x32_bf16 v[78:81], v[158:161], v[220:223], v[78:81]
	v_mfma_f32_16x16x32_bf16 v[78:81], v[148:151], v[216:219], v[78:81]
	v_mfma_f32_16x16x32_bf16 v[74:77], v[162:165], v[216:219], v[74:77]
	v_mfma_f32_16x16x32_bf16 v[74:77], v[166:169], v[220:223], v[74:77]
	v_mfma_f32_16x16x32_bf16 v[90:93], v[166:169], v[212:215], v[90:93]
	v_mfma_f32_16x16x32_bf16 v[90:93], v[162:165], v[208:211], v[90:93]
	v_mfma_f32_16x16x32_bf16 v[106:109], v[162:165], v[200:203], v[106:109]
	v_mfma_f32_16x16x32_bf16 v[106:109], v[166:169], v[204:207], v[106:109]
	v_mfma_f32_16x16x32_bf16 v[122:125], v[166:169], v[196:199], v[122:125]
	v_mfma_f32_16x16x32_bf16 v[122:125], v[162:165], v[188:191], v[122:125]
	v_mfma_f32_16x16x32_bf16 v[118:121], v[170:173], v[188:191], v[118:121]
	v_mfma_f32_16x16x32_bf16 v[118:121], v[174:177], v[196:199], v[118:121]
	v_mfma_f32_16x16x32_bf16 v[102:105], v[174:177], v[204:207], v[102:105]
	v_mfma_f32_16x16x32_bf16 v[102:105], v[170:173], v[200:203], v[102:105]
	v_mfma_f32_16x16x32_bf16 v[86:89], v[170:173], v[208:211], v[86:89]
	v_mfma_f32_16x16x32_bf16 v[86:89], v[174:177], v[212:215], v[86:89]
	v_mfma_f32_16x16x32_bf16 v[70:73], v[174:177], v[220:223], v[70:73]
	v_mfma_f32_16x16x32_bf16 v[70:73], v[170:173], v[216:219], v[70:73]
	v_mfma_f32_16x16x32_bf16 v[66:69], v[180:183], v[216:219], v[66:69]
	v_mfma_f32_16x16x32_bf16 v[66:69], v[184:187], v[220:223], v[66:69]
	v_mfma_f32_16x16x32_bf16 v[82:85], v[184:187], v[212:215], v[82:85]
	v_mfma_f32_16x16x32_bf16 v[82:85], v[180:183], v[208:211], v[82:85]
	v_mfma_f32_16x16x32_bf16 v[98:101], v[180:183], v[200:203], v[98:101]
	v_mfma_f32_16x16x32_bf16 v[98:101], v[184:187], v[204:207], v[98:101]
	v_mfma_f32_16x16x32_bf16 v[114:117], v[184:187], v[196:199], v[114:117]
	v_mfma_f32_16x16x32_bf16 v[114:117], v[180:183], v[188:191], v[114:117]
	s_barrier
	s_add_u32 s50, s48, 0x8000
	s_addc_u32 s51, s49, 0
	s_add_i32 s77, s77, s3
	s_mov_b32 m0, s77
	ds_read_b128 v[188:191], v156 offset:49152
	ds_read_b128 v[196:199], v156 offset:50176
	ds_read_b128 v[200:203], v156 offset:51200
	ds_read_b128 v[204:207], v156 offset:52224
	ds_read_b128 v[208:211], v156 offset:53248
	ds_read_b128 v[212:215], v156 offset:54272
	ds_read_b128 v[216:219], v156 offset:55296
	ds_read_b128 v[220:223], v156 offset:56320
	global_load_lds_dwordx4 v132, s[50:51]
	s_add_i32 m0, s77, 0x2000
	s_add_u32 s48, s48, 0xc000
	v_lshl_add_u64 v[224:225], s[50:51], 0, v[136:137]
	s_addc_u32 s49, s49, 0
	s_add_i32 s50, s78, s3
	global_load_lds_dwordx4 v[224:225], off
	s_mov_b32 m0, s50
	s_nop 0
	global_load_lds_dwordx4 v132, s[48:49]
	s_add_i32 m0, s50, 0x2000
	s_nop 0
	global_load_lds_dwordx4 v136, s[48:49]
	s_add_i32 s76, s76, 2
	s_add_u32 s44, s44, 0x10000
	s_addc_u32 s45, s45, 0
	s_add_u32 s74, s74, 0x10000
	s_addc_u32 s75, s75, 0
	s_add_u32 s46, s44, 0x4000
	s_addc_u32 s47, s45, 0
	s_cmpk_eq_i32 s76, 0xa8
	s_cselect_b32 s50, s6, s46
	s_cselect_b32 s51, s7, s47
	s_cselect_b32 s48, s24, s74
	s_cselect_b32 s49, s25, s75
	s_add_u32 s46, s50, 0x8000
	s_addc_u32 s47, s51, 0
	s_sub_u32 s46, s44, 0x4000
	s_subb_u32 s47, s45, 0
	s_cmpk_gt_u32 s76, 0xa9
	s_waitcnt vmcnt(6)
	s_waitcnt lgkmcnt(0)
	s_barrier
	s_waitcnt lgkmcnt(0)
	v_mfma_f32_16x16x32_bf16 v[62:65], v[148:151], v[188:191], v[62:65]
	v_mfma_f32_16x16x32_bf16 v[62:65], v[158:161], v[196:199], v[62:65]
	v_mfma_f32_16x16x32_bf16 v[46:49], v[158:161], v[204:207], v[46:49]
	v_mfma_f32_16x16x32_bf16 v[46:49], v[148:151], v[200:203], v[46:49]
	v_mfma_f32_16x16x32_bf16 v[30:33], v[148:151], v[208:211], v[30:33]
	v_mfma_f32_16x16x32_bf16 v[30:33], v[158:161], v[212:215], v[30:33]
	v_mfma_f32_16x16x32_bf16 v[14:17], v[158:161], v[220:223], v[14:17]
	v_mfma_f32_16x16x32_bf16 v[14:17], v[148:151], v[216:219], v[14:17]
	v_mfma_f32_16x16x32_bf16 v[10:13], v[162:165], v[216:219], v[10:13]
	v_mfma_f32_16x16x32_bf16 v[10:13], v[166:169], v[220:223], v[10:13]
	v_mfma_f32_16x16x32_bf16 v[26:29], v[166:169], v[212:215], v[26:29]
	v_mfma_f32_16x16x32_bf16 v[26:29], v[162:165], v[208:211], v[26:29]
	v_mfma_f32_16x16x32_bf16 v[42:45], v[162:165], v[200:203], v[42:45]
	v_mfma_f32_16x16x32_bf16 v[42:45], v[166:169], v[204:207], v[42:45]
	v_mfma_f32_16x16x32_bf16 v[58:61], v[166:169], v[196:199], v[58:61]
	v_mfma_f32_16x16x32_bf16 v[58:61], v[162:165], v[188:191], v[58:61]
	v_mfma_f32_16x16x32_bf16 v[54:57], v[170:173], v[188:191], v[54:57]
	v_mfma_f32_16x16x32_bf16 v[54:57], v[174:177], v[196:199], v[54:57]
	v_mfma_f32_16x16x32_bf16 v[38:41], v[174:177], v[204:207], v[38:41]
	v_mfma_f32_16x16x32_bf16 v[38:41], v[170:173], v[200:203], v[38:41]
	v_mfma_f32_16x16x32_bf16 v[22:25], v[170:173], v[208:211], v[22:25]
	v_mfma_f32_16x16x32_bf16 v[22:25], v[174:177], v[212:215], v[22:25]
	v_mfma_f32_16x16x32_bf16 v[6:9], v[174:177], v[220:223], v[6:9]
	v_mfma_f32_16x16x32_bf16 v[6:9], v[170:173], v[216:219], v[6:9]
	v_mfma_f32_16x16x32_bf16 v[2:5], v[180:183], v[216:219], v[2:5]
	v_mfma_f32_16x16x32_bf16 v[2:5], v[184:187], v[220:223], v[2:5]
	v_mfma_f32_16x16x32_bf16 v[18:21], v[184:187], v[212:215], v[18:21]
	v_mfma_f32_16x16x32_bf16 v[18:21], v[180:183], v[208:211], v[18:21]
	v_mfma_f32_16x16x32_bf16 v[34:37], v[180:183], v[200:203], v[34:37]
	v_mfma_f32_16x16x32_bf16 v[34:37], v[184:187], v[204:207], v[34:37]
	v_mfma_f32_16x16x32_bf16 v[50:53], v[184:187], v[196:199], v[50:53]
	v_mfma_f32_16x16x32_bf16 v[50:53], v[180:183], v[188:191], v[50:53]
	s_barrier
; #define PG8_STAGE(bufoff, gbase, voff) do { _Pragma("unroll") for (int _i = 0; _i < 2; ++_i) \
;         __builtin_amdgcn_global_load_lds((const unsigned*)((const char*)(gbase) + (voff)[_i]), (PG8_LAS unsigned*)(lds + (bufoff) + ldsw + _i * 8192), 16, 0, 0); } while (0)
; #define PG8_LDA(dst, b, h) do { _Pragma("unroll") for (int m = 0; m < 4; ++m) _Pragma("unroll") for (int k = 0; k < 2; ++k) dst[m][k] = *(const PG8_LAS bf16x8*)(lds + PG8_SA(b, h) + aoff + m * 2048 + k * 1024); } while (0)
; #define PG8_LDB(dst, b, h) do { _Pragma("unroll") for (int n = 0; n < 2; ++n) _Pragma("unroll") for (int k = 0; k < 2; ++k) dst[n][k] = *(const PG8_LAS bf16x8*)(lds + PG8_SB(b, h) + boff + n * 2048 + k * 1024); } while (0)
; #define PG8_MMA(ai, bj, At, Bt) do { __builtin_amdgcn_s_setprio(1); _Pragma("unroll") for (int m = 0; m < 4; ++m) _Pragma("unroll") for (int n = 0; n < 2; ++n) _Pragma("unroll") for (int k = 0; k < 2; ++k) \
;         acc[ai][bj][m][n] = __builtin_amdgcn_mfma_f32_16x16x32_bf16(Bt[n][k], At[m][k], acc[ai][bj][m][n], 0, 0, 0); __builtin_amdgcn_s_setprio(0); } while (0)
; #define PG8_WAIT_V(n) asm volatile("s_waitcnt vmcnt(" #n ")" ::: "memory")
; #define PG8_WAIT_L(n) asm volatile("s_waitcnt lgkmcnt(" #n ")" ::: "memory")
; #define PG8_BAR __builtin_amdgcn_s_barrier()
; #define PG8_SCHED __builtin_amdgcn_sched_barrier(0)
; template <class Epi, class Sched, bool ALIGN_EPI = false, bool SP2 = false>
; __device__ __forceinline__ void gemm_phase(PG8_LAS unsigned char* lds, const Gemm g, const Sched& S, const Epi& E) {
;     ...
;             PG8_LDB(B0, 0, 0); PG8_LDB(B1, 0, 1); PG8_SCHED; PG8_LDA(At, 0, 0); PG8_STAGE(PG8_SA(1, 1), a1 + hstep, voffA);
;             PG8_WAIT_V(8); PG8_WAIT_L(0); PG8_BAR; PG8_MMA(0, 0, At, B0); PG8_MMA(0, 1, At, B1); PG8_BAR; PG8_SCHED;
;             PG8_LDA(At, 0, 1); PG8_STAGE(PG8_SB(0, 0), b2, voffB); PG8_STAGE(PG8_SB(0, 1), b2 + hstep, voffB); PG8_STAGE(PG8_SA(0, 0), a2, voffA);
;             PG8_WAIT_V(8); PG8_WAIT_L(0); PG8_BAR; PG8_MMA(1, 0, At, B0); PG8_MMA(1, 1, At, B1); PG8_BAR; PG8_SCHED;
.LBB0_200:
	ds_read_b128 v[148:151], v154
	ds_read_b128 v[158:161], v154 offset:1024
	ds_read_b128 v[162:165], v154 offset:2048
	ds_read_b128 v[166:169], v154 offset:3072
	ds_read_b128 v[170:173], v155
	ds_read_b128 v[174:177], v155 offset:1024
	ds_read_b128 v[180:183], v155 offset:2048
	ds_read_b128 v[184:187], v155 offset:3072
	ds_read_b128 v[188:191], v156
	ds_read_b128 v[196:199], v156 offset:1024
	ds_read_b128 v[200:203], v156 offset:2048
	ds_read_b128 v[204:207], v156 offset:3072
	ds_read_b128 v[208:211], v156 offset:4096
	ds_read_b128 v[212:215], v156 offset:5120
	ds_read_b128 v[216:219], v156 offset:6144
	ds_read_b128 v[220:223], v156 offset:7168
	s_mov_b32 m0, s57
	s_nop 0
	global_load_lds_dwordx4 v130, s[46:47]
	s_mov_b32 m0, s58
	s_nop 0
	global_load_lds_dwordx4 v134, s[46:47]
	s_add_i32 m0, s26, 0xc000
	s_nop 0
	global_load_lds_dwordx4 v140, s[44:45]
	s_add_i32 m0, s26, 0xe000
	s_nop 0
	global_load_lds_dwordx4 v142, s[44:45]
	s_waitcnt vmcnt(8)
	s_waitcnt lgkmcnt(0)
	s_barrier
	s_waitcnt lgkmcnt(0)
	v_mfma_f32_16x16x32_bf16 v[126:129], v[148:151], v[188:191], v[126:129]
	v_mfma_f32_16x16x32_bf16 v[126:129], v[158:161], v[196:199], v[126:129]
	v_mfma_f32_16x16x32_bf16 v[110:113], v[158:161], v[204:207], v[110:113]
	v_mfma_f32_16x16x32_bf16 v[110:113], v[148:151], v[200:203], v[110:113]
	v_mfma_f32_16x16x32_bf16 v[94:97], v[148:151], v[208:211], v[94:97]
	v_mfma_f32_16x16x32_bf16 v[94:97], v[158:161], v[212:215], v[94:97]
	v_mfma_f32_16x16x32_bf16 v[78:81], v[158:161], v[220:223], v[78:81]
	v_mfma_f32_16x16x32_bf16 v[78:81], v[148:151], v[216:219], v[78:81]
	v_mfma_f32_16x16x32_bf16 v[74:77], v[162:165], v[216:219], v[74:77]
	v_mfma_f32_16x16x32_bf16 v[74:77], v[166:169], v[220:223], v[74:77]
	v_mfma_f32_16x16x32_bf16 v[90:93], v[166:169], v[212:215], v[90:93]
	v_mfma_f32_16x16x32_bf16 v[90:93], v[162:165], v[208:211], v[90:93]
	v_mfma_f32_16x16x32_bf16 v[106:109], v[162:165], v[200:203], v[106:109]
	v_mfma_f32_16x16x32_bf16 v[106:109], v[166:169], v[204:207], v[106:109]
	v_mfma_f32_16x16x32_bf16 v[122:125], v[166:169], v[196:199], v[122:125]
	v_mfma_f32_16x16x32_bf16 v[122:125], v[162:165], v[188:191], v[122:125]
	v_mfma_f32_16x16x32_bf16 v[118:121], v[170:173], v[188:191], v[118:121]
	v_mfma_f32_16x16x32_bf16 v[118:121], v[174:177], v[196:199], v[118:121]
	v_mfma_f32_16x16x32_bf16 v[102:105], v[174:177], v[204:207], v[102:105]
	v_mfma_f32_16x16x32_bf16 v[102:105], v[170:173], v[200:203], v[102:105]
	v_mfma_f32_16x16x32_bf16 v[86:89], v[170:173], v[208:211], v[86:89]
	v_mfma_f32_16x16x32_bf16 v[86:89], v[174:177], v[212:215], v[86:89]
	v_mfma_f32_16x16x32_bf16 v[70:73], v[174:177], v[220:223], v[70:73]
	v_mfma_f32_16x16x32_bf16 v[70:73], v[170:173], v[216:219], v[70:73]
	v_mfma_f32_16x16x32_bf16 v[66:69], v[180:183], v[216:219], v[66:69]
	v_mfma_f32_16x16x32_bf16 v[66:69], v[184:187], v[220:223], v[66:69]
	v_mfma_f32_16x16x32_bf16 v[82:85], v[184:187], v[212:215], v[82:85]
	v_mfma_f32_16x16x32_bf16 v[82:85], v[180:183], v[208:211], v[82:85]
	v_mfma_f32_16x16x32_bf16 v[98:101], v[180:183], v[200:203], v[98:101]
	v_mfma_f32_16x16x32_bf16 v[98:101], v[184:187], v[204:207], v[98:101]
	v_mfma_f32_16x16x32_bf16 v[114:117], v[184:187], v[196:199], v[114:117]
	v_mfma_f32_16x16x32_bf16 v[114:117], v[180:183], v[188:191], v[114:117]
	s_barrier
	s_add_i32 s77, s59, s3
	s_mov_b32 m0, s77
	ds_read_b128 v[188:191], v156 offset:16384
	ds_read_b128 v[196:199], v156 offset:17408
	ds_read_b128 v[200:203], v156 offset:18432
	ds_read_b128 v[204:207], v156 offset:19456
	ds_read_b128 v[208:211], v156 offset:20480
	ds_read_b128 v[212:215], v156 offset:21504
	ds_read_b128 v[216:219], v156 offset:22528
	ds_read_b128 v[220:223], v156 offset:23552
	global_load_lds_dwordx4 v132, s[48:49]
	s_add_i32 m0, s77, 0x2000
	s_add_u32 s78, s48, 0x4000
	s_addc_u32 s79, s49, 0
	s_add_i32 s77, s61, s3
	global_load_lds_dwordx4 v136, s[48:49]
	s_mov_b32 m0, s77
	s_nop 0
	global_load_lds_dwordx4 v132, s[78:79]
	s_add_i32 m0, s77, 0x2000
	s_nop 0
	global_load_lds_dwordx4 v136, s[78:79]
	s_waitcnt vmcnt(6)
	s_waitcnt lgkmcnt(0)
	s_barrier
	s_waitcnt lgkmcnt(0)
	v_mfma_f32_16x16x32_bf16 v[62:65], v[148:151], v[188:191], v[62:65]
	v_mfma_f32_16x16x32_bf16 v[62:65], v[158:161], v[196:199], v[62:65]
	v_mfma_f32_16x16x32_bf16 v[46:49], v[158:161], v[204:207], v[46:49]
	v_mfma_f32_16x16x32_bf16 v[46:49], v[148:151], v[200:203], v[46:49]
	v_mfma_f32_16x16x32_bf16 v[30:33], v[148:151], v[208:211], v[30:33]
	v_mfma_f32_16x16x32_bf16 v[30:33], v[158:161], v[212:215], v[30:33]
	v_mfma_f32_16x16x32_bf16 v[14:17], v[158:161], v[220:223], v[14:17]
	v_mfma_f32_16x16x32_bf16 v[14:17], v[148:151], v[216:219], v[14:17]
	v_mfma_f32_16x16x32_bf16 v[10:13], v[162:165], v[216:219], v[10:13]
	v_mfma_f32_16x16x32_bf16 v[10:13], v[166:169], v[220:223], v[10:13]
	v_mfma_f32_16x16x32_bf16 v[26:29], v[166:169], v[212:215], v[26:29]
	v_mfma_f32_16x16x32_bf16 v[26:29], v[162:165], v[208:211], v[26:29]
	v_mfma_f32_16x16x32_bf16 v[42:45], v[162:165], v[200:203], v[42:45]
	v_mfma_f32_16x16x32_bf16 v[42:45], v[166:169], v[204:207], v[42:45]
	v_mfma_f32_16x16x32_bf16 v[58:61], v[166:169], v[196:199], v[58:61]
	v_mfma_f32_16x16x32_bf16 v[58:61], v[162:165], v[188:191], v[58:61]
	v_mfma_f32_16x16x32_bf16 v[54:57], v[170:173], v[188:191], v[54:57]
	v_mfma_f32_16x16x32_bf16 v[54:57], v[174:177], v[196:199], v[54:57]
	v_mfma_f32_16x16x32_bf16 v[38:41], v[174:177], v[204:207], v[38:41]
	v_mfma_f32_16x16x32_bf16 v[38:41], v[170:173], v[200:203], v[38:41]
	v_mfma_f32_16x16x32_bf16 v[22:25], v[170:173], v[208:211], v[22:25]
	v_mfma_f32_16x16x32_bf16 v[22:25], v[174:177], v[212:215], v[22:25]
	v_mfma_f32_16x16x32_bf16 v[6:9], v[174:177], v[220:223], v[6:9]
	v_mfma_f32_16x16x32_bf16 v[6:9], v[170:173], v[216:219], v[6:9]
	v_mfma_f32_16x16x32_bf16 v[2:5], v[180:183], v[216:219], v[2:5]
	v_mfma_f32_16x16x32_bf16 v[2:5], v[184:187], v[220:223], v[2:5]
	v_mfma_f32_16x16x32_bf16 v[18:21], v[184:187], v[212:215], v[18:21]
	v_mfma_f32_16x16x32_bf16 v[18:21], v[180:183], v[208:211], v[18:21]
	v_mfma_f32_16x16x32_bf16 v[34:37], v[180:183], v[200:203], v[34:37]
	v_mfma_f32_16x16x32_bf16 v[34:37], v[184:187], v[204:207], v[34:37]
	v_mfma_f32_16x16x32_bf16 v[50:53], v[184:187], v[196:199], v[50:53]
	v_mfma_f32_16x16x32_bf16 v[50:53], v[180:183], v[188:191], v[50:53]
	s_barrier
; #define PG8_STAGE(bufoff, gbase, voff) do { _Pragma("unroll") for (int _i = 0; _i < 2; ++_i) \
;         __builtin_amdgcn_global_load_lds((const unsigned*)((const char*)(gbase) + (voff)[_i]), (PG8_LAS unsigned*)(lds + (bufoff) + ldsw + _i * 8192), 16, 0, 0); } while (0)
; #define PG8_LDA(dst, b, h) do { _Pragma("unroll") for (int m = 0; m < 4; ++m) _Pragma("unroll") for (int k = 0; k < 2; ++k) dst[m][k] = *(const PG8_LAS bf16x8*)(lds + PG8_SA(b, h) + aoff + m * 2048 + k * 1024); } while (0)
; #define PG8_LDB(dst, b, h) do { _Pragma("unroll") for (int n = 0; n < 2; ++n) _Pragma("unroll") for (int k = 0; k < 2; ++k) dst[n][k] = *(const PG8_LAS bf16x8*)(lds + PG8_SB(b, h) + boff + n * 2048 + k * 1024); } while (0)
; #define PG8_MMA(ai, bj, At, Bt) do { __builtin_amdgcn_s_setprio(1); _Pragma("unroll") for (int m = 0; m < 4; ++m) _Pragma("unroll") for (int n = 0; n < 2; ++n) _Pragma("unroll") for (int k = 0; k < 2; ++k) \
;         acc[ai][bj][m][n] = __builtin_amdgcn_mfma_f32_16x16x32_bf16(Bt[n][k], At[m][k], acc[ai][bj][m][n], 0, 0, 0); __builtin_amdgcn_s_setprio(0); } while (0)
; #define PG8_WAIT_V(n) asm volatile("s_waitcnt vmcnt(" #n ")" ::: "memory")
; #define PG8_WAIT_L(n) asm volatile("s_waitcnt lgkmcnt(" #n ")" ::: "memory")
; #define PG8_BAR __builtin_amdgcn_s_barrier()
; #define PG8_SCHED __builtin_amdgcn_sched_barrier(0)
; template <class Epi, class Sched, bool ALIGN_EPI = false, bool SP2 = false>
; __device__ __forceinline__ void gemm_phase(PG8_LAS unsigned char* lds, const Gemm g, const Sched& S, const Epi& E) {
;     ...
;             PG8_LDB(B0, 1, 0); PG8_LDB(B1, 1, 1); PG8_SCHED; PG8_LDA(At, 1, 0); PG8_STAGE(PG8_SA(0, 1), a2 + hstep, voffA);
;             PG8_WAIT_V(8); PG8_WAIT_L(0); PG8_BAR; PG8_MMA(0, 0, At, B0); PG8_MMA(0, 1, At, B1); PG8_BAR; PG8_SCHED;
	s_add_i32 s77, 0, 0x18000
	v_add_u32_e32 v138, s77, v153
	s_add_i32 s78, 0, 0x1c000
	ds_read_b128 v[148:151], v138
	ds_read_b128 v[158:161], v138 offset:1024
	ds_read_b128 v[162:165], v138 offset:2048
	ds_read_b128 v[166:169], v138 offset:3072
	v_add_u32_e32 v138, s78, v153
	ds_read_b128 v[170:173], v138
	ds_read_b128 v[174:177], v138 offset:1024
	ds_read_b128 v[180:183], v138 offset:2048
	ds_read_b128 v[184:187], v138 offset:3072
	ds_read_b128 v[188:191], v156 offset:32768
	ds_read_b128 v[196:199], v156 offset:33792
	ds_read_b128 v[200:203], v156 offset:34816
	ds_read_b128 v[204:207], v156 offset:35840
	ds_read_b128 v[208:211], v156 offset:36864
	ds_read_b128 v[212:215], v156 offset:37888
	ds_read_b128 v[216:219], v156 offset:38912
	ds_read_b128 v[220:223], v156 offset:39936
	s_mov_b32 m0, s26
	s_nop 0
	global_load_lds_dwordx4 v130, s[50:51]
	s_mov_b32 m0, s27
	s_nop 0
	global_load_lds_dwordx4 v134, s[50:51]
	s_add_u32 s50, s50, 0x4000
	s_addc_u32 s51, s51, 0
	s_mov_b32 m0, s28
	s_nop 0
	global_load_lds_dwordx4 v130, s[50:51]
	s_mov_b32 m0, s29
	s_nop 0
	global_load_lds_dwordx4 v134, s[50:51]
	s_waitcnt vmcnt(8)
	s_waitcnt lgkmcnt(0)
	s_barrier
	s_waitcnt lgkmcnt(0)
	v_mfma_f32_16x16x32_bf16 v[126:129], v[148:151], v[188:191], v[126:129]
	v_mfma_f32_16x16x32_bf16 v[126:129], v[158:161], v[196:199], v[126:129]
	v_mfma_f32_16x16x32_bf16 v[110:113], v[158:161], v[204:207], v[110:113]
	v_mfma_f32_16x16x32_bf16 v[110:113], v[148:151], v[200:203], v[110:113]
	v_mfma_f32_16x16x32_bf16 v[94:97], v[148:151], v[208:211], v[94:97]
	v_mfma_f32_16x16x32_bf16 v[94:97], v[158:161], v[212:215], v[94:97]
	v_mfma_f32_16x16x32_bf16 v[78:81], v[158:161], v[220:223], v[78:81]
	v_mfma_f32_16x16x32_bf16 v[78:81], v[148:151], v[216:219], v[78:81]
	v_mfma_f32_16x16x32_bf16 v[74:77], v[162:165], v[216:219], v[74:77]
	v_mfma_f32_16x16x32_bf16 v[74:77], v[166:169], v[220:223], v[74:77]
	v_mfma_f32_16x16x32_bf16 v[90:93], v[166:169], v[212:215], v[90:93]
	v_mfma_f32_16x16x32_bf16 v[90:93], v[162:165], v[208:211], v[90:93]
	v_mfma_f32_16x16x32_bf16 v[106:109], v[162:165], v[200:203], v[106:109]
	v_mfma_f32_16x16x32_bf16 v[106:109], v[166:169], v[204:207], v[106:109]
	v_mfma_f32_16x16x32_bf16 v[122:125], v[166:169], v[196:199], v[122:125]
	v_mfma_f32_16x16x32_bf16 v[122:125], v[162:165], v[188:191], v[122:125]
	v_mfma_f32_16x16x32_bf16 v[118:121], v[170:173], v[188:191], v[118:121]
	v_mfma_f32_16x16x32_bf16 v[118:121], v[174:177], v[196:199], v[118:121]
	v_mfma_f32_16x16x32_bf16 v[102:105], v[174:177], v[204:207], v[102:105]
	v_mfma_f32_16x16x32_bf16 v[102:105], v[170:173], v[200:203], v[102:105]
	v_mfma_f32_16x16x32_bf16 v[86:89], v[170:173], v[208:211], v[86:89]
	v_mfma_f32_16x16x32_bf16 v[86:89], v[174:177], v[212:215], v[86:89]
	v_mfma_f32_16x16x32_bf16 v[70:73], v[174:177], v[220:223], v[70:73]
	v_mfma_f32_16x16x32_bf16 v[70:73], v[170:173], v[216:219], v[70:73]
	v_mfma_f32_16x16x32_bf16 v[66:69], v[180:183], v[216:219], v[66:69]
	v_mfma_f32_16x16x32_bf16 v[66:69], v[184:187], v[220:223], v[66:69]
	v_mfma_f32_16x16x32_bf16 v[82:85], v[184:187], v[212:215], v[82:85]
	v_mfma_f32_16x16x32_bf16 v[82:85], v[180:183], v[208:211], v[82:85]
	v_mfma_f32_16x16x32_bf16 v[98:101], v[180:183], v[200:203], v[98:101]
	v_mfma_f32_16x16x32_bf16 v[98:101], v[184:187], v[204:207], v[98:101]
	v_mfma_f32_16x16x32_bf16 v[114:117], v[184:187], v[196:199], v[114:117]
	v_mfma_f32_16x16x32_bf16 v[114:117], v[180:183], v[188:191], v[114:117]
	s_barrier
; #define PG8_STAGE(bufoff, gbase, voff) do { _Pragma("unroll") for (int _i = 0; _i < 2; ++_i) \
;         __builtin_amdgcn_global_load_lds((const unsigned*)((const char*)(gbase) + (voff)[_i]), (PG8_LAS unsigned*)(lds + (bufoff) + ldsw + _i * 8192), 16, 0, 0); } while (0)
; #define PG8_LDA(dst, b, h) do { _Pragma("unroll") for (int m = 0; m < 4; ++m) _Pragma("unroll") for (int k = 0; k < 2; ++k) dst[m][k] = *(const PG8_LAS bf16x8*)(lds + PG8_SA(b, h) + aoff + m * 2048 + k * 1024); } while (0)
; #define PG8_MMA(ai, bj, At, Bt) do { __builtin_amdgcn_s_setprio(1); _Pragma("unroll") for (int m = 0; m < 4; ++m) _Pragma("unroll") for (int n = 0; n < 2; ++n) _Pragma("unroll") for (int k = 0; k < 2; ++k) \
;         acc[ai][bj][m][n] = __builtin_amdgcn_mfma_f32_16x16x32_bf16(Bt[n][k], At[m][k], acc[ai][bj][m][n], 0, 0, 0); __builtin_amdgcn_s_setprio(0); } while (0)
; #define PG8_WAIT_V(n) asm volatile("s_waitcnt vmcnt(" #n ")" ::: "memory")
; #define PG8_WAIT_L(n) asm volatile("s_waitcnt lgkmcnt(" #n ")" ::: "memory")
; #define PG8_BAR __builtin_amdgcn_s_barrier()
; #define PG8_SCHED __builtin_amdgcn_sched_barrier(0)
; template <class Epi, class Sched, bool ALIGN_EPI = false, bool SP2 = false>
; __device__ __forceinline__ void gemm_phase(PG8_LAS unsigned char* lds, const Gemm g, const Sched& S, const Epi& E) {
;     ...
;         for (; t < tend; t += 2) {
;             const bool last = (t == nt - 2);
;             const char* a1 = cA + (size_t)(t + 1) * kstep;
;             const char* a2 = last ? nA : cA + (size_t)(t + 2) * kstep; const char* b2 = last ? nB : cB + (size_t)(t + 2) * kstep;
;             const char* a3 = a2 + kstep; const char* b3 = b2 + kstep;
;             if (last && has_next) S.a_ready(nxt);
;     ...
;             PG8_LDA(At, 1, 1); PG8_STAGE(PG8_SB(1, 0), b3, voffB); PG8_STAGE(PG8_SB(1, 1), b3 + hstep, voffB); PG8_STAGE(PG8_SA(1, 0), a3, voffA);
;             PG8_WAIT_V(8); PG8_WAIT_L(0); PG8_BAR; PG8_MMA(1, 0, At, B0); PG8_MMA(1, 1, At, B1); PG8_BAR; PG8_SCHED;
	s_add_u32 s50, s48, 0x8000
	s_addc_u32 s51, s49, 0
	s_add_i32 s77, s77, s3
	s_mov_b32 m0, s77
	ds_read_b128 v[188:191], v156 offset:49152
	ds_read_b128 v[196:199], v156 offset:50176
	ds_read_b128 v[200:203], v156 offset:51200
	ds_read_b128 v[204:207], v156 offset:52224
	ds_read_b128 v[208:211], v156 offset:53248
	ds_read_b128 v[212:215], v156 offset:54272
	ds_read_b128 v[216:219], v156 offset:55296
	ds_read_b128 v[220:223], v156 offset:56320
	global_load_lds_dwordx4 v132, s[50:51]
	s_add_i32 m0, s77, 0x2000
	s_add_u32 s48, s48, 0xc000
	v_lshl_add_u64 v[224:225], s[50:51], 0, v[136:137]
	s_addc_u32 s49, s49, 0
	s_add_i32 s50, s78, s3
	global_load_lds_dwordx4 v[224:225], off
	s_mov_b32 m0, s50
	s_nop 0
	global_load_lds_dwordx4 v132, s[48:49]
	s_add_i32 m0, s50, 0x2000
	s_nop 0
	global_load_lds_dwordx4 v136, s[48:49]
	s_add_i32 s76, s76, 2
	s_add_u32 s44, s44, 0x10000
	s_addc_u32 s45, s45, 0
	s_add_u32 s74, s74, 0x10000
	s_addc_u32 s75, s75, 0
	s_add_u32 s46, s44, 0x4000
	s_addc_u32 s47, s45, 0
	s_cmpk_eq_i32 s76, 0xa8
	s_cselect_b32 s50, s6, s46
	s_cselect_b32 s51, s7, s47
	s_cselect_b32 s48, s24, s74
	s_cselect_b32 s49, s25, s75
	s_add_u32 s46, s50, 0x8000
	s_addc_u32 s47, s51, 0
	s_sub_u32 s46, s44, 0x4000
	s_subb_u32 s47, s45, 0
	s_cmpk_gt_u32 s76, 0xa9
	s_waitcnt vmcnt(6)
	s_waitcnt lgkmcnt(0)
	s_barrier
	s_waitcnt lgkmcnt(0)
	v_mfma_f32_16x16x32_bf16 v[62:65], v[148:151], v[188:191], v[62:65]
	v_mfma_f32_16x16x32_bf16 v[62:65], v[158:161], v[196:199], v[62:65]
	v_mfma_f32_16x16x32_bf16 v[46:49], v[158:161], v[204:207], v[46:49]
	v_mfma_f32_16x16x32_bf16 v[46:49], v[148:151], v[200:203], v[46:49]
	v_mfma_f32_16x16x32_bf16 v[30:33], v[148:151], v[208:211], v[30:33]
	v_mfma_f32_16x16x32_bf16 v[30:33], v[158:161], v[212:215], v[30:33]
	v_mfma_f32_16x16x32_bf16 v[14:17], v[158:161], v[220:223], v[14:17]
	v_mfma_f32_16x16x32_bf16 v[14:17], v[148:151], v[216:219], v[14:17]
	v_mfma_f32_16x16x32_bf16 v[10:13], v[162:165], v[216:219], v[10:13]
	v_mfma_f32_16x16x32_bf16 v[10:13], v[166:169], v[220:223], v[10:13]
	v_mfma_f32_16x16x32_bf16 v[26:29], v[166:169], v[212:215], v[26:29]
	v_mfma_f32_16x16x32_bf16 v[26:29], v[162:165], v[208:211], v[26:29]
	v_mfma_f32_16x16x32_bf16 v[42:45], v[162:165], v[200:203], v[42:45]
	v_mfma_f32_16x16x32_bf16 v[42:45], v[166:169], v[204:207], v[42:45]
	v_mfma_f32_16x16x32_bf16 v[58:61], v[166:169], v[196:199], v[58:61]
	v_mfma_f32_16x16x32_bf16 v[58:61], v[162:165], v[188:191], v[58:61]
	v_mfma_f32_16x16x32_bf16 v[54:57], v[170:173], v[188:191], v[54:57]
	v_mfma_f32_16x16x32_bf16 v[54:57], v[174:177], v[196:199], v[54:57]
	v_mfma_f32_16x16x32_bf16 v[38:41], v[174:177], v[204:207], v[38:41]
	v_mfma_f32_16x16x32_bf16 v[38:41], v[170:173], v[200:203], v[38:41]
	v_mfma_f32_16x16x32_bf16 v[22:25], v[170:173], v[208:211], v[22:25]
	v_mfma_f32_16x16x32_bf16 v[22:25], v[174:177], v[212:215], v[22:25]
	v_mfma_f32_16x16x32_bf16 v[6:9], v[174:177], v[220:223], v[6:9]
	v_mfma_f32_16x16x32_bf16 v[6:9], v[170:173], v[216:219], v[6:9]
	v_mfma_f32_16x16x32_bf16 v[2:5], v[180:183], v[216:219], v[2:5]
	v_mfma_f32_16x16x32_bf16 v[2:5], v[184:187], v[220:223], v[2:5]
	v_mfma_f32_16x16x32_bf16 v[18:21], v[184:187], v[212:215], v[18:21]
	v_mfma_f32_16x16x32_bf16 v[18:21], v[180:183], v[208:211], v[18:21]
	v_mfma_f32_16x16x32_bf16 v[34:37], v[180:183], v[200:203], v[34:37]
	v_mfma_f32_16x16x32_bf16 v[34:37], v[184:187], v[204:207], v[34:37]
	v_mfma_f32_16x16x32_bf16 v[50:53], v[184:187], v[196:199], v[50:53]
	v_mfma_f32_16x16x32_bf16 v[50:53], v[180:183], v[188:191], v[50:53]
	s_barrier
	s_cbranch_scc0 .LBB0_200
	s_and_b64 vcc, exec, s[18:19]
	s_cbranch_vccz .LBB0_203
	s_barrier

;     __device__ __forceinline__ bool next(int i, Unit& u) const { if (i >= 2) return false; const int xcd = c & 7, off = c >> 3; u.pm = 16 * i + 4 * (xcd >> 1) + (off & 3); u.pn = 8 * (xcd & 1) + (off >> 2); return true; }
; #define PG8_STAGE(bufoff, gbase, voff) do { _Pragma("unroll") for (int _i = 0; _i < 2; ++_i) \
;         __builtin_amdgcn_global_load_lds((const unsigned*)((const char*)(gbase) + (voff)[_i]), (PG8_LAS unsigned*)(lds + (bufoff) + ldsw + _i * 8192), 16, 0, 0); } while (0)
; #define PG8_LDA(dst, b, h) do { _Pragma("unroll") for (int m = 0; m < 4; ++m) _Pragma("unroll") for (int k = 0; k < 2; ++k) dst[m][k] = *(const PG8_LAS bf16x8*)(lds + PG8_SA(b, h) + aoff + m * 2048 + k * 1024); } while (0)
; #define PG8_WAIT_V(n) asm volatile("s_waitcnt vmcnt(" #n ")" ::: "memory")
; #define PG8_BAR __builtin_amdgcn_s_barrier()
; template <class Epi, class Sched, bool ALIGN_EPI = false, bool SP2 = false>
; __device__ __forceinline__ void gemm_phase(PG8_LAS unsigned char* lds, const Gemm g, const Sched& S, const Epi& E) {
;     ...
;         const bool has_next = S.next(ui + 1, nxt);
;         const char* nA = has_next ? (const char*)g.A + (size_t)nxt.pm * tstep : cA; const char* nB = has_next ? (const char*)g.Bt + (size_t)nxt.pn * tstep : cB;
;         constexpr int NSEG = Epi::HAS_MID ? 2 : 1; int t = 0;
; #pragma unroll
;         for (int seg = 0; seg < NSEG; ++seg) { const int tend = (seg + 1 < NSEG) ? (nt >> 1) : nt;
;         for (; t < tend; t += 2) {
;             const bool last = (t == nt - 2);
;             const char* a1 = cA + (size_t)(t + 1) * kstep;
;             const char* a2 = last ? nA : cA + (size_t)(t + 2) * kstep; const char* b2 = last ? nB : cB + (size_t)(t + 2) * kstep;
;             const char* a3 = a2 + kstep; const char* b3 = b2 + kstep;
;             if (last && has_next) S.a_ready(nxt);
;             if constexpr (SP2) {
;             PG8_LDB(B0, 0, 0); PG8_LDB(B1, 0, 1); PG8_SCHED; PG8_LDA(At, 0, 0); PG8_STAGE(PG8_SA(1, 1), a1 + hstep, voffA);
;             PG8_WAIT_V(8); PG8_WAIT_L(0); PG8_BAR; PG8_MMA(0, 0, At, B0); PG8_MMA(0, 1, At, B1); PG8_BAR; PG8_SCHED;
;             PG8_LDA(At, 0, 1); PG8_STAGE(PG8_SB(0, 0), b2, voffB); PG8_STAGE(PG8_SB(0, 1), b2 + hstep, voffB); PG8_STAGE(PG8_SA(0, 0), a2, voffA);
;             PG8_WAIT_V(8); PG8_WAIT_L(0); PG8_BAR; PG8_MMA(1, 0, At, B0); PG8_MMA(1, 1, At, B1); PG8_BAR; PG8_SCHED;
.LBB0_289:
	s_ashr_i32 s19, s18, 31
	s_lshl_b64 s[46:47], s[18:19], 21
	s_add_u32 s46, s42, s46
	s_addc_u32 s47, s43, s47
	s_and_b64 s[48:49], s[0:1], exec
	s_cselect_b32 s5, s47, s73
	s_cselect_b32 s19, s46, s72
	s_ashr_i32 s17, s16, 31
	s_lshl_b64 s[48:49], s[16:17], 21
	s_add_u32 s48, s70, s48
	s_addc_u32 s49, s71, s49
	s_and_b64 s[58:59], s[0:1], exec
	s_cselect_b32 s17, s49, s75
	s_cselect_b32 s26, s48, s74
	s_add_u32 s72, s72, 0xc000
	s_addc_u32 s73, s73, 0
	s_add_u32 s33, s74, 0x10000
	s_addc_u32 s56, s75, 0
	s_mov_b32 s58, -2
	s_nop 3
	s_add_u32 s59, s72, 0x4000
	s_addc_u32 s62, s73, 0
	s_cmp_eq_u32 s58, 60
	s_cselect_b32 s78, s19, s59
	s_cselect_b32 s79, s5, s62
	s_cselect_b32 s76, s26, s33
	s_cselect_b32 s77, s17, s56
	s_add_u32 s74, s78, 0x8000
	s_addc_u32 s75, s79, 0
	s_sub_u32 s74, s72, 0x4000
	s_subb_u32 s75, s73, 0
	ds_read_b128 v[146:149], v162
	ds_read_b128 v[150:153], v162 offset:1024
	ds_read_b128 v[154:157], v162 offset:2048
	ds_read_b128 v[168:171], v162 offset:3072
	ds_read_b128 v[172:175], v163
	ds_read_b128 v[180:183], v163 offset:1024
	ds_read_b128 v[184:187], v163 offset:2048
	ds_read_b128 v[188:191], v163 offset:3072
	ds_read_b128 v[198:201], v164
	ds_read_b128 v[202:205], v164 offset:1024
	ds_read_b128 v[206:209], v164 offset:2048
	ds_read_b128 v[210:213], v164 offset:3072
	ds_read_b128 v[214:217], v164 offset:4096
	ds_read_b128 v[218:221], v164 offset:5120
	ds_read_b128 v[222:225], v164 offset:6144
	ds_read_b128 v[226:229], v164 offset:7168
	s_mov_b32 m0, s51
	s_nop 0
	global_load_lds_dwordx4 v130, s[74:75]
	s_mov_b32 m0, s57
	s_nop 0
	global_load_lds_dwordx4 v134, s[74:75]
	s_add_i32 m0, s15, 0xc000
	s_nop 0
	global_load_lds_dwordx4 v138, s[72:73]
	s_add_i32 m0, s15, 0xe000
	s_nop 0
	global_load_lds_dwordx4 v140, s[72:73]
	s_waitcnt vmcnt(8)
	s_waitcnt lgkmcnt(0)
	s_barrier
	s_waitcnt lgkmcnt(0)
	v_mfma_f32_16x16x32_bf16 v[126:129], v[146:149], v[198:201], 0
	v_mfma_f32_16x16x32_bf16 v[126:129], v[150:153], v[202:205], v[126:129]
	v_mfma_f32_16x16x32_bf16 v[110:113], v[150:153], v[210:213], 0
	v_mfma_f32_16x16x32_bf16 v[110:113], v[146:149], v[206:209], v[110:113]
	v_mfma_f32_16x16x32_bf16 v[94:97], v[146:149], v[214:217], 0
	v_mfma_f32_16x16x32_bf16 v[94:97], v[150:153], v[218:221], v[94:97]
	v_mfma_f32_16x16x32_bf16 v[78:81], v[150:153], v[226:229], 0
	v_mfma_f32_16x16x32_bf16 v[78:81], v[146:149], v[222:225], v[78:81]
	v_mfma_f32_16x16x32_bf16 v[74:77], v[154:157], v[222:225], 0
	v_mfma_f32_16x16x32_bf16 v[74:77], v[168:171], v[226:229], v[74:77]
	v_mfma_f32_16x16x32_bf16 v[90:93], v[168:171], v[218:221], 0
	v_mfma_f32_16x16x32_bf16 v[90:93], v[154:157], v[214:217], v[90:93]
	v_mfma_f32_16x16x32_bf16 v[106:109], v[154:157], v[206:209], 0
	v_mfma_f32_16x16x32_bf16 v[106:109], v[168:171], v[210:213], v[106:109]
	v_mfma_f32_16x16x32_bf16 v[122:125], v[168:171], v[202:205], 0
	v_mfma_f32_16x16x32_bf16 v[122:125], v[154:157], v[198:201], v[122:125]
	v_mfma_f32_16x16x32_bf16 v[118:121], v[172:175], v[198:201], 0
	v_mfma_f32_16x16x32_bf16 v[118:121], v[180:183], v[202:205], v[118:121]
	v_mfma_f32_16x16x32_bf16 v[102:105], v[180:183], v[210:213], 0
	v_mfma_f32_16x16x32_bf16 v[102:105], v[172:175], v[206:209], v[102:105]
	v_mfma_f32_16x16x32_bf16 v[86:89], v[172:175], v[214:217], 0
	v_mfma_f32_16x16x32_bf16 v[86:89], v[180:183], v[218:221], v[86:89]
	v_mfma_f32_16x16x32_bf16 v[70:73], v[180:183], v[226:229], 0
	v_mfma_f32_16x16x32_bf16 v[70:73], v[172:175], v[222:225], v[70:73]
	v_mfma_f32_16x16x32_bf16 v[66:69], v[184:187], v[222:225], 0
	v_mfma_f32_16x16x32_bf16 v[66:69], v[188:191], v[226:229], v[66:69]
	v_mfma_f32_16x16x32_bf16 v[82:85], v[188:191], v[218:221], 0
	v_mfma_f32_16x16x32_bf16 v[82:85], v[184:187], v[214:217], v[82:85]
	v_mfma_f32_16x16x32_bf16 v[98:101], v[184:187], v[206:209], 0
	v_mfma_f32_16x16x32_bf16 v[98:101], v[188:191], v[210:213], v[98:101]
	v_mfma_f32_16x16x32_bf16 v[114:117], v[188:191], v[202:205], 0
	v_mfma_f32_16x16x32_bf16 v[114:117], v[184:187], v[198:201], v[114:117]
	s_barrier
	s_add_i32 s59, s81, s3
	s_mov_b32 m0, s59
	ds_read_b128 v[198:201], v164 offset:16384
	ds_read_b128 v[202:205], v164 offset:17408
	ds_read_b128 v[206:209], v164 offset:18432
	ds_read_b128 v[210:213], v164 offset:19456
	ds_read_b128 v[214:217], v164 offset:20480
	ds_read_b128 v[218:221], v164 offset:21504
	ds_read_b128 v[222:225], v164 offset:22528
	ds_read_b128 v[226:229], v164 offset:23552
	global_load_lds_dwordx4 v132, s[76:77]
	s_add_i32 m0, s59, 0x2000
	s_add_u32 s62, s76, 0x4000
	s_addc_u32 s63, s77, 0
	s_add_i32 s59, s82, s3
	global_load_lds_dwordx4 v136, s[76:77]
	s_mov_b32 m0, s59
	s_nop 0
	global_load_lds_dwordx4 v132, s[62:63]
	s_add_i32 m0, s59, 0x2000
	s_nop 0
	global_load_lds_dwordx4 v136, s[62:63]
	s_waitcnt vmcnt(6)
	s_waitcnt lgkmcnt(0)
	s_barrier
; #define PG8_STAGE(bufoff, gbase, voff) do { _Pragma("unroll") for (int _i = 0; _i < 2; ++_i) \
;         __builtin_amdgcn_global_load_lds((const unsigned*)((const char*)(gbase) + (voff)[_i]), (PG8_LAS unsigned*)(lds + (bufoff) + ldsw + _i * 8192), 16, 0, 0); } while (0)
; #define PG8_LDA(dst, b, h) do { _Pragma("unroll") for (int m = 0; m < 4; ++m) _Pragma("unroll") for (int k = 0; k < 2; ++k) dst[m][k] = *(const PG8_LAS bf16x8*)(lds + PG8_SA(b, h) + aoff + m * 2048 + k * 1024); } while (0)
; #define PG8_LDB(dst, b, h) do { _Pragma("unroll") for (int n = 0; n < 2; ++n) _Pragma("unroll") for (int k = 0; k < 2; ++k) dst[n][k] = *(const PG8_LAS bf16x8*)(lds + PG8_SB(b, h) + boff + n * 2048 + k * 1024); } while (0)
; #define PG8_MMA(ai, bj, At, Bt) do { __builtin_amdgcn_s_setprio(1); _Pragma("unroll") for (int m = 0; m < 4; ++m) _Pragma("unroll") for (int n = 0; n < 2; ++n) _Pragma("unroll") for (int k = 0; k < 2; ++k) \
;         acc[ai][bj][m][n] = __builtin_amdgcn_mfma_f32_16x16x32_bf16(Bt[n][k], At[m][k], acc[ai][bj][m][n], 0, 0, 0); __builtin_amdgcn_s_setprio(0); } while (0)
; #define PG8_WAIT_V(n) asm volatile("s_waitcnt vmcnt(" #n ")" ::: "memory")
; #define PG8_WAIT_L(n) asm volatile("s_waitcnt lgkmcnt(" #n ")" ::: "memory")
; #define PG8_BAR __builtin_amdgcn_s_barrier()
; #define PG8_SCHED __builtin_amdgcn_sched_barrier(0)
; template <class Epi, class Sched, bool ALIGN_EPI = false, bool SP2 = false>
; __device__ __forceinline__ void gemm_phase(PG8_LAS unsigned char* lds, const Gemm g, const Sched& S, const Epi& E) {
;     ...
;             PG8_WAIT_V(8); PG8_WAIT_L(0); PG8_BAR; PG8_MMA(1, 0, At, B0); PG8_MMA(1, 1, At, B1); PG8_BAR; PG8_SCHED;
;             PG8_LDB(B0, 1, 0); PG8_LDB(B1, 1, 1); PG8_SCHED; PG8_LDA(At, 1, 0); PG8_STAGE(PG8_SA(0, 1), a2 + hstep, voffA);
;             PG8_WAIT_V(8); PG8_WAIT_L(0); PG8_BAR; PG8_MMA(0, 0, At, B0); PG8_MMA(0, 1, At, B1); PG8_BAR; PG8_SCHED;
	s_waitcnt lgkmcnt(0)
	v_mfma_f32_16x16x32_bf16 v[62:65], v[146:149], v[198:201], 0
	v_mfma_f32_16x16x32_bf16 v[62:65], v[150:153], v[202:205], v[62:65]
	v_mfma_f32_16x16x32_bf16 v[46:49], v[150:153], v[210:213], 0
	v_mfma_f32_16x16x32_bf16 v[46:49], v[146:149], v[206:209], v[46:49]
	v_mfma_f32_16x16x32_bf16 v[30:33], v[146:149], v[214:217], 0
	v_mfma_f32_16x16x32_bf16 v[30:33], v[150:153], v[218:221], v[30:33]
	v_mfma_f32_16x16x32_bf16 v[14:17], v[150:153], v[226:229], 0
	v_mfma_f32_16x16x32_bf16 v[14:17], v[146:149], v[222:225], v[14:17]
	v_mfma_f32_16x16x32_bf16 v[10:13], v[154:157], v[222:225], 0
	v_mfma_f32_16x16x32_bf16 v[10:13], v[168:171], v[226:229], v[10:13]
	v_mfma_f32_16x16x32_bf16 v[26:29], v[168:171], v[218:221], 0
	v_mfma_f32_16x16x32_bf16 v[26:29], v[154:157], v[214:217], v[26:29]
	v_mfma_f32_16x16x32_bf16 v[42:45], v[154:157], v[206:209], 0
	v_mfma_f32_16x16x32_bf16 v[42:45], v[168:171], v[210:213], v[42:45]
	v_mfma_f32_16x16x32_bf16 v[58:61], v[168:171], v[202:205], 0
	v_mfma_f32_16x16x32_bf16 v[58:61], v[154:157], v[198:201], v[58:61]
	v_mfma_f32_16x16x32_bf16 v[54:57], v[172:175], v[198:201], 0
	v_mfma_f32_16x16x32_bf16 v[54:57], v[180:183], v[202:205], v[54:57]
	v_mfma_f32_16x16x32_bf16 v[38:41], v[180:183], v[210:213], 0
	v_mfma_f32_16x16x32_bf16 v[38:41], v[172:175], v[206:209], v[38:41]
	v_mfma_f32_16x16x32_bf16 v[22:25], v[172:175], v[214:217], 0
	v_mfma_f32_16x16x32_bf16 v[22:25], v[180:183], v[218:221], v[22:25]
	v_mfma_f32_16x16x32_bf16 v[6:9], v[180:183], v[226:229], 0
	v_mfma_f32_16x16x32_bf16 v[6:9], v[172:175], v[222:225], v[6:9]
	v_mfma_f32_16x16x32_bf16 v[2:5], v[184:187], v[222:225], 0
	v_mfma_f32_16x16x32_bf16 v[2:5], v[188:191], v[226:229], v[2:5]
	v_mfma_f32_16x16x32_bf16 v[18:21], v[188:191], v[218:221], 0
	v_mfma_f32_16x16x32_bf16 v[18:21], v[184:187], v[214:217], v[18:21]
	v_mfma_f32_16x16x32_bf16 v[34:37], v[184:187], v[206:209], 0
	v_mfma_f32_16x16x32_bf16 v[34:37], v[188:191], v[210:213], v[34:37]
	v_mfma_f32_16x16x32_bf16 v[50:53], v[188:191], v[202:205], 0
	v_mfma_f32_16x16x32_bf16 v[50:53], v[184:187], v[198:201], v[50:53]
	s_barrier
	s_add_i32 s59, 0, 0x18000
	v_add_u32_e32 v158, s59, v160
	s_add_i32 s64, 0, 0x1c000
	ds_read_b128 v[146:149], v158
	ds_read_b128 v[150:153], v158 offset:1024
	ds_read_b128 v[154:157], v158 offset:2048
	ds_read_b128 v[168:171], v158 offset:3072
	v_add_u32_e32 v158, s64, v160
	ds_read_b128 v[172:175], v158
	ds_read_b128 v[180:183], v158 offset:1024
	ds_read_b128 v[184:187], v158 offset:2048
	ds_read_b128 v[188:191], v158 offset:3072
	ds_read_b128 v[198:201], v164 offset:32768
	ds_read_b128 v[202:205], v164 offset:33792
	ds_read_b128 v[206:209], v164 offset:34816
	ds_read_b128 v[210:213], v164 offset:35840
	ds_read_b128 v[214:217], v164 offset:36864
	ds_read_b128 v[218:221], v164 offset:37888
	ds_read_b128 v[222:225], v164 offset:38912
	ds_read_b128 v[226:229], v164 offset:39936
	s_mov_b32 m0, s15
	s_nop 0
	global_load_lds_dwordx4 v130, s[78:79]
	s_mov_b32 m0, s27
	s_nop 0
	global_load_lds_dwordx4 v134, s[78:79]
	s_add_u32 s62, s78, 0x4000
	s_addc_u32 s63, s79, 0
	s_mov_b32 m0, s28
	s_nop 0
	global_load_lds_dwordx4 v130, s[62:63]
	s_mov_b32 m0, s29
	s_nop 0
	global_load_lds_dwordx4 v134, s[62:63]
	s_waitcnt vmcnt(8)
	s_waitcnt lgkmcnt(0)
	s_barrier
	s_waitcnt lgkmcnt(0)
	v_mfma_f32_16x16x32_bf16 v[126:129], v[146:149], v[198:201], v[126:129]
	v_mfma_f32_16x16x32_bf16 v[126:129], v[150:153], v[202:205], v[126:129]
	v_mfma_f32_16x16x32_bf16 v[110:113], v[150:153], v[210:213], v[110:113]
	v_mfma_f32_16x16x32_bf16 v[110:113], v[146:149], v[206:209], v[110:113]
	v_mfma_f32_16x16x32_bf16 v[94:97], v[146:149], v[214:217], v[94:97]
	v_mfma_f32_16x16x32_bf16 v[94:97], v[150:153], v[218:221], v[94:97]
	v_mfma_f32_16x16x32_bf16 v[78:81], v[150:153], v[226:229], v[78:81]
	v_mfma_f32_16x16x32_bf16 v[78:81], v[146:149], v[222:225], v[78:81]
	v_mfma_f32_16x16x32_bf16 v[74:77], v[154:157], v[222:225], v[74:77]
	v_mfma_f32_16x16x32_bf16 v[74:77], v[168:171], v[226:229], v[74:77]
	v_mfma_f32_16x16x32_bf16 v[90:93], v[168:171], v[218:221], v[90:93]
	v_mfma_f32_16x16x32_bf16 v[90:93], v[154:157], v[214:217], v[90:93]
	v_mfma_f32_16x16x32_bf16 v[106:109], v[154:157], v[206:209], v[106:109]
	v_mfma_f32_16x16x32_bf16 v[106:109], v[168:171], v[210:213], v[106:109]
	v_mfma_f32_16x16x32_bf16 v[122:125], v[168:171], v[202:205], v[122:125]
	v_mfma_f32_16x16x32_bf16 v[122:125], v[154:157], v[198:201], v[122:125]
	v_mfma_f32_16x16x32_bf16 v[118:121], v[172:175], v[198:201], v[118:121]
	v_mfma_f32_16x16x32_bf16 v[118:121], v[180:183], v[202:205], v[118:121]
	v_mfma_f32_16x16x32_bf16 v[102:105], v[180:183], v[210:213], v[102:105]
	v_mfma_f32_16x16x32_bf16 v[102:105], v[172:175], v[206:209], v[102:105]
	v_mfma_f32_16x16x32_bf16 v[86:89], v[172:175], v[214:217], v[86:89]
	v_mfma_f32_16x16x32_bf16 v[86:89], v[180:183], v[218:221], v[86:89]
	v_mfma_f32_16x16x32_bf16 v[70:73], v[180:183], v[226:229], v[70:73]
	v_mfma_f32_16x16x32_bf16 v[70:73], v[172:175], v[222:225], v[70:73]
	v_mfma_f32_16x16x32_bf16 v[66:69], v[184:187], v[222:225], v[66:69]
	v_mfma_f32_16x16x32_bf16 v[66:69], v[188:191], v[226:229], v[66:69]
	v_mfma_f32_16x16x32_bf16 v[82:85], v[188:191], v[218:221], v[82:85]
	v_mfma_f32_16x16x32_bf16 v[82:85], v[184:187], v[214:217], v[82:85]
	v_mfma_f32_16x16x32_bf16 v[98:101], v[184:187], v[206:209], v[98:101]
	v_mfma_f32_16x16x32_bf16 v[98:101], v[188:191], v[210:213], v[98:101]
	v_mfma_f32_16x16x32_bf16 v[114:117], v[188:191], v[202:205], v[114:117]
	v_mfma_f32_16x16x32_bf16 v[114:117], v[184:187], v[198:201], v[114:117]
	s_barrier
; #define PG8_STAGE(bufoff, gbase, voff) do { _Pragma("unroll") for (int _i = 0; _i < 2; ++_i) \
;         __builtin_amdgcn_global_load_lds((const unsigned*)((const char*)(gbase) + (voff)[_i]), (PG8_LAS unsigned*)(lds + (bufoff) + ldsw + _i * 8192), 16, 0, 0); } while (0)
; #define PG8_LDA(dst, b, h) do { _Pragma("unroll") for (int m = 0; m < 4; ++m) _Pragma("unroll") for (int k = 0; k < 2; ++k) dst[m][k] = *(const PG8_LAS bf16x8*)(lds + PG8_SA(b, h) + aoff + m * 2048 + k * 1024); } while (0)
; #define PG8_LDB(dst, b, h) do { _Pragma("unroll") for (int n = 0; n < 2; ++n) _Pragma("unroll") for (int k = 0; k < 2; ++k) dst[n][k] = *(const PG8_LAS bf16x8*)(lds + PG8_SB(b, h) + boff + n * 2048 + k * 1024); } while (0)
; template <class Epi, class Sched, bool ALIGN_EPI = false, bool SP2 = false>
; __device__ __forceinline__ void gemm_phase(PG8_LAS unsigned char* lds, const Gemm g, const Sched& S, const Epi& E) {
;     ...
;         for (; t < tend; t += 2) {
;             const bool last = (t == nt - 2);
;             const char* a1 = cA + (size_t)(t + 1) * kstep;
;             const char* a2 = last ? nA : cA + (size_t)(t + 2) * kstep; const char* b2 = last ? nB : cB + (size_t)(t + 2) * kstep;
;             const char* a3 = a2 + kstep; const char* b3 = b2 + kstep;
;             if (last && has_next) S.a_ready(nxt);
;             if constexpr (SP2) {
;             PG8_LDB(B0, 0, 0); PG8_LDB(B1, 0, 1); PG8_SCHED; PG8_LDA(At, 0, 0); PG8_STAGE(PG8_SA(1, 1), a1 + hstep, voffA);
;             PG8_WAIT_V(8); PG8_WAIT_L(0); PG8_BAR; PG8_MMA(0, 0, At, B0); PG8_MMA(0, 1, At, B1); PG8_BAR; PG8_SCHED;
;             PG8_LDA(At, 0, 1); PG8_STAGE(PG8_SB(0, 0), b2, voffB); PG8_STAGE(PG8_SB(0, 1), b2 + hstep, voffB); PG8_STAGE(PG8_SA(0, 0), a2, voffA);
;             PG8_WAIT_V(8); PG8_WAIT_L(0); PG8_BAR; PG8_MMA(1, 0, At, B0); PG8_MMA(1, 1, At, B1); PG8_BAR; PG8_SCHED;
;             PG8_LDB(B0, 1, 0); PG8_LDB(B1, 1, 1); PG8_SCHED; PG8_LDA(At, 1, 0); PG8_STAGE(PG8_SA(0, 1), a2 + hstep, voffA);
;             PG8_WAIT_V(8); PG8_WAIT_L(0); PG8_BAR; PG8_MMA(0, 0, At, B0); PG8_MMA(0, 1, At, B1); PG8_BAR; PG8_SCHED;
;             PG8_LDA(At, 1, 1); PG8_STAGE(PG8_SB(1, 0), b3, voffB); PG8_STAGE(PG8_SB(1, 1), b3 + hstep, voffB); PG8_STAGE(PG8_SA(1, 0), a3, voffA);
;             PG8_WAIT_V(8); PG8_WAIT_L(0); PG8_BAR; PG8_MMA(1, 0, At, B0); PG8_MMA(1, 1, At, B1); PG8_BAR; PG8_SCHED;
	s_add_u32 s62, s76, 0x8000
	s_addc_u32 s63, s77, 0
	s_add_i32 s59, s59, s3
	s_mov_b32 m0, s59
	ds_read_b128 v[198:201], v164 offset:49152
	ds_read_b128 v[202:205], v164 offset:50176
	ds_read_b128 v[206:209], v164 offset:51200
	ds_read_b128 v[210:213], v164 offset:52224
	ds_read_b128 v[214:217], v164 offset:53248
	ds_read_b128 v[218:221], v164 offset:54272
	ds_read_b128 v[222:225], v164 offset:55296
	ds_read_b128 v[226:229], v164 offset:56320
	global_load_lds_dwordx4 v132, s[62:63]
	s_add_i32 m0, s59, 0x2000
	v_lshl_add_u64 v[158:159], s[62:63], 0, v[136:137]
	s_add_u32 s62, s76, 0xc000
	s_addc_u32 s63, s77, 0
	s_add_i32 s59, s64, s3
	global_load_lds_dwordx4 v[158:159], off
	s_mov_b32 m0, s59
	s_nop 0
	global_load_lds_dwordx4 v132, s[62:63]
	s_add_i32 m0, s59, 0x2000
	s_nop 0
	global_load_lds_dwordx4 v136, s[62:63]
	s_add_i32 s58, s58, 2
	s_add_u32 s72, s72, 0x10000
	s_addc_u32 s73, s73, 0
	s_add_u32 s33, s33, 0x10000
	s_addc_u32 s56, s56, 0
	s_add_u32 s59, s72, 0x4000
	s_addc_u32 s62, s73, 0
	s_cmp_eq_u32 s58, 60
	s_cselect_b32 s78, s19, s59
	s_cselect_b32 s79, s5, s62
	s_cselect_b32 s76, s26, s33
	s_cselect_b32 s77, s17, s56
	s_add_u32 s74, s78, 0x8000
	s_addc_u32 s75, s79, 0
	s_sub_u32 s74, s72, 0x4000
	s_subb_u32 s75, s73, 0
	s_cmp_gt_u32 s58, 61
	s_waitcnt vmcnt(6)
	s_waitcnt lgkmcnt(0)
	s_barrier
	s_waitcnt lgkmcnt(0)
	v_mfma_f32_16x16x32_bf16 v[62:65], v[146:149], v[198:201], v[62:65]
	v_mfma_f32_16x16x32_bf16 v[62:65], v[150:153], v[202:205], v[62:65]
	v_mfma_f32_16x16x32_bf16 v[46:49], v[150:153], v[210:213], v[46:49]
	v_mfma_f32_16x16x32_bf16 v[46:49], v[146:149], v[206:209], v[46:49]
	v_mfma_f32_16x16x32_bf16 v[30:33], v[146:149], v[214:217], v[30:33]
	v_mfma_f32_16x16x32_bf16 v[30:33], v[150:153], v[218:221], v[30:33]
	v_mfma_f32_16x16x32_bf16 v[14:17], v[150:153], v[226:229], v[14:17]
	v_mfma_f32_16x16x32_bf16 v[14:17], v[146:149], v[222:225], v[14:17]
	v_mfma_f32_16x16x32_bf16 v[10:13], v[154:157], v[222:225], v[10:13]
	v_mfma_f32_16x16x32_bf16 v[10:13], v[168:171], v[226:229], v[10:13]
	v_mfma_f32_16x16x32_bf16 v[26:29], v[168:171], v[218:221], v[26:29]
	v_mfma_f32_16x16x32_bf16 v[26:29], v[154:157], v[214:217], v[26:29]
	v_mfma_f32_16x16x32_bf16 v[42:45], v[154:157], v[206:209], v[42:45]
	v_mfma_f32_16x16x32_bf16 v[42:45], v[168:171], v[210:213], v[42:45]
	v_mfma_f32_16x16x32_bf16 v[58:61], v[168:171], v[202:205], v[58:61]
	v_mfma_f32_16x16x32_bf16 v[58:61], v[154:157], v[198:201], v[58:61]
	v_mfma_f32_16x16x32_bf16 v[54:57], v[172:175], v[198:201], v[54:57]
	v_mfma_f32_16x16x32_bf16 v[54:57], v[180:183], v[202:205], v[54:57]
	v_mfma_f32_16x16x32_bf16 v[38:41], v[180:183], v[210:213], v[38:41]
	v_mfma_f32_16x16x32_bf16 v[38:41], v[172:175], v[206:209], v[38:41]
	v_mfma_f32_16x16x32_bf16 v[22:25], v[172:175], v[214:217], v[22:25]
	v_mfma_f32_16x16x32_bf16 v[22:25], v[180:183], v[218:221], v[22:25]
	v_mfma_f32_16x16x32_bf16 v[6:9], v[180:183], v[226:229], v[6:9]
	v_mfma_f32_16x16x32_bf16 v[6:9], v[172:175], v[222:225], v[6:9]
	v_mfma_f32_16x16x32_bf16 v[2:5], v[184:187], v[222:225], v[2:5]
	v_mfma_f32_16x16x32_bf16 v[2:5], v[188:191], v[226:229], v[2:5]
	v_mfma_f32_16x16x32_bf16 v[18:21], v[188:191], v[218:221], v[18:21]
	v_mfma_f32_16x16x32_bf16 v[18:21], v[184:187], v[214:217], v[18:21]
	v_mfma_f32_16x16x32_bf16 v[34:37], v[184:187], v[206:209], v[34:37]
	v_mfma_f32_16x16x32_bf16 v[34:37], v[188:191], v[210:213], v[34:37]
	v_mfma_f32_16x16x32_bf16 v[50:53], v[188:191], v[202:205], v[50:53]
	v_mfma_f32_16x16x32_bf16 v[50:53], v[184:187], v[198:201], v[50:53]
	s_barrier
.LBB0_290:
	ds_read_b128 v[146:149], v162
	ds_read_b128 v[150:153], v162 offset:1024
	ds_read_b128 v[154:157], v162 offset:2048
	ds_read_b128 v[168:171], v162 offset:3072
	ds_read_b128 v[172:175], v163
	ds_read_b128 v[180:183], v163 offset:1024
	ds_read_b128 v[184:187], v163 offset:2048
	ds_read_b128 v[188:191], v163 offset:3072
	ds_read_b128 v[198:201], v164
	ds_read_b128 v[202:205], v164 offset:1024
	ds_read_b128 v[206:209], v164 offset:2048
	ds_read_b128 v[210:213], v164 offset:3072
	ds_read_b128 v[214:217], v164 offset:4096
	ds_read_b128 v[218:221], v164 offset:5120
	ds_read_b128 v[222:225], v164 offset:6144
	ds_read_b128 v[226:229], v164 offset:7168
	s_mov_b32 m0, s51
	s_nop 0
	global_load_lds_dwordx4 v130, s[74:75]
	s_mov_b32 m0, s57
	s_nop 0
	global_load_lds_dwordx4 v134, s[74:75]
	s_add_i32 m0, s15, 0xc000
	s_nop 0
	global_load_lds_dwordx4 v138, s[72:73]
	s_add_i32 m0, s15, 0xe000
	s_nop 0
	global_load_lds_dwordx4 v140, s[72:73]
	s_waitcnt vmcnt(8)
	s_waitcnt lgkmcnt(0)
	s_barrier
; #define PG8_STAGE(bufoff, gbase, voff) do { _Pragma("unroll") for (int _i = 0; _i < 2; ++_i) \
;         __builtin_amdgcn_global_load_lds((const unsigned*)((const char*)(gbase) + (voff)[_i]), (PG8_LAS unsigned*)(lds + (bufoff) + ldsw + _i * 8192), 16, 0, 0); } while (0)
; #define PG8_LDA(dst, b, h) do { _Pragma("unroll") for (int m = 0; m < 4; ++m) _Pragma("unroll") for (int k = 0; k < 2; ++k) dst[m][k] = *(const PG8_LAS bf16x8*)(lds + PG8_SA(b, h) + aoff + m * 2048 + k * 1024); } while (0)
; #define PG8_MMA(ai, bj, At, Bt) do { __builtin_amdgcn_s_setprio(1); _Pragma("unroll") for (int m = 0; m < 4; ++m) _Pragma("unroll") for (int n = 0; n < 2; ++n) _Pragma("unroll") for (int k = 0; k < 2; ++k) \
;         acc[ai][bj][m][n] = __builtin_amdgcn_mfma_f32_16x16x32_bf16(Bt[n][k], At[m][k], acc[ai][bj][m][n], 0, 0, 0); __builtin_amdgcn_s_setprio(0); } while (0)
; #define PG8_WAIT_V(n) asm volatile("s_waitcnt vmcnt(" #n ")" ::: "memory")
; #define PG8_WAIT_L(n) asm volatile("s_waitcnt lgkmcnt(" #n ")" ::: "memory")
; #define PG8_BAR __builtin_amdgcn_s_barrier()
; #define PG8_SCHED __builtin_amdgcn_sched_barrier(0)
; template <class Epi, class Sched, bool ALIGN_EPI = false, bool SP2 = false>
; __device__ __forceinline__ void gemm_phase(PG8_LAS unsigned char* lds, const Gemm g, const Sched& S, const Epi& E) {
;     ...
;             PG8_WAIT_V(8); PG8_WAIT_L(0); PG8_BAR; PG8_MMA(0, 0, At, B0); PG8_MMA(0, 1, At, B1); PG8_BAR; PG8_SCHED;
;             PG8_LDA(At, 0, 1); PG8_STAGE(PG8_SB(0, 0), b2, voffB); PG8_STAGE(PG8_SB(0, 1), b2 + hstep, voffB); PG8_STAGE(PG8_SA(0, 0), a2, voffA);
;             PG8_WAIT_V(8); PG8_WAIT_L(0); PG8_BAR; PG8_MMA(1, 0, At, B0); PG8_MMA(1, 1, At, B1); PG8_BAR; PG8_SCHED;
	s_waitcnt lgkmcnt(0)
	v_mfma_f32_16x16x32_bf16 v[126:129], v[146:149], v[198:201], v[126:129]
	v_mfma_f32_16x16x32_bf16 v[126:129], v[150:153], v[202:205], v[126:129]
	v_mfma_f32_16x16x32_bf16 v[110:113], v[150:153], v[210:213], v[110:113]
	v_mfma_f32_16x16x32_bf16 v[110:113], v[146:149], v[206:209], v[110:113]
	v_mfma_f32_16x16x32_bf16 v[94:97], v[146:149], v[214:217], v[94:97]
	v_mfma_f32_16x16x32_bf16 v[94:97], v[150:153], v[218:221], v[94:97]
	v_mfma_f32_16x16x32_bf16 v[78:81], v[150:153], v[226:229], v[78:81]
	v_mfma_f32_16x16x32_bf16 v[78:81], v[146:149], v[222:225], v[78:81]
	v_mfma_f32_16x16x32_bf16 v[74:77], v[154:157], v[222:225], v[74:77]
	v_mfma_f32_16x16x32_bf16 v[74:77], v[168:171], v[226:229], v[74:77]
	v_mfma_f32_16x16x32_bf16 v[90:93], v[168:171], v[218:221], v[90:93]
	v_mfma_f32_16x16x32_bf16 v[90:93], v[154:157], v[214:217], v[90:93]
	v_mfma_f32_16x16x32_bf16 v[106:109], v[154:157], v[206:209], v[106:109]
	v_mfma_f32_16x16x32_bf16 v[106:109], v[168:171], v[210:213], v[106:109]
	v_mfma_f32_16x16x32_bf16 v[122:125], v[168:171], v[202:205], v[122:125]
	v_mfma_f32_16x16x32_bf16 v[122:125], v[154:157], v[198:201], v[122:125]
	v_mfma_f32_16x16x32_bf16 v[118:121], v[172:175], v[198:201], v[118:121]
	v_mfma_f32_16x16x32_bf16 v[118:121], v[180:183], v[202:205], v[118:121]
	v_mfma_f32_16x16x32_bf16 v[102:105], v[180:183], v[210:213], v[102:105]
	v_mfma_f32_16x16x32_bf16 v[102:105], v[172:175], v[206:209], v[102:105]
	v_mfma_f32_16x16x32_bf16 v[86:89], v[172:175], v[214:217], v[86:89]
	v_mfma_f32_16x16x32_bf16 v[86:89], v[180:183], v[218:221], v[86:89]
	v_mfma_f32_16x16x32_bf16 v[70:73], v[180:183], v[226:229], v[70:73]
	v_mfma_f32_16x16x32_bf16 v[70:73], v[172:175], v[222:225], v[70:73]
	v_mfma_f32_16x16x32_bf16 v[66:69], v[184:187], v[222:225], v[66:69]
	v_mfma_f32_16x16x32_bf16 v[66:69], v[188:191], v[226:229], v[66:69]
	v_mfma_f32_16x16x32_bf16 v[82:85], v[188:191], v[218:221], v[82:85]
	v_mfma_f32_16x16x32_bf16 v[82:85], v[184:187], v[214:217], v[82:85]
	v_mfma_f32_16x16x32_bf16 v[98:101], v[184:187], v[206:209], v[98:101]
	v_mfma_f32_16x16x32_bf16 v[98:101], v[188:191], v[210:213], v[98:101]
	v_mfma_f32_16x16x32_bf16 v[114:117], v[188:191], v[202:205], v[114:117]
	v_mfma_f32_16x16x32_bf16 v[114:117], v[184:187], v[198:201], v[114:117]
	s_barrier
	s_add_i32 s59, s81, s3
	s_mov_b32 m0, s59
	ds_read_b128 v[198:201], v164 offset:16384
	ds_read_b128 v[202:205], v164 offset:17408
	ds_read_b128 v[206:209], v164 offset:18432
	ds_read_b128 v[210:213], v164 offset:19456
	ds_read_b128 v[214:217], v164 offset:20480
	ds_read_b128 v[218:221], v164 offset:21504
	ds_read_b128 v[222:225], v164 offset:22528
	ds_read_b128 v[226:229], v164 offset:23552
	global_load_lds_dwordx4 v132, s[76:77]
	s_add_i32 m0, s59, 0x2000
	s_add_u32 s62, s76, 0x4000
	s_addc_u32 s63, s77, 0
	s_add_i32 s59, s82, s3
	global_load_lds_dwordx4 v136, s[76:77]
	s_mov_b32 m0, s59
	s_nop 0
	global_load_lds_dwordx4 v132, s[62:63]
	s_add_i32 m0, s59, 0x2000
	s_nop 0
	global_load_lds_dwordx4 v136, s[62:63]
	s_waitcnt vmcnt(6)
	s_waitcnt lgkmcnt(0)
	s_barrier
	s_waitcnt lgkmcnt(0)
	v_mfma_f32_16x16x32_bf16 v[62:65], v[146:149], v[198:201], v[62:65]
	v_mfma_f32_16x16x32_bf16 v[62:65], v[150:153], v[202:205], v[62:65]
	v_mfma_f32_16x16x32_bf16 v[46:49], v[150:153], v[210:213], v[46:49]
	v_mfma_f32_16x16x32_bf16 v[46:49], v[146:149], v[206:209], v[46:49]
	v_mfma_f32_16x16x32_bf16 v[30:33], v[146:149], v[214:217], v[30:33]
	v_mfma_f32_16x16x32_bf16 v[30:33], v[150:153], v[218:221], v[30:33]
	v_mfma_f32_16x16x32_bf16 v[14:17], v[150:153], v[226:229], v[14:17]
	v_mfma_f32_16x16x32_bf16 v[14:17], v[146:149], v[222:225], v[14:17]
	v_mfma_f32_16x16x32_bf16 v[10:13], v[154:157], v[222:225], v[10:13]
	v_mfma_f32_16x16x32_bf16 v[10:13], v[168:171], v[226:229], v[10:13]
	v_mfma_f32_16x16x32_bf16 v[26:29], v[168:171], v[218:221], v[26:29]
	v_mfma_f32_16x16x32_bf16 v[26:29], v[154:157], v[214:217], v[26:29]
	v_mfma_f32_16x16x32_bf16 v[42:45], v[154:157], v[206:209], v[42:45]
	v_mfma_f32_16x16x32_bf16 v[42:45], v[168:171], v[210:213], v[42:45]
	v_mfma_f32_16x16x32_bf16 v[58:61], v[168:171], v[202:205], v[58:61]
	v_mfma_f32_16x16x32_bf16 v[58:61], v[154:157], v[198:201], v[58:61]
	v_mfma_f32_16x16x32_bf16 v[54:57], v[172:175], v[198:201], v[54:57]
	v_mfma_f32_16x16x32_bf16 v[54:57], v[180:183], v[202:205], v[54:57]
	v_mfma_f32_16x16x32_bf16 v[38:41], v[180:183], v[210:213], v[38:41]
	v_mfma_f32_16x16x32_bf16 v[38:41], v[172:175], v[206:209], v[38:41]
	v_mfma_f32_16x16x32_bf16 v[22:25], v[172:175], v[214:217], v[22:25]
	v_mfma_f32_16x16x32_bf16 v[22:25], v[180:183], v[218:221], v[22:25]
	v_mfma_f32_16x16x32_bf16 v[6:9], v[180:183], v[226:229], v[6:9]
	v_mfma_f32_16x16x32_bf16 v[6:9], v[172:175], v[222:225], v[6:9]
	v_mfma_f32_16x16x32_bf16 v[2:5], v[184:187], v[222:225], v[2:5]
	v_mfma_f32_16x16x32_bf16 v[2:5], v[188:191], v[226:229], v[2:5]
	v_mfma_f32_16x16x32_bf16 v[18:21], v[188:191], v[218:221], v[18:21]
	v_mfma_f32_16x16x32_bf16 v[18:21], v[184:187], v[214:217], v[18:21]
	v_mfma_f32_16x16x32_bf16 v[34:37], v[184:187], v[206:209], v[34:37]
	v_mfma_f32_16x16x32_bf16 v[34:37], v[188:191], v[210:213], v[34:37]
	v_mfma_f32_16x16x32_bf16 v[50:53], v[188:191], v[202:205], v[50:53]
	v_mfma_f32_16x16x32_bf16 v[50:53], v[184:187], v[198:201], v[50:53]
	s_barrier
; #define PG8_STAGE(bufoff, gbase, voff) do { _Pragma("unroll") for (int _i = 0; _i < 2; ++_i) \
;         __builtin_amdgcn_global_load_lds((const unsigned*)((const char*)(gbase) + (voff)[_i]), (PG8_LAS unsigned*)(lds + (bufoff) + ldsw + _i * 8192), 16, 0, 0); } while (0)
; #define PG8_LDA(dst, b, h) do { _Pragma("unroll") for (int m = 0; m < 4; ++m) _Pragma("unroll") for (int k = 0; k < 2; ++k) dst[m][k] = *(const PG8_LAS bf16x8*)(lds + PG8_SA(b, h) + aoff + m * 2048 + k * 1024); } while (0)
; #define PG8_LDB(dst, b, h) do { _Pragma("unroll") for (int n = 0; n < 2; ++n) _Pragma("unroll") for (int k = 0; k < 2; ++k) dst[n][k] = *(const PG8_LAS bf16x8*)(lds + PG8_SB(b, h) + boff + n * 2048 + k * 1024); } while (0)
; #define PG8_MMA(ai, bj, At, Bt) do { __builtin_amdgcn_s_setprio(1); _Pragma("unroll") for (int m = 0; m < 4; ++m) _Pragma("unroll") for (int n = 0; n < 2; ++n) _Pragma("unroll") for (int k = 0; k < 2; ++k) \
;         acc[ai][bj][m][n] = __builtin_amdgcn_mfma_f32_16x16x32_bf16(Bt[n][k], At[m][k], acc[ai][bj][m][n], 0, 0, 0); __builtin_amdgcn_s_setprio(0); } while (0)
; #define PG8_WAIT_V(n) asm volatile("s_waitcnt vmcnt(" #n ")" ::: "memory")
; #define PG8_WAIT_L(n) asm volatile("s_waitcnt lgkmcnt(" #n ")" ::: "memory")
; #define PG8_BAR __builtin_amdgcn_s_barrier()
; #define PG8_SCHED __builtin_amdgcn_sched_barrier(0)
; template <class Epi, class Sched, bool ALIGN_EPI = false, bool SP2 = false>
; __device__ __forceinline__ void gemm_phase(PG8_LAS unsigned char* lds, const Gemm g, const Sched& S, const Epi& E) {
;     ...
;             PG8_LDB(B0, 1, 0); PG8_LDB(B1, 1, 1); PG8_SCHED; PG8_LDA(At, 1, 0); PG8_STAGE(PG8_SA(0, 1), a2 + hstep, voffA);
;             PG8_WAIT_V(8); PG8_WAIT_L(0); PG8_BAR; PG8_MMA(0, 0, At, B0); PG8_MMA(0, 1, At, B1); PG8_BAR; PG8_SCHED;
	s_add_i32 s59, 0, 0x18000
	v_add_u32_e32 v158, s59, v160
	s_add_i32 s64, 0, 0x1c000
	ds_read_b128 v[146:149], v158
	ds_read_b128 v[150:153], v158 offset:1024
	ds_read_b128 v[154:157], v158 offset:2048
	ds_read_b128 v[168:171], v158 offset:3072
	v_add_u32_e32 v158, s64, v160
	ds_read_b128 v[172:175], v158
	ds_read_b128 v[180:183], v158 offset:1024
	ds_read_b128 v[184:187], v158 offset:2048
	ds_read_b128 v[188:191], v158 offset:3072
	ds_read_b128 v[198:201], v164 offset:32768
	ds_read_b128 v[202:205], v164 offset:33792
	ds_read_b128 v[206:209], v164 offset:34816
	ds_read_b128 v[210:213], v164 offset:35840
	ds_read_b128 v[214:217], v164 offset:36864
	ds_read_b128 v[218:221], v164 offset:37888
	ds_read_b128 v[222:225], v164 offset:38912
	ds_read_b128 v[226:229], v164 offset:39936
	s_mov_b32 m0, s15
	s_nop 0
	global_load_lds_dwordx4 v130, s[78:79]
	s_mov_b32 m0, s27
	s_nop 0
	global_load_lds_dwordx4 v134, s[78:79]
	s_add_u32 s62, s78, 0x4000
	s_addc_u32 s63, s79, 0
	s_mov_b32 m0, s28
	s_nop 0
	global_load_lds_dwordx4 v130, s[62:63]
	s_mov_b32 m0, s29
	s_nop 0
	global_load_lds_dwordx4 v134, s[62:63]
	s_waitcnt vmcnt(8)
	s_waitcnt lgkmcnt(0)
	s_barrier
	s_waitcnt lgkmcnt(0)
	v_mfma_f32_16x16x32_bf16 v[126:129], v[146:149], v[198:201], v[126:129]
	v_mfma_f32_16x16x32_bf16 v[126:129], v[150:153], v[202:205], v[126:129]
	v_mfma_f32_16x16x32_bf16 v[110:113], v[150:153], v[210:213], v[110:113]
	v_mfma_f32_16x16x32_bf16 v[110:113], v[146:149], v[206:209], v[110:113]
	v_mfma_f32_16x16x32_bf16 v[94:97], v[146:149], v[214:217], v[94:97]
	v_mfma_f32_16x16x32_bf16 v[94:97], v[150:153], v[218:221], v[94:97]
	v_mfma_f32_16x16x32_bf16 v[78:81], v[150:153], v[226:229], v[78:81]
	v_mfma_f32_16x16x32_bf16 v[78:81], v[146:149], v[222:225], v[78:81]
	v_mfma_f32_16x16x32_bf16 v[74:77], v[154:157], v[222:225], v[74:77]
	v_mfma_f32_16x16x32_bf16 v[74:77], v[168:171], v[226:229], v[74:77]
	v_mfma_f32_16x16x32_bf16 v[90:93], v[168:171], v[218:221], v[90:93]
	v_mfma_f32_16x16x32_bf16 v[90:93], v[154:157], v[214:217], v[90:93]
	v_mfma_f32_16x16x32_bf16 v[106:109], v[154:157], v[206:209], v[106:109]
	v_mfma_f32_16x16x32_bf16 v[106:109], v[168:171], v[210:213], v[106:109]
	v_mfma_f32_16x16x32_bf16 v[122:125], v[168:171], v[202:205], v[122:125]
	v_mfma_f32_16x16x32_bf16 v[122:125], v[154:157], v[198:201], v[122:125]
	v_mfma_f32_16x16x32_bf16 v[118:121], v[172:175], v[198:201], v[118:121]
	v_mfma_f32_16x16x32_bf16 v[118:121], v[180:183], v[202:205], v[118:121]
	v_mfma_f32_16x16x32_bf16 v[102:105], v[180:183], v[210:213], v[102:105]
	v_mfma_f32_16x16x32_bf16 v[102:105], v[172:175], v[206:209], v[102:105]
	v_mfma_f32_16x16x32_bf16 v[86:89], v[172:175], v[214:217], v[86:89]
	v_mfma_f32_16x16x32_bf16 v[86:89], v[180:183], v[218:221], v[86:89]
	v_mfma_f32_16x16x32_bf16 v[70:73], v[180:183], v[226:229], v[70:73]
	v_mfma_f32_16x16x32_bf16 v[70:73], v[172:175], v[222:225], v[70:73]
	v_mfma_f32_16x16x32_bf16 v[66:69], v[184:187], v[222:225], v[66:69]
	v_mfma_f32_16x16x32_bf16 v[66:69], v[188:191], v[226:229], v[66:69]
	v_mfma_f32_16x16x32_bf16 v[82:85], v[188:191], v[218:221], v[82:85]
	v_mfma_f32_16x16x32_bf16 v[82:85], v[184:187], v[214:217], v[82:85]
	v_mfma_f32_16x16x32_bf16 v[98:101], v[184:187], v[206:209], v[98:101]
	v_mfma_f32_16x16x32_bf16 v[98:101], v[188:191], v[210:213], v[98:101]
	v_mfma_f32_16x16x32_bf16 v[114:117], v[188:191], v[202:205], v[114:117]
	v_mfma_f32_16x16x32_bf16 v[114:117], v[184:187], v[198:201], v[114:117]
	s_barrier
; #define PG8_STAGE(bufoff, gbase, voff) do { _Pragma("unroll") for (int _i = 0; _i < 2; ++_i) \
;         __builtin_amdgcn_global_load_lds((const unsigned*)((const char*)(gbase) + (voff)[_i]), (PG8_LAS unsigned*)(lds + (bufoff) + ldsw + _i * 8192), 16, 0, 0); } while (0)
; #define PG8_LDA(dst, b, h) do { _Pragma("unroll") for (int m = 0; m < 4; ++m) _Pragma("unroll") for (int k = 0; k < 2; ++k) dst[m][k] = *(const PG8_LAS bf16x8*)(lds + PG8_SA(b, h) + aoff + m * 2048 + k * 1024); } while (0)
; #define PG8_LDB(dst, b, h) do { _Pragma("unroll") for (int n = 0; n < 2; ++n) _Pragma("unroll") for (int k = 0; k < 2; ++k) dst[n][k] = *(const PG8_LAS bf16x8*)(lds + PG8_SB(b, h) + boff + n * 2048 + k * 1024); } while (0)
; template <class Epi, class Sched, bool ALIGN_EPI = false, bool SP2 = false>
; __device__ __forceinline__ void gemm_phase(PG8_LAS unsigned char* lds, const Gemm g, const Sched& S, const Epi& E) {
;     ...
;         for (; t < tend; t += 2) {
;             const bool last = (t == nt - 2);
;             const char* a1 = cA + (size_t)(t + 1) * kstep;
;             const char* a2 = last ? nA : cA + (size_t)(t + 2) * kstep; const char* b2 = last ? nB : cB + (size_t)(t + 2) * kstep;
;             const char* a3 = a2 + kstep; const char* b3 = b2 + kstep;
;             if (last && has_next) S.a_ready(nxt);
;             if constexpr (SP2) {
;             PG8_LDB(B0, 0, 0); PG8_LDB(B1, 0, 1); PG8_SCHED; PG8_LDA(At, 0, 0); PG8_STAGE(PG8_SA(1, 1), a1 + hstep, voffA);
;             PG8_WAIT_V(8); PG8_WAIT_L(0); PG8_BAR; PG8_MMA(0, 0, At, B0); PG8_MMA(0, 1, At, B1); PG8_BAR; PG8_SCHED;
;             PG8_LDA(At, 0, 1); PG8_STAGE(PG8_SB(0, 0), b2, voffB); PG8_STAGE(PG8_SB(0, 1), b2 + hstep, voffB); PG8_STAGE(PG8_SA(0, 0), a2, voffA);
;             PG8_WAIT_V(8); PG8_WAIT_L(0); PG8_BAR; PG8_MMA(1, 0, At, B0); PG8_MMA(1, 1, At, B1); PG8_BAR; PG8_SCHED;
;             PG8_LDB(B0, 1, 0); PG8_LDB(B1, 1, 1); PG8_SCHED; PG8_LDA(At, 1, 0); PG8_STAGE(PG8_SA(0, 1), a2 + hstep, voffA);
;             PG8_WAIT_V(8); PG8_WAIT_L(0); PG8_BAR; PG8_MMA(0, 0, At, B0); PG8_MMA(0, 1, At, B1); PG8_BAR; PG8_SCHED;
;             PG8_LDA(At, 1, 1); PG8_STAGE(PG8_SB(1, 0), b3, voffB); PG8_STAGE(PG8_SB(1, 1), b3 + hstep, voffB); PG8_STAGE(PG8_SA(1, 0), a3, voffA);
;             PG8_WAIT_V(8); PG8_WAIT_L(0); PG8_BAR; PG8_MMA(1, 0, At, B0); PG8_MMA(1, 1, At, B1); PG8_BAR; PG8_SCHED;
	s_add_u32 s62, s76, 0x8000
	s_addc_u32 s63, s77, 0
	s_add_i32 s59, s59, s3
	s_mov_b32 m0, s59
	ds_read_b128 v[198:201], v164 offset:49152
	ds_read_b128 v[202:205], v164 offset:50176
	ds_read_b128 v[206:209], v164 offset:51200
	ds_read_b128 v[210:213], v164 offset:52224
	ds_read_b128 v[214:217], v164 offset:53248
	ds_read_b128 v[218:221], v164 offset:54272
	ds_read_b128 v[222:225], v164 offset:55296
	ds_read_b128 v[226:229], v164 offset:56320
	global_load_lds_dwordx4 v132, s[62:63]
	s_add_i32 m0, s59, 0x2000
	v_lshl_add_u64 v[158:159], s[62:63], 0, v[136:137]
	s_add_u32 s62, s76, 0xc000
	s_addc_u32 s63, s77, 0
	s_add_i32 s59, s64, s3
	global_load_lds_dwordx4 v[158:159], off
	s_mov_b32 m0, s59
	s_nop 0
	global_load_lds_dwordx4 v132, s[62:63]
	s_add_i32 m0, s59, 0x2000
	s_nop 0
	global_load_lds_dwordx4 v136, s[62:63]
	s_add_i32 s58, s58, 2
	s_add_u32 s72, s72, 0x10000
	s_addc_u32 s73, s73, 0
	s_add_u32 s33, s33, 0x10000
	s_addc_u32 s56, s56, 0
	s_add_u32 s59, s72, 0x4000
	s_addc_u32 s62, s73, 0
	s_cmp_eq_u32 s58, 60
	s_cselect_b32 s78, s19, s59
	s_cselect_b32 s79, s5, s62
	s_cselect_b32 s76, s26, s33
	s_cselect_b32 s77, s17, s56
	s_add_u32 s74, s78, 0x8000
	s_addc_u32 s75, s79, 0
	s_sub_u32 s74, s72, 0x4000
	s_subb_u32 s75, s73, 0
	s_cmp_gt_u32 s58, 61
	s_waitcnt vmcnt(6)
	s_waitcnt lgkmcnt(0)
	s_barrier
	s_waitcnt lgkmcnt(0)
	v_mfma_f32_16x16x32_bf16 v[62:65], v[146:149], v[198:201], v[62:65]
	v_mfma_f32_16x16x32_bf16 v[62:65], v[150:153], v[202:205], v[62:65]
	v_mfma_f32_16x16x32_bf16 v[46:49], v[150:153], v[210:213], v[46:49]
	v_mfma_f32_16x16x32_bf16 v[46:49], v[146:149], v[206:209], v[46:49]
	v_mfma_f32_16x16x32_bf16 v[30:33], v[146:149], v[214:217], v[30:33]
	v_mfma_f32_16x16x32_bf16 v[30:33], v[150:153], v[218:221], v[30:33]
	v_mfma_f32_16x16x32_bf16 v[14:17], v[150:153], v[226:229], v[14:17]
	v_mfma_f32_16x16x32_bf16 v[14:17], v[146:149], v[222:225], v[14:17]
	v_mfma_f32_16x16x32_bf16 v[10:13], v[154:157], v[222:225], v[10:13]
	v_mfma_f32_16x16x32_bf16 v[10:13], v[168:171], v[226:229], v[10:13]
	v_mfma_f32_16x16x32_bf16 v[26:29], v[168:171], v[218:221], v[26:29]
	v_mfma_f32_16x16x32_bf16 v[26:29], v[154:157], v[214:217], v[26:29]
	v_mfma_f32_16x16x32_bf16 v[42:45], v[154:157], v[206:209], v[42:45]
	v_mfma_f32_16x16x32_bf16 v[42:45], v[168:171], v[210:213], v[42:45]
	v_mfma_f32_16x16x32_bf16 v[58:61], v[168:171], v[202:205], v[58:61]
	v_mfma_f32_16x16x32_bf16 v[58:61], v[154:157], v[198:201], v[58:61]
	v_mfma_f32_16x16x32_bf16 v[54:57], v[172:175], v[198:201], v[54:57]
	v_mfma_f32_16x16x32_bf16 v[54:57], v[180:183], v[202:205], v[54:57]
	v_mfma_f32_16x16x32_bf16 v[38:41], v[180:183], v[210:213], v[38:41]
	v_mfma_f32_16x16x32_bf16 v[38:41], v[172:175], v[206:209], v[38:41]
	v_mfma_f32_16x16x32_bf16 v[22:25], v[172:175], v[214:217], v[22:25]
	v_mfma_f32_16x16x32_bf16 v[22:25], v[180:183], v[218:221], v[22:25]
	v_mfma_f32_16x16x32_bf16 v[6:9], v[180:183], v[226:229], v[6:9]
	v_mfma_f32_16x16x32_bf16 v[6:9], v[172:175], v[222:225], v[6:9]
	v_mfma_f32_16x16x32_bf16 v[2:5], v[184:187], v[222:225], v[2:5]
	v_mfma_f32_16x16x32_bf16 v[2:5], v[188:191], v[226:229], v[2:5]
	v_mfma_f32_16x16x32_bf16 v[18:21], v[188:191], v[218:221], v[18:21]
	v_mfma_f32_16x16x32_bf16 v[18:21], v[184:187], v[214:217], v[18:21]
	v_mfma_f32_16x16x32_bf16 v[34:37], v[184:187], v[206:209], v[34:37]
	v_mfma_f32_16x16x32_bf16 v[34:37], v[188:191], v[210:213], v[34:37]
	v_mfma_f32_16x16x32_bf16 v[50:53], v[188:191], v[202:205], v[50:53]
	v_mfma_f32_16x16x32_bf16 v[50:53], v[184:187], v[198:201], v[50:53]
	s_barrier
	s_cbranch_scc0 .LBB0_290
	s_and_b64 vcc, exec, s[12:13]
	s_cbranch_vccz .LBB0_293
	s_barrier

;     __device__ __forceinline__ bool next(int i, Unit& u) const { if (i >= 2) return false; const int xcd = c & 7, off = c >> 3; u.pm = 16 * i + 4 * (xcd >> 1) + (off & 3); u.pn = 8 * (xcd & 1) + (off >> 2); return true; }
; #define PG8_STAGE(bufoff, gbase, voff) do { _Pragma("unroll") for (int _i = 0; _i < 2; ++_i) \
;         __builtin_amdgcn_global_load_lds((const unsigned*)((const char*)(gbase) + (voff)[_i]), (PG8_LAS unsigned*)(lds + (bufoff) + ldsw + _i * 8192), 16, 0, 0); } while (0)
; #define PG8_LDA(dst, b, h) do { _Pragma("unroll") for (int m = 0; m < 4; ++m) _Pragma("unroll") for (int k = 0; k < 2; ++k) dst[m][k] = *(const PG8_LAS bf16x8*)(lds + PG8_SA(b, h) + aoff + m * 2048 + k * 1024); } while (0)
; #define PG8_WAIT_V(n) asm volatile("s_waitcnt vmcnt(" #n ")" ::: "memory")
; #define PG8_BAR __builtin_amdgcn_s_barrier()
; template <class Epi, class Sched, bool ALIGN_EPI = false, bool SP2 = false>
; __device__ __forceinline__ void gemm_phase(PG8_LAS unsigned char* lds, const Gemm g, const Sched& S, const Epi& E) {
;     ...
;         const bool has_next = S.next(ui + 1, nxt);
;         const char* nA = has_next ? (const char*)g.A + (size_t)nxt.pm * tstep : cA; const char* nB = has_next ? (const char*)g.Bt + (size_t)nxt.pn * tstep : cB;
;         constexpr int NSEG = Epi::HAS_MID ? 2 : 1; int t = 0;
; #pragma unroll
;         for (int seg = 0; seg < NSEG; ++seg) { const int tend = (seg + 1 < NSEG) ? (nt >> 1) : nt;
;         for (; t < tend; t += 2) {
;             const bool last = (t == nt - 2);
;             const char* a1 = cA + (size_t)(t + 1) * kstep;
;             const char* a2 = last ? nA : cA + (size_t)(t + 2) * kstep; const char* b2 = last ? nB : cB + (size_t)(t + 2) * kstep;
;             const char* a3 = a2 + kstep; const char* b3 = b2 + kstep;
;             if (last && has_next) S.a_ready(nxt);
;             if constexpr (SP2) {
;             PG8_LDB(B0, 0, 0); PG8_LDB(B1, 0, 1); PG8_SCHED; PG8_LDA(At, 0, 0); PG8_STAGE(PG8_SA(1, 1), a1 + hstep, voffA);
;             PG8_WAIT_V(8); PG8_WAIT_L(0); PG8_BAR; PG8_MMA(0, 0, At, B0); PG8_MMA(0, 1, At, B1); PG8_BAR; PG8_SCHED;
;             PG8_LDA(At, 0, 1); PG8_STAGE(PG8_SB(0, 0), b2, voffB); PG8_STAGE(PG8_SB(0, 1), b2 + hstep, voffB); PG8_STAGE(PG8_SA(0, 0), a2, voffA);
;             PG8_WAIT_V(8); PG8_WAIT_L(0); PG8_BAR; PG8_MMA(1, 0, At, B0); PG8_MMA(1, 1, At, B1); PG8_BAR; PG8_SCHED;
.LBB0_756:
	s_ashr_i32 s17, s16, 31
	s_lshl_b64 s[22:23], s[16:17], 21
	s_add_u32 s22, s66, s22
	s_addc_u32 s23, s67, s23
	s_and_b64 s[36:37], s[4:5], exec
	s_cselect_b32 s17, s23, s45
	s_cselect_b32 s39, s22, s44
	s_ashr_i32 s15, s14, 31
	s_lshl_b64 s[36:37], s[14:15], 21
	v_readlane_b32 s48, v255, 17
	v_readlane_b32 s49, v255, 18
	s_add_u32 s36, s48, s36
	s_addc_u32 s37, s49, s37
	s_and_b64 s[48:49], s[4:5], exec
	s_cselect_b32 s15, s37, s47
	s_cselect_b32 s41, s36, s46
	s_add_u32 s44, s44, 0xc000
	s_addc_u32 s45, s45, 0
	s_add_u32 s68, s46, 0x10000
	s_addc_u32 s69, s47, 0
	s_mov_b32 s70, -2
	s_waitcnt lgkmcnt(0)
	s_nop 3
	s_add_u32 s46, s44, 0x4000
	s_addc_u32 s47, s45, 0
	s_cmp_eq_u32 s70, 60
	s_cselect_b32 s50, s39, s46
	s_cselect_b32 s51, s17, s47
	s_cselect_b32 s48, s41, s68
	s_cselect_b32 s49, s15, s69
	s_add_u32 s46, s50, 0x8000
	s_addc_u32 s47, s51, 0
	s_sub_u32 s46, s44, 0x4000
	s_subb_u32 s47, s45, 0
	ds_read_b128 v[154:157], v149
	ds_read_b128 v[158:161], v149 offset:1024
	ds_read_b128 v[162:165], v149 offset:2048
	ds_read_b128 v[166:169], v149 offset:3072
	ds_read_b128 v[170:173], v150
	ds_read_b128 v[174:177], v150 offset:1024
	ds_read_b128 v[180:183], v150 offset:2048
	ds_read_b128 v[184:187], v150 offset:3072
	ds_read_b128 v[188:191], v151
	ds_read_b128 v[198:201], v151 offset:1024
	ds_read_b128 v[202:205], v151 offset:2048
	ds_read_b128 v[206:209], v151 offset:3072
	ds_read_b128 v[210:213], v151 offset:4096
	ds_read_b128 v[214:217], v151 offset:5120
	ds_read_b128 v[218:221], v151 offset:6144
	ds_read_b128 v[222:225], v151 offset:7168
	s_mov_b32 m0, s57
	s_nop 0
	global_load_lds_dwordx4 v130, s[46:47]
	s_mov_b32 m0, s58
	s_nop 0
	global_load_lds_dwordx4 v134, s[46:47]
	s_add_i32 m0, s26, 0xc000
	s_nop 0
	global_load_lds_dwordx4 v138, s[44:45]
	s_add_i32 m0, s26, 0xe000
	s_nop 0
	global_load_lds_dwordx4 v140, s[44:45]
	s_waitcnt vmcnt(8)
	s_waitcnt lgkmcnt(0)
	s_barrier
	s_waitcnt lgkmcnt(0)
	v_mfma_f32_16x16x32_bf16 v[126:129], v[154:157], v[188:191], 0
	v_mfma_f32_16x16x32_bf16 v[126:129], v[158:161], v[198:201], v[126:129]
	v_mfma_f32_16x16x32_bf16 v[110:113], v[158:161], v[206:209], 0
	v_mfma_f32_16x16x32_bf16 v[110:113], v[154:157], v[202:205], v[110:113]
	v_mfma_f32_16x16x32_bf16 v[94:97], v[154:157], v[210:213], 0
	v_mfma_f32_16x16x32_bf16 v[94:97], v[158:161], v[214:217], v[94:97]
	v_mfma_f32_16x16x32_bf16 v[78:81], v[158:161], v[222:225], 0
	v_mfma_f32_16x16x32_bf16 v[78:81], v[154:157], v[218:221], v[78:81]
	v_mfma_f32_16x16x32_bf16 v[74:77], v[162:165], v[218:221], 0
	v_mfma_f32_16x16x32_bf16 v[74:77], v[166:169], v[222:225], v[74:77]
	v_mfma_f32_16x16x32_bf16 v[90:93], v[166:169], v[214:217], 0
	v_mfma_f32_16x16x32_bf16 v[90:93], v[162:165], v[210:213], v[90:93]
	v_mfma_f32_16x16x32_bf16 v[106:109], v[162:165], v[202:205], 0
	v_mfma_f32_16x16x32_bf16 v[106:109], v[166:169], v[206:209], v[106:109]
	v_mfma_f32_16x16x32_bf16 v[122:125], v[166:169], v[198:201], 0
	v_mfma_f32_16x16x32_bf16 v[122:125], v[162:165], v[188:191], v[122:125]
	v_mfma_f32_16x16x32_bf16 v[118:121], v[170:173], v[188:191], 0
	v_mfma_f32_16x16x32_bf16 v[118:121], v[174:177], v[198:201], v[118:121]
	v_mfma_f32_16x16x32_bf16 v[102:105], v[174:177], v[206:209], 0
	v_mfma_f32_16x16x32_bf16 v[102:105], v[170:173], v[202:205], v[102:105]
	v_mfma_f32_16x16x32_bf16 v[86:89], v[170:173], v[210:213], 0
	v_mfma_f32_16x16x32_bf16 v[86:89], v[174:177], v[214:217], v[86:89]
	v_mfma_f32_16x16x32_bf16 v[70:73], v[174:177], v[222:225], 0
	v_mfma_f32_16x16x32_bf16 v[70:73], v[170:173], v[218:221], v[70:73]
	v_mfma_f32_16x16x32_bf16 v[66:69], v[180:183], v[218:221], 0
	v_mfma_f32_16x16x32_bf16 v[66:69], v[184:187], v[222:225], v[66:69]
	v_mfma_f32_16x16x32_bf16 v[82:85], v[184:187], v[214:217], 0
	v_mfma_f32_16x16x32_bf16 v[82:85], v[180:183], v[210:213], v[82:85]
	v_mfma_f32_16x16x32_bf16 v[98:101], v[180:183], v[202:205], 0
	v_mfma_f32_16x16x32_bf16 v[98:101], v[184:187], v[206:209], v[98:101]
	v_mfma_f32_16x16x32_bf16 v[114:117], v[184:187], v[198:201], 0
	v_mfma_f32_16x16x32_bf16 v[114:117], v[180:183], v[188:191], v[114:117]
	s_barrier
	s_add_i32 s71, s59, s3
	s_mov_b32 m0, s71
	ds_read_b128 v[188:191], v151 offset:16384
	ds_read_b128 v[198:201], v151 offset:17408
	ds_read_b128 v[202:205], v151 offset:18432
	ds_read_b128 v[206:209], v151 offset:19456
	ds_read_b128 v[210:213], v151 offset:20480
	ds_read_b128 v[214:217], v151 offset:21504
	ds_read_b128 v[218:221], v151 offset:22528
	ds_read_b128 v[222:225], v151 offset:23552
	global_load_lds_dwordx4 v132, s[48:49]
	s_add_i32 m0, s71, 0x2000
	s_add_u32 s72, s48, 0x4000
	s_addc_u32 s73, s49, 0
	s_add_i32 s71, s61, s3
	global_load_lds_dwordx4 v136, s[48:49]
	s_mov_b32 m0, s71
	s_nop 0
	global_load_lds_dwordx4 v132, s[72:73]
	s_add_i32 m0, s71, 0x2000
	s_nop 0
	global_load_lds_dwordx4 v136, s[72:73]
	s_waitcnt vmcnt(6)
	s_waitcnt lgkmcnt(0)
	s_barrier
; #define PG8_STAGE(bufoff, gbase, voff) do { _Pragma("unroll") for (int _i = 0; _i < 2; ++_i) \
;         __builtin_amdgcn_global_load_lds((const unsigned*)((const char*)(gbase) + (voff)[_i]), (PG8_LAS unsigned*)(lds + (bufoff) + ldsw + _i * 8192), 16, 0, 0); } while (0)
; #define PG8_LDA(dst, b, h) do { _Pragma("unroll") for (int m = 0; m < 4; ++m) _Pragma("unroll") for (int k = 0; k < 2; ++k) dst[m][k] = *(const PG8_LAS bf16x8*)(lds + PG8_SA(b, h) + aoff + m * 2048 + k * 1024); } while (0)
; #define PG8_LDB(dst, b, h) do { _Pragma("unroll") for (int n = 0; n < 2; ++n) _Pragma("unroll") for (int k = 0; k < 2; ++k) dst[n][k] = *(const PG8_LAS bf16x8*)(lds + PG8_SB(b, h) + boff + n * 2048 + k * 1024); } while (0)
; #define PG8_MMA(ai, bj, At, Bt) do { __builtin_amdgcn_s_setprio(1); _Pragma("unroll") for (int m = 0; m < 4; ++m) _Pragma("unroll") for (int n = 0; n < 2; ++n) _Pragma("unroll") for (int k = 0; k < 2; ++k) \
;         acc[ai][bj][m][n] = __builtin_amdgcn_mfma_f32_16x16x32_bf16(Bt[n][k], At[m][k], acc[ai][bj][m][n], 0, 0, 0); __builtin_amdgcn_s_setprio(0); } while (0)
; #define PG8_WAIT_V(n) asm volatile("s_waitcnt vmcnt(" #n ")" ::: "memory")
; #define PG8_WAIT_L(n) asm volatile("s_waitcnt lgkmcnt(" #n ")" ::: "memory")
; #define PG8_BAR __builtin_amdgcn_s_barrier()
; #define PG8_SCHED __builtin_amdgcn_sched_barrier(0)
; template <class Epi, class Sched, bool ALIGN_EPI = false, bool SP2 = false>
; __device__ __forceinline__ void gemm_phase(PG8_LAS unsigned char* lds, const Gemm g, const Sched& S, const Epi& E) {
;     ...
;             PG8_WAIT_V(8); PG8_WAIT_L(0); PG8_BAR; PG8_MMA(1, 0, At, B0); PG8_MMA(1, 1, At, B1); PG8_BAR; PG8_SCHED;
;             PG8_LDB(B0, 1, 0); PG8_LDB(B1, 1, 1); PG8_SCHED; PG8_LDA(At, 1, 0); PG8_STAGE(PG8_SA(0, 1), a2 + hstep, voffA);
;             PG8_WAIT_V(8); PG8_WAIT_L(0); PG8_BAR; PG8_MMA(0, 0, At, B0); PG8_MMA(0, 1, At, B1); PG8_BAR; PG8_SCHED;
	s_waitcnt lgkmcnt(0)
	v_mfma_f32_16x16x32_bf16 v[62:65], v[154:157], v[188:191], 0
	v_mfma_f32_16x16x32_bf16 v[62:65], v[158:161], v[198:201], v[62:65]
	v_mfma_f32_16x16x32_bf16 v[46:49], v[158:161], v[206:209], 0
	v_mfma_f32_16x16x32_bf16 v[46:49], v[154:157], v[202:205], v[46:49]
	v_mfma_f32_16x16x32_bf16 v[30:33], v[154:157], v[210:213], 0
	v_mfma_f32_16x16x32_bf16 v[30:33], v[158:161], v[214:217], v[30:33]
	v_mfma_f32_16x16x32_bf16 v[14:17], v[158:161], v[222:225], 0
	v_mfma_f32_16x16x32_bf16 v[14:17], v[154:157], v[218:221], v[14:17]
	v_mfma_f32_16x16x32_bf16 v[10:13], v[162:165], v[218:221], 0
	v_mfma_f32_16x16x32_bf16 v[10:13], v[166:169], v[222:225], v[10:13]
	v_mfma_f32_16x16x32_bf16 v[26:29], v[166:169], v[214:217], 0
	v_mfma_f32_16x16x32_bf16 v[26:29], v[162:165], v[210:213], v[26:29]
	v_mfma_f32_16x16x32_bf16 v[42:45], v[162:165], v[202:205], 0
	v_mfma_f32_16x16x32_bf16 v[42:45], v[166:169], v[206:209], v[42:45]
	v_mfma_f32_16x16x32_bf16 v[58:61], v[166:169], v[198:201], 0
	v_mfma_f32_16x16x32_bf16 v[58:61], v[162:165], v[188:191], v[58:61]
	v_mfma_f32_16x16x32_bf16 v[54:57], v[170:173], v[188:191], 0
	v_mfma_f32_16x16x32_bf16 v[54:57], v[174:177], v[198:201], v[54:57]
	v_mfma_f32_16x16x32_bf16 v[38:41], v[174:177], v[206:209], 0
	v_mfma_f32_16x16x32_bf16 v[38:41], v[170:173], v[202:205], v[38:41]
	v_mfma_f32_16x16x32_bf16 v[22:25], v[170:173], v[210:213], 0
	v_mfma_f32_16x16x32_bf16 v[22:25], v[174:177], v[214:217], v[22:25]
	v_mfma_f32_16x16x32_bf16 v[6:9], v[174:177], v[222:225], 0
	v_mfma_f32_16x16x32_bf16 v[6:9], v[170:173], v[218:221], v[6:9]
	v_mfma_f32_16x16x32_bf16 v[2:5], v[180:183], v[218:221], 0
	v_mfma_f32_16x16x32_bf16 v[2:5], v[184:187], v[222:225], v[2:5]
	v_mfma_f32_16x16x32_bf16 v[18:21], v[184:187], v[214:217], 0
	v_mfma_f32_16x16x32_bf16 v[18:21], v[180:183], v[210:213], v[18:21]
	v_mfma_f32_16x16x32_bf16 v[34:37], v[180:183], v[202:205], 0
	v_mfma_f32_16x16x32_bf16 v[34:37], v[184:187], v[206:209], v[34:37]
	v_mfma_f32_16x16x32_bf16 v[50:53], v[184:187], v[198:201], 0
	v_mfma_f32_16x16x32_bf16 v[50:53], v[180:183], v[188:191], v[50:53]
	s_barrier
	s_add_i32 s71, 0, 0x18000
	v_add_u32_e32 v146, s71, v1
	s_add_i32 s72, 0, 0x1c000
	ds_read_b128 v[154:157], v146
	ds_read_b128 v[158:161], v146 offset:1024
	ds_read_b128 v[162:165], v146 offset:2048
	ds_read_b128 v[166:169], v146 offset:3072
	v_add_u32_e32 v146, s72, v1
	ds_read_b128 v[170:173], v146
	ds_read_b128 v[174:177], v146 offset:1024
	ds_read_b128 v[180:183], v146 offset:2048
	ds_read_b128 v[184:187], v146 offset:3072
	ds_read_b128 v[188:191], v151 offset:32768
	ds_read_b128 v[198:201], v151 offset:33792
	ds_read_b128 v[202:205], v151 offset:34816
	ds_read_b128 v[206:209], v151 offset:35840
	ds_read_b128 v[210:213], v151 offset:36864
	ds_read_b128 v[214:217], v151 offset:37888
	ds_read_b128 v[218:221], v151 offset:38912
	ds_read_b128 v[222:225], v151 offset:39936
	s_mov_b32 m0, s26
	s_nop 0
	global_load_lds_dwordx4 v130, s[50:51]
	s_mov_b32 m0, s27
	s_nop 0
	global_load_lds_dwordx4 v134, s[50:51]
	s_add_u32 s50, s50, 0x4000
	s_addc_u32 s51, s51, 0
	s_mov_b32 m0, s28
	s_nop 0
	global_load_lds_dwordx4 v130, s[50:51]
	s_mov_b32 m0, s29
	s_nop 0
	global_load_lds_dwordx4 v134, s[50:51]
	s_waitcnt vmcnt(8)
	s_waitcnt lgkmcnt(0)
	s_barrier
	s_waitcnt lgkmcnt(0)
	v_mfma_f32_16x16x32_bf16 v[126:129], v[154:157], v[188:191], v[126:129]
	v_mfma_f32_16x16x32_bf16 v[126:129], v[158:161], v[198:201], v[126:129]
	v_mfma_f32_16x16x32_bf16 v[110:113], v[158:161], v[206:209], v[110:113]
	v_mfma_f32_16x16x32_bf16 v[110:113], v[154:157], v[202:205], v[110:113]
	v_mfma_f32_16x16x32_bf16 v[94:97], v[154:157], v[210:213], v[94:97]
	v_mfma_f32_16x16x32_bf16 v[94:97], v[158:161], v[214:217], v[94:97]
	v_mfma_f32_16x16x32_bf16 v[78:81], v[158:161], v[222:225], v[78:81]
	v_mfma_f32_16x16x32_bf16 v[78:81], v[154:157], v[218:221], v[78:81]
	v_mfma_f32_16x16x32_bf16 v[74:77], v[162:165], v[218:221], v[74:77]
	v_mfma_f32_16x16x32_bf16 v[74:77], v[166:169], v[222:225], v[74:77]
	v_mfma_f32_16x16x32_bf16 v[90:93], v[166:169], v[214:217], v[90:93]
	v_mfma_f32_16x16x32_bf16 v[90:93], v[162:165], v[210:213], v[90:93]
	v_mfma_f32_16x16x32_bf16 v[106:109], v[162:165], v[202:205], v[106:109]
	v_mfma_f32_16x16x32_bf16 v[106:109], v[166:169], v[206:209], v[106:109]
	v_mfma_f32_16x16x32_bf16 v[122:125], v[166:169], v[198:201], v[122:125]
	v_mfma_f32_16x16x32_bf16 v[122:125], v[162:165], v[188:191], v[122:125]
	v_mfma_f32_16x16x32_bf16 v[118:121], v[170:173], v[188:191], v[118:121]
	v_mfma_f32_16x16x32_bf16 v[118:121], v[174:177], v[198:201], v[118:121]
	v_mfma_f32_16x16x32_bf16 v[102:105], v[174:177], v[206:209], v[102:105]
	v_mfma_f32_16x16x32_bf16 v[102:105], v[170:173], v[202:205], v[102:105]
	v_mfma_f32_16x16x32_bf16 v[86:89], v[170:173], v[210:213], v[86:89]
	v_mfma_f32_16x16x32_bf16 v[86:89], v[174:177], v[214:217], v[86:89]
	v_mfma_f32_16x16x32_bf16 v[70:73], v[174:177], v[222:225], v[70:73]
	v_mfma_f32_16x16x32_bf16 v[70:73], v[170:173], v[218:221], v[70:73]
	v_mfma_f32_16x16x32_bf16 v[66:69], v[180:183], v[218:221], v[66:69]
	v_mfma_f32_16x16x32_bf16 v[66:69], v[184:187], v[222:225], v[66:69]
	v_mfma_f32_16x16x32_bf16 v[82:85], v[184:187], v[214:217], v[82:85]
	v_mfma_f32_16x16x32_bf16 v[82:85], v[180:183], v[210:213], v[82:85]
	v_mfma_f32_16x16x32_bf16 v[98:101], v[180:183], v[202:205], v[98:101]
	v_mfma_f32_16x16x32_bf16 v[98:101], v[184:187], v[206:209], v[98:101]
	v_mfma_f32_16x16x32_bf16 v[114:117], v[184:187], v[198:201], v[114:117]
	v_mfma_f32_16x16x32_bf16 v[114:117], v[180:183], v[188:191], v[114:117]
	s_barrier
; #define PG8_STAGE(bufoff, gbase, voff) do { _Pragma("unroll") for (int _i = 0; _i < 2; ++_i) \
;         __builtin_amdgcn_global_load_lds((const unsigned*)((const char*)(gbase) + (voff)[_i]), (PG8_LAS unsigned*)(lds + (bufoff) + ldsw + _i * 8192), 16, 0, 0); } while (0)
; #define PG8_LDA(dst, b, h) do { _Pragma("unroll") for (int m = 0; m < 4; ++m) _Pragma("unroll") for (int k = 0; k < 2; ++k) dst[m][k] = *(const PG8_LAS bf16x8*)(lds + PG8_SA(b, h) + aoff + m * 2048 + k * 1024); } while (0)
; #define PG8_LDB(dst, b, h) do { _Pragma("unroll") for (int n = 0; n < 2; ++n) _Pragma("unroll") for (int k = 0; k < 2; ++k) dst[n][k] = *(const PG8_LAS bf16x8*)(lds + PG8_SB(b, h) + boff + n * 2048 + k * 1024); } while (0)
; #define PG8_MMA(ai, bj, At, Bt) do { __builtin_amdgcn_s_setprio(1); _Pragma("unroll") for (int m = 0; m < 4; ++m) _Pragma("unroll") for (int n = 0; n < 2; ++n) _Pragma("unroll") for (int k = 0; k < 2; ++k) \
;         acc[ai][bj][m][n] = __builtin_amdgcn_mfma_f32_16x16x32_bf16(Bt[n][k], At[m][k], acc[ai][bj][m][n], 0, 0, 0); __builtin_amdgcn_s_setprio(0); } while (0)
; #define PG8_WAIT_V(n) asm volatile("s_waitcnt vmcnt(" #n ")" ::: "memory")
; template <class Epi, class Sched, bool ALIGN_EPI = false, bool SP2 = false>
; __device__ __forceinline__ void gemm_phase(PG8_LAS unsigned char* lds, const Gemm g, const Sched& S, const Epi& E) {
;     ...
;             PG8_LDB(B0, 0, 0); PG8_LDB(B1, 0, 1); PG8_SCHED; PG8_LDA(At, 0, 0); PG8_STAGE(PG8_SA(1, 1), a1 + hstep, voffA);
;             PG8_WAIT_V(8); PG8_WAIT_L(0); PG8_BAR; PG8_MMA(0, 0, At, B0); PG8_MMA(0, 1, At, B1); PG8_BAR; PG8_SCHED;
;             PG8_LDA(At, 0, 1); PG8_STAGE(PG8_SB(0, 0), b2, voffB); PG8_STAGE(PG8_SB(0, 1), b2 + hstep, voffB); PG8_STAGE(PG8_SA(0, 0), a2, voffA);
;             PG8_WAIT_V(8); PG8_WAIT_L(0); PG8_BAR; PG8_MMA(1, 0, At, B0); PG8_MMA(1, 1, At, B1); PG8_BAR; PG8_SCHED;
;             PG8_LDB(B0, 1, 0); PG8_LDB(B1, 1, 1); PG8_SCHED; PG8_LDA(At, 1, 0); PG8_STAGE(PG8_SA(0, 1), a2 + hstep, voffA);
;             PG8_WAIT_V(8); PG8_WAIT_L(0); PG8_BAR; PG8_MMA(0, 0, At, B0); PG8_MMA(0, 1, At, B1); PG8_BAR; PG8_SCHED;
;             PG8_LDA(At, 1, 1); PG8_STAGE(PG8_SB(1, 0), b3, voffB); PG8_STAGE(PG8_SB(1, 1), b3 + hstep, voffB); PG8_STAGE(PG8_SA(1, 0), a3, voffA);
;             PG8_WAIT_V(8); PG8_WAIT_L(0); PG8_BAR; PG8_MMA(1, 0, At, B0); PG8_MMA(1, 1, At, B1); PG8_BAR; PG8_SCHED;
	s_add_u32 s50, s48, 0x8000
	s_addc_u32 s51, s49, 0
	s_add_i32 s71, s71, s3
	s_mov_b32 m0, s71
	ds_read_b128 v[188:191], v151 offset:49152
	ds_read_b128 v[198:201], v151 offset:50176
	ds_read_b128 v[202:205], v151 offset:51200
	ds_read_b128 v[206:209], v151 offset:52224
	ds_read_b128 v[210:213], v151 offset:53248
	ds_read_b128 v[214:217], v151 offset:54272
	ds_read_b128 v[218:221], v151 offset:55296
	ds_read_b128 v[222:225], v151 offset:56320
	global_load_lds_dwordx4 v132, s[50:51]
	s_add_i32 m0, s71, 0x2000
	s_add_u32 s48, s48, 0xc000
	v_lshl_add_u64 v[146:147], s[50:51], 0, v[136:137]
	s_addc_u32 s49, s49, 0
	s_add_i32 s50, s72, s3
	global_load_lds_dwordx4 v[146:147], off
	s_mov_b32 m0, s50
	s_nop 0
	global_load_lds_dwordx4 v132, s[48:49]
	s_add_i32 m0, s50, 0x2000
	s_nop 0
	global_load_lds_dwordx4 v136, s[48:49]
	s_add_i32 s70, s70, 2
	s_add_u32 s44, s44, 0x10000
	s_addc_u32 s45, s45, 0
	s_add_u32 s68, s68, 0x10000
	s_addc_u32 s69, s69, 0
	s_add_u32 s46, s44, 0x4000
	s_addc_u32 s47, s45, 0
	s_cmp_eq_u32 s70, 60
	s_cselect_b32 s50, s39, s46
	s_cselect_b32 s51, s17, s47
	s_cselect_b32 s48, s41, s68
	s_cselect_b32 s49, s15, s69
	s_add_u32 s46, s50, 0x8000
	s_addc_u32 s47, s51, 0
	s_sub_u32 s46, s44, 0x4000
	s_subb_u32 s47, s45, 0
	s_cmp_gt_u32 s70, 61
	s_waitcnt vmcnt(6)
	s_waitcnt lgkmcnt(0)
	s_barrier
	s_waitcnt lgkmcnt(0)
	v_mfma_f32_16x16x32_bf16 v[62:65], v[154:157], v[188:191], v[62:65]
	v_mfma_f32_16x16x32_bf16 v[62:65], v[158:161], v[198:201], v[62:65]
	v_mfma_f32_16x16x32_bf16 v[46:49], v[158:161], v[206:209], v[46:49]
	v_mfma_f32_16x16x32_bf16 v[46:49], v[154:157], v[202:205], v[46:49]
	v_mfma_f32_16x16x32_bf16 v[30:33], v[154:157], v[210:213], v[30:33]
	v_mfma_f32_16x16x32_bf16 v[30:33], v[158:161], v[214:217], v[30:33]
	v_mfma_f32_16x16x32_bf16 v[14:17], v[158:161], v[222:225], v[14:17]
	v_mfma_f32_16x16x32_bf16 v[14:17], v[154:157], v[218:221], v[14:17]
	v_mfma_f32_16x16x32_bf16 v[10:13], v[162:165], v[218:221], v[10:13]
	v_mfma_f32_16x16x32_bf16 v[10:13], v[166:169], v[222:225], v[10:13]
	v_mfma_f32_16x16x32_bf16 v[26:29], v[166:169], v[214:217], v[26:29]
	v_mfma_f32_16x16x32_bf16 v[26:29], v[162:165], v[210:213], v[26:29]
	v_mfma_f32_16x16x32_bf16 v[42:45], v[162:165], v[202:205], v[42:45]
	v_mfma_f32_16x16x32_bf16 v[42:45], v[166:169], v[206:209], v[42:45]
	v_mfma_f32_16x16x32_bf16 v[58:61], v[166:169], v[198:201], v[58:61]
	v_mfma_f32_16x16x32_bf16 v[58:61], v[162:165], v[188:191], v[58:61]
	v_mfma_f32_16x16x32_bf16 v[54:57], v[170:173], v[188:191], v[54:57]
	v_mfma_f32_16x16x32_bf16 v[54:57], v[174:177], v[198:201], v[54:57]
	v_mfma_f32_16x16x32_bf16 v[38:41], v[174:177], v[206:209], v[38:41]
	v_mfma_f32_16x16x32_bf16 v[38:41], v[170:173], v[202:205], v[38:41]
	v_mfma_f32_16x16x32_bf16 v[22:25], v[170:173], v[210:213], v[22:25]
	v_mfma_f32_16x16x32_bf16 v[22:25], v[174:177], v[214:217], v[22:25]
	v_mfma_f32_16x16x32_bf16 v[6:9], v[174:177], v[222:225], v[6:9]
	v_mfma_f32_16x16x32_bf16 v[6:9], v[170:173], v[218:221], v[6:9]
	v_mfma_f32_16x16x32_bf16 v[2:5], v[180:183], v[218:221], v[2:5]
	v_mfma_f32_16x16x32_bf16 v[2:5], v[184:187], v[222:225], v[2:5]
	v_mfma_f32_16x16x32_bf16 v[18:21], v[184:187], v[214:217], v[18:21]
	v_mfma_f32_16x16x32_bf16 v[18:21], v[180:183], v[210:213], v[18:21]
	v_mfma_f32_16x16x32_bf16 v[34:37], v[180:183], v[202:205], v[34:37]
	v_mfma_f32_16x16x32_bf16 v[34:37], v[184:187], v[206:209], v[34:37]
	v_mfma_f32_16x16x32_bf16 v[50:53], v[184:187], v[198:201], v[50:53]
	v_mfma_f32_16x16x32_bf16 v[50:53], v[180:183], v[188:191], v[50:53]
	s_barrier
.LBB0_757:
	ds_read_b128 v[154:157], v149
	ds_read_b128 v[158:161], v149 offset:1024
	ds_read_b128 v[162:165], v149 offset:2048
	ds_read_b128 v[166:169], v149 offset:3072
	ds_read_b128 v[170:173], v150
	ds_read_b128 v[174:177], v150 offset:1024
	ds_read_b128 v[180:183], v150 offset:2048
	ds_read_b128 v[184:187], v150 offset:3072
	ds_read_b128 v[188:191], v151
	ds_read_b128 v[198:201], v151 offset:1024
	ds_read_b128 v[202:205], v151 offset:2048
	ds_read_b128 v[206:209], v151 offset:3072
	ds_read_b128 v[210:213], v151 offset:4096
	ds_read_b128 v[214:217], v151 offset:5120
	ds_read_b128 v[218:221], v151 offset:6144
	ds_read_b128 v[222:225], v151 offset:7168
	s_mov_b32 m0, s57
	s_nop 0
	global_load_lds_dwordx4 v130, s[46:47]
	s_mov_b32 m0, s58
	s_nop 0
	global_load_lds_dwordx4 v134, s[46:47]
	s_add_i32 m0, s26, 0xc000
	s_nop 0
	global_load_lds_dwordx4 v138, s[44:45]
	s_add_i32 m0, s26, 0xe000
	s_nop 0
	global_load_lds_dwordx4 v140, s[44:45]
	s_waitcnt vmcnt(8)
	s_waitcnt lgkmcnt(0)
	s_barrier
; #define PG8_STAGE(bufoff, gbase, voff) do { _Pragma("unroll") for (int _i = 0; _i < 2; ++_i) \
;         __builtin_amdgcn_global_load_lds((const unsigned*)((const char*)(gbase) + (voff)[_i]), (PG8_LAS unsigned*)(lds + (bufoff) + ldsw + _i * 8192), 16, 0, 0); } while (0)
; #define PG8_LDA(dst, b, h) do { _Pragma("unroll") for (int m = 0; m < 4; ++m) _Pragma("unroll") for (int k = 0; k < 2; ++k) dst[m][k] = *(const PG8_LAS bf16x8*)(lds + PG8_SA(b, h) + aoff + m * 2048 + k * 1024); } while (0)
; #define PG8_MMA(ai, bj, At, Bt) do { __builtin_amdgcn_s_setprio(1); _Pragma("unroll") for (int m = 0; m < 4; ++m) _Pragma("unroll") for (int n = 0; n < 2; ++n) _Pragma("unroll") for (int k = 0; k < 2; ++k) \
;         acc[ai][bj][m][n] = __builtin_amdgcn_mfma_f32_16x16x32_bf16(Bt[n][k], At[m][k], acc[ai][bj][m][n], 0, 0, 0); __builtin_amdgcn_s_setprio(0); } while (0)
; #define PG8_WAIT_V(n) asm volatile("s_waitcnt vmcnt(" #n ")" ::: "memory")
; #define PG8_WAIT_L(n) asm volatile("s_waitcnt lgkmcnt(" #n ")" ::: "memory")
; #define PG8_BAR __builtin_amdgcn_s_barrier()
; #define PG8_SCHED __builtin_amdgcn_sched_barrier(0)
; template <class Epi, class Sched, bool ALIGN_EPI = false, bool SP2 = false>
; __device__ __forceinline__ void gemm_phase(PG8_LAS unsigned char* lds, const Gemm g, const Sched& S, const Epi& E) {
;     ...
;             PG8_WAIT_V(8); PG8_WAIT_L(0); PG8_BAR; PG8_MMA(0, 0, At, B0); PG8_MMA(0, 1, At, B1); PG8_BAR; PG8_SCHED;
;             PG8_LDA(At, 0, 1); PG8_STAGE(PG8_SB(0, 0), b2, voffB); PG8_STAGE(PG8_SB(0, 1), b2 + hstep, voffB); PG8_STAGE(PG8_SA(0, 0), a2, voffA);
;             PG8_WAIT_V(8); PG8_WAIT_L(0); PG8_BAR; PG8_MMA(1, 0, At, B0); PG8_MMA(1, 1, At, B1); PG8_BAR; PG8_SCHED;
	s_waitcnt lgkmcnt(0)
	v_mfma_f32_16x16x32_bf16 v[126:129], v[154:157], v[188:191], v[126:129]
	v_mfma_f32_16x16x32_bf16 v[126:129], v[158:161], v[198:201], v[126:129]
	v_mfma_f32_16x16x32_bf16 v[110:113], v[158:161], v[206:209], v[110:113]
	v_mfma_f32_16x16x32_bf16 v[110:113], v[154:157], v[202:205], v[110:113]
	v_mfma_f32_16x16x32_bf16 v[94:97], v[154:157], v[210:213], v[94:97]
	v_mfma_f32_16x16x32_bf16 v[94:97], v[158:161], v[214:217], v[94:97]
	v_mfma_f32_16x16x32_bf16 v[78:81], v[158:161], v[222:225], v[78:81]
	v_mfma_f32_16x16x32_bf16 v[78:81], v[154:157], v[218:221], v[78:81]
	v_mfma_f32_16x16x32_bf16 v[74:77], v[162:165], v[218:221], v[74:77]
	v_mfma_f32_16x16x32_bf16 v[74:77], v[166:169], v[222:225], v[74:77]
	v_mfma_f32_16x16x32_bf16 v[90:93], v[166:169], v[214:217], v[90:93]
	v_mfma_f32_16x16x32_bf16 v[90:93], v[162:165], v[210:213], v[90:93]
	v_mfma_f32_16x16x32_bf16 v[106:109], v[162:165], v[202:205], v[106:109]
	v_mfma_f32_16x16x32_bf16 v[106:109], v[166:169], v[206:209], v[106:109]
	v_mfma_f32_16x16x32_bf16 v[122:125], v[166:169], v[198:201], v[122:125]
	v_mfma_f32_16x16x32_bf16 v[122:125], v[162:165], v[188:191], v[122:125]
	v_mfma_f32_16x16x32_bf16 v[118:121], v[170:173], v[188:191], v[118:121]
	v_mfma_f32_16x16x32_bf16 v[118:121], v[174:177], v[198:201], v[118:121]
	v_mfma_f32_16x16x32_bf16 v[102:105], v[174:177], v[206:209], v[102:105]
	v_mfma_f32_16x16x32_bf16 v[102:105], v[170:173], v[202:205], v[102:105]
	v_mfma_f32_16x16x32_bf16 v[86:89], v[170:173], v[210:213], v[86:89]
	v_mfma_f32_16x16x32_bf16 v[86:89], v[174:177], v[214:217], v[86:89]
	v_mfma_f32_16x16x32_bf16 v[70:73], v[174:177], v[222:225], v[70:73]
	v_mfma_f32_16x16x32_bf16 v[70:73], v[170:173], v[218:221], v[70:73]
	v_mfma_f32_16x16x32_bf16 v[66:69], v[180:183], v[218:221], v[66:69]
	v_mfma_f32_16x16x32_bf16 v[66:69], v[184:187], v[222:225], v[66:69]
	v_mfma_f32_16x16x32_bf16 v[82:85], v[184:187], v[214:217], v[82:85]
	v_mfma_f32_16x16x32_bf16 v[82:85], v[180:183], v[210:213], v[82:85]
	v_mfma_f32_16x16x32_bf16 v[98:101], v[180:183], v[202:205], v[98:101]
	v_mfma_f32_16x16x32_bf16 v[98:101], v[184:187], v[206:209], v[98:101]
	v_mfma_f32_16x16x32_bf16 v[114:117], v[184:187], v[198:201], v[114:117]
	v_mfma_f32_16x16x32_bf16 v[114:117], v[180:183], v[188:191], v[114:117]
	s_barrier
	s_add_i32 s71, s59, s3
	s_mov_b32 m0, s71
	ds_read_b128 v[188:191], v151 offset:16384
	ds_read_b128 v[198:201], v151 offset:17408
	ds_read_b128 v[202:205], v151 offset:18432
	ds_read_b128 v[206:209], v151 offset:19456
	ds_read_b128 v[210:213], v151 offset:20480
	ds_read_b128 v[214:217], v151 offset:21504
	ds_read_b128 v[218:221], v151 offset:22528
	ds_read_b128 v[222:225], v151 offset:23552
	global_load_lds_dwordx4 v132, s[48:49]
	s_add_i32 m0, s71, 0x2000
	s_add_u32 s72, s48, 0x4000
	s_addc_u32 s73, s49, 0
	s_add_i32 s71, s61, s3
	global_load_lds_dwordx4 v136, s[48:49]
	s_mov_b32 m0, s71
	s_nop 0
	global_load_lds_dwordx4 v132, s[72:73]
	s_add_i32 m0, s71, 0x2000
	s_nop 0
	global_load_lds_dwordx4 v136, s[72:73]
	s_waitcnt vmcnt(6)
	s_waitcnt lgkmcnt(0)
	s_barrier
	s_waitcnt lgkmcnt(0)
	v_mfma_f32_16x16x32_bf16 v[62:65], v[154:157], v[188:191], v[62:65]
	v_mfma_f32_16x16x32_bf16 v[62:65], v[158:161], v[198:201], v[62:65]
	v_mfma_f32_16x16x32_bf16 v[46:49], v[158:161], v[206:209], v[46:49]
	v_mfma_f32_16x16x32_bf16 v[46:49], v[154:157], v[202:205], v[46:49]
	v_mfma_f32_16x16x32_bf16 v[30:33], v[154:157], v[210:213], v[30:33]
	v_mfma_f32_16x16x32_bf16 v[30:33], v[158:161], v[214:217], v[30:33]
	v_mfma_f32_16x16x32_bf16 v[14:17], v[158:161], v[222:225], v[14:17]
	v_mfma_f32_16x16x32_bf16 v[14:17], v[154:157], v[218:221], v[14:17]
	v_mfma_f32_16x16x32_bf16 v[10:13], v[162:165], v[218:221], v[10:13]
	v_mfma_f32_16x16x32_bf16 v[10:13], v[166:169], v[222:225], v[10:13]
	v_mfma_f32_16x16x32_bf16 v[26:29], v[166:169], v[214:217], v[26:29]
	v_mfma_f32_16x16x32_bf16 v[26:29], v[162:165], v[210:213], v[26:29]
	v_mfma_f32_16x16x32_bf16 v[42:45], v[162:165], v[202:205], v[42:45]
	v_mfma_f32_16x16x32_bf16 v[42:45], v[166:169], v[206:209], v[42:45]
	v_mfma_f32_16x16x32_bf16 v[58:61], v[166:169], v[198:201], v[58:61]
	v_mfma_f32_16x16x32_bf16 v[58:61], v[162:165], v[188:191], v[58:61]
	v_mfma_f32_16x16x32_bf16 v[54:57], v[170:173], v[188:191], v[54:57]
	v_mfma_f32_16x16x32_bf16 v[54:57], v[174:177], v[198:201], v[54:57]
	v_mfma_f32_16x16x32_bf16 v[38:41], v[174:177], v[206:209], v[38:41]
	v_mfma_f32_16x16x32_bf16 v[38:41], v[170:173], v[202:205], v[38:41]
	v_mfma_f32_16x16x32_bf16 v[22:25], v[170:173], v[210:213], v[22:25]
	v_mfma_f32_16x16x32_bf16 v[22:25], v[174:177], v[214:217], v[22:25]
	v_mfma_f32_16x16x32_bf16 v[6:9], v[174:177], v[222:225], v[6:9]
	v_mfma_f32_16x16x32_bf16 v[6:9], v[170:173], v[218:221], v[6:9]
	v_mfma_f32_16x16x32_bf16 v[2:5], v[180:183], v[218:221], v[2:5]
	v_mfma_f32_16x16x32_bf16 v[2:5], v[184:187], v[222:225], v[2:5]
	v_mfma_f32_16x16x32_bf16 v[18:21], v[184:187], v[214:217], v[18:21]
	v_mfma_f32_16x16x32_bf16 v[18:21], v[180:183], v[210:213], v[18:21]
	v_mfma_f32_16x16x32_bf16 v[34:37], v[180:183], v[202:205], v[34:37]
	v_mfma_f32_16x16x32_bf16 v[34:37], v[184:187], v[206:209], v[34:37]
	v_mfma_f32_16x16x32_bf16 v[50:53], v[184:187], v[198:201], v[50:53]
	v_mfma_f32_16x16x32_bf16 v[50:53], v[180:183], v[188:191], v[50:53]
	s_barrier
; #define PG8_STAGE(bufoff, gbase, voff) do { _Pragma("unroll") for (int _i = 0; _i < 2; ++_i) \
;         __builtin_amdgcn_global_load_lds((const unsigned*)((const char*)(gbase) + (voff)[_i]), (PG8_LAS unsigned*)(lds + (bufoff) + ldsw + _i * 8192), 16, 0, 0); } while (0)
; #define PG8_LDA(dst, b, h) do { _Pragma("unroll") for (int m = 0; m < 4; ++m) _Pragma("unroll") for (int k = 0; k < 2; ++k) dst[m][k] = *(const PG8_LAS bf16x8*)(lds + PG8_SA(b, h) + aoff + m * 2048 + k * 1024); } while (0)
; #define PG8_LDB(dst, b, h) do { _Pragma("unroll") for (int n = 0; n < 2; ++n) _Pragma("unroll") for (int k = 0; k < 2; ++k) dst[n][k] = *(const PG8_LAS bf16x8*)(lds + PG8_SB(b, h) + boff + n * 2048 + k * 1024); } while (0)
; #define PG8_MMA(ai, bj, At, Bt) do { __builtin_amdgcn_s_setprio(1); _Pragma("unroll") for (int m = 0; m < 4; ++m) _Pragma("unroll") for (int n = 0; n < 2; ++n) _Pragma("unroll") for (int k = 0; k < 2; ++k) \
;         acc[ai][bj][m][n] = __builtin_amdgcn_mfma_f32_16x16x32_bf16(Bt[n][k], At[m][k], acc[ai][bj][m][n], 0, 0, 0); __builtin_amdgcn_s_setprio(0); } while (0)
; #define PG8_WAIT_V(n) asm volatile("s_waitcnt vmcnt(" #n ")" ::: "memory")
; #define PG8_WAIT_L(n) asm volatile("s_waitcnt lgkmcnt(" #n ")" ::: "memory")
; #define PG8_BAR __builtin_amdgcn_s_barrier()
; #define PG8_SCHED __builtin_amdgcn_sched_barrier(0)
; template <class Epi, class Sched, bool ALIGN_EPI = false, bool SP2 = false>
; __device__ __forceinline__ void gemm_phase(PG8_LAS unsigned char* lds, const Gemm g, const Sched& S, const Epi& E) {
;     ...
;             PG8_LDB(B0, 1, 0); PG8_LDB(B1, 1, 1); PG8_SCHED; PG8_LDA(At, 1, 0); PG8_STAGE(PG8_SA(0, 1), a2 + hstep, voffA);
;             PG8_WAIT_V(8); PG8_WAIT_L(0); PG8_BAR; PG8_MMA(0, 0, At, B0); PG8_MMA(0, 1, At, B1); PG8_BAR; PG8_SCHED;
	s_add_i32 s71, 0, 0x18000
	v_add_u32_e32 v146, s71, v1
	s_add_i32 s72, 0, 0x1c000
	ds_read_b128 v[154:157], v146
	ds_read_b128 v[158:161], v146 offset:1024
	ds_read_b128 v[162:165], v146 offset:2048
	ds_read_b128 v[166:169], v146 offset:3072
	v_add_u32_e32 v146, s72, v1
	ds_read_b128 v[170:173], v146
	ds_read_b128 v[174:177], v146 offset:1024
	ds_read_b128 v[180:183], v146 offset:2048
	ds_read_b128 v[184:187], v146 offset:3072
	ds_read_b128 v[188:191], v151 offset:32768
	ds_read_b128 v[198:201], v151 offset:33792
	ds_read_b128 v[202:205], v151 offset:34816
	ds_read_b128 v[206:209], v151 offset:35840
	ds_read_b128 v[210:213], v151 offset:36864
	ds_read_b128 v[214:217], v151 offset:37888
	ds_read_b128 v[218:221], v151 offset:38912
	ds_read_b128 v[222:225], v151 offset:39936
	s_mov_b32 m0, s26
	s_nop 0
	global_load_lds_dwordx4 v130, s[50:51]
	s_mov_b32 m0, s27
	s_nop 0
	global_load_lds_dwordx4 v134, s[50:51]
	s_add_u32 s50, s50, 0x4000
	s_addc_u32 s51, s51, 0
	s_mov_b32 m0, s28
	s_nop 0
	global_load_lds_dwordx4 v130, s[50:51]
	s_mov_b32 m0, s29
	s_nop 0
	global_load_lds_dwordx4 v134, s[50:51]
	s_waitcnt vmcnt(8)
	s_waitcnt lgkmcnt(0)
	s_barrier
	s_waitcnt lgkmcnt(0)
	v_mfma_f32_16x16x32_bf16 v[126:129], v[154:157], v[188:191], v[126:129]
	v_mfma_f32_16x16x32_bf16 v[126:129], v[158:161], v[198:201], v[126:129]
	v_mfma_f32_16x16x32_bf16 v[110:113], v[158:161], v[206:209], v[110:113]
	v_mfma_f32_16x16x32_bf16 v[110:113], v[154:157], v[202:205], v[110:113]
	v_mfma_f32_16x16x32_bf16 v[94:97], v[154:157], v[210:213], v[94:97]
	v_mfma_f32_16x16x32_bf16 v[94:97], v[158:161], v[214:217], v[94:97]
	v_mfma_f32_16x16x32_bf16 v[78:81], v[158:161], v[222:225], v[78:81]
	v_mfma_f32_16x16x32_bf16 v[78:81], v[154:157], v[218:221], v[78:81]
	v_mfma_f32_16x16x32_bf16 v[74:77], v[162:165], v[218:221], v[74:77]
	v_mfma_f32_16x16x32_bf16 v[74:77], v[166:169], v[222:225], v[74:77]
	v_mfma_f32_16x16x32_bf16 v[90:93], v[166:169], v[214:217], v[90:93]
	v_mfma_f32_16x16x32_bf16 v[90:93], v[162:165], v[210:213], v[90:93]
	v_mfma_f32_16x16x32_bf16 v[106:109], v[162:165], v[202:205], v[106:109]
	v_mfma_f32_16x16x32_bf16 v[106:109], v[166:169], v[206:209], v[106:109]
	v_mfma_f32_16x16x32_bf16 v[122:125], v[166:169], v[198:201], v[122:125]
	v_mfma_f32_16x16x32_bf16 v[122:125], v[162:165], v[188:191], v[122:125]
	v_mfma_f32_16x16x32_bf16 v[118:121], v[170:173], v[188:191], v[118:121]
	v_mfma_f32_16x16x32_bf16 v[118:121], v[174:177], v[198:201], v[118:121]
	v_mfma_f32_16x16x32_bf16 v[102:105], v[174:177], v[206:209], v[102:105]
	v_mfma_f32_16x16x32_bf16 v[102:105], v[170:173], v[202:205], v[102:105]
	v_mfma_f32_16x16x32_bf16 v[86:89], v[170:173], v[210:213], v[86:89]
	v_mfma_f32_16x16x32_bf16 v[86:89], v[174:177], v[214:217], v[86:89]
	v_mfma_f32_16x16x32_bf16 v[70:73], v[174:177], v[222:225], v[70:73]
	v_mfma_f32_16x16x32_bf16 v[70:73], v[170:173], v[218:221], v[70:73]
	v_mfma_f32_16x16x32_bf16 v[66:69], v[180:183], v[218:221], v[66:69]
	v_mfma_f32_16x16x32_bf16 v[66:69], v[184:187], v[222:225], v[66:69]
	v_mfma_f32_16x16x32_bf16 v[82:85], v[184:187], v[214:217], v[82:85]
	v_mfma_f32_16x16x32_bf16 v[82:85], v[180:183], v[210:213], v[82:85]
	v_mfma_f32_16x16x32_bf16 v[98:101], v[180:183], v[202:205], v[98:101]
	v_mfma_f32_16x16x32_bf16 v[98:101], v[184:187], v[206:209], v[98:101]
	v_mfma_f32_16x16x32_bf16 v[114:117], v[184:187], v[198:201], v[114:117]
	v_mfma_f32_16x16x32_bf16 v[114:117], v[180:183], v[188:191], v[114:117]
	s_barrier
; #define PG8_STAGE(bufoff, gbase, voff) do { _Pragma("unroll") for (int _i = 0; _i < 2; ++_i) \
;         __builtin_amdgcn_global_load_lds((const unsigned*)((const char*)(gbase) + (voff)[_i]), (PG8_LAS unsigned*)(lds + (bufoff) + ldsw + _i * 8192), 16, 0, 0); } while (0)
; #define PG8_LDA(dst, b, h) do { _Pragma("unroll") for (int m = 0; m < 4; ++m) _Pragma("unroll") for (int k = 0; k < 2; ++k) dst[m][k] = *(const PG8_LAS bf16x8*)(lds + PG8_SA(b, h) + aoff + m * 2048 + k * 1024); } while (0)
; #define PG8_LDB(dst, b, h) do { _Pragma("unroll") for (int n = 0; n < 2; ++n) _Pragma("unroll") for (int k = 0; k < 2; ++k) dst[n][k] = *(const PG8_LAS bf16x8*)(lds + PG8_SB(b, h) + boff + n * 2048 + k * 1024); } while (0)
; template <class Epi, class Sched, bool ALIGN_EPI = false, bool SP2 = false>
; __device__ __forceinline__ void gemm_phase(PG8_LAS unsigned char* lds, const Gemm g, const Sched& S, const Epi& E) {
;     ...
;         for (; t < tend; t += 2) {
;             const bool last = (t == nt - 2);
;             const char* a1 = cA + (size_t)(t + 1) * kstep;
;             const char* a2 = last ? nA : cA + (size_t)(t + 2) * kstep; const char* b2 = last ? nB : cB + (size_t)(t + 2) * kstep;
;             const char* a3 = a2 + kstep; const char* b3 = b2 + kstep;
;             if (last && has_next) S.a_ready(nxt);
;             if constexpr (SP2) {
;             PG8_LDB(B0, 0, 0); PG8_LDB(B1, 0, 1); PG8_SCHED; PG8_LDA(At, 0, 0); PG8_STAGE(PG8_SA(1, 1), a1 + hstep, voffA);
;             PG8_WAIT_V(8); PG8_WAIT_L(0); PG8_BAR; PG8_MMA(0, 0, At, B0); PG8_MMA(0, 1, At, B1); PG8_BAR; PG8_SCHED;
;             PG8_LDA(At, 0, 1); PG8_STAGE(PG8_SB(0, 0), b2, voffB); PG8_STAGE(PG8_SB(0, 1), b2 + hstep, voffB); PG8_STAGE(PG8_SA(0, 0), a2, voffA);
;             PG8_WAIT_V(8); PG8_WAIT_L(0); PG8_BAR; PG8_MMA(1, 0, At, B0); PG8_MMA(1, 1, At, B1); PG8_BAR; PG8_SCHED;
;             PG8_LDB(B0, 1, 0); PG8_LDB(B1, 1, 1); PG8_SCHED; PG8_LDA(At, 1, 0); PG8_STAGE(PG8_SA(0, 1), a2 + hstep, voffA);
;             PG8_WAIT_V(8); PG8_WAIT_L(0); PG8_BAR; PG8_MMA(0, 0, At, B0); PG8_MMA(0, 1, At, B1); PG8_BAR; PG8_SCHED;
;             PG8_LDA(At, 1, 1); PG8_STAGE(PG8_SB(1, 0), b3, voffB); PG8_STAGE(PG8_SB(1, 1), b3 + hstep, voffB); PG8_STAGE(PG8_SA(1, 0), a3, voffA);
;             PG8_WAIT_V(8); PG8_WAIT_L(0); PG8_BAR; PG8_MMA(1, 0, At, B0); PG8_MMA(1, 1, At, B1); PG8_BAR; PG8_SCHED;
	s_add_u32 s50, s48, 0x8000
	s_addc_u32 s51, s49, 0
	s_add_i32 s71, s71, s3
	s_mov_b32 m0, s71
	ds_read_b128 v[188:191], v151 offset:49152
	ds_read_b128 v[198:201], v151 offset:50176
	ds_read_b128 v[202:205], v151 offset:51200
	ds_read_b128 v[206:209], v151 offset:52224
	ds_read_b128 v[210:213], v151 offset:53248
	ds_read_b128 v[214:217], v151 offset:54272
	ds_read_b128 v[218:221], v151 offset:55296
	ds_read_b128 v[222:225], v151 offset:56320
	global_load_lds_dwordx4 v132, s[50:51]
	s_add_i32 m0, s71, 0x2000
	s_add_u32 s48, s48, 0xc000
	v_lshl_add_u64 v[146:147], s[50:51], 0, v[136:137]
	s_addc_u32 s49, s49, 0
	s_add_i32 s50, s72, s3
	global_load_lds_dwordx4 v[146:147], off
	s_mov_b32 m0, s50
	s_nop 0
	global_load_lds_dwordx4 v132, s[48:49]
	s_add_i32 m0, s50, 0x2000
	s_nop 0
	global_load_lds_dwordx4 v136, s[48:49]
	s_add_i32 s70, s70, 2
	s_add_u32 s44, s44, 0x10000
	s_addc_u32 s45, s45, 0
	s_add_u32 s68, s68, 0x10000
	s_addc_u32 s69, s69, 0
	s_add_u32 s46, s44, 0x4000
	s_addc_u32 s47, s45, 0
	s_cmp_eq_u32 s70, 60
	s_cselect_b32 s50, s39, s46
	s_cselect_b32 s51, s17, s47
	s_cselect_b32 s48, s41, s68
	s_cselect_b32 s49, s15, s69
	s_add_u32 s46, s50, 0x8000
	s_addc_u32 s47, s51, 0
	s_sub_u32 s46, s44, 0x4000
	s_subb_u32 s47, s45, 0
	s_cmp_gt_u32 s70, 61
	s_waitcnt vmcnt(6)
	s_waitcnt lgkmcnt(0)
	s_barrier
	s_waitcnt lgkmcnt(0)
	v_mfma_f32_16x16x32_bf16 v[62:65], v[154:157], v[188:191], v[62:65]
	v_mfma_f32_16x16x32_bf16 v[62:65], v[158:161], v[198:201], v[62:65]
	v_mfma_f32_16x16x32_bf16 v[46:49], v[158:161], v[206:209], v[46:49]
	v_mfma_f32_16x16x32_bf16 v[46:49], v[154:157], v[202:205], v[46:49]
	v_mfma_f32_16x16x32_bf16 v[30:33], v[154:157], v[210:213], v[30:33]
	v_mfma_f32_16x16x32_bf16 v[30:33], v[158:161], v[214:217], v[30:33]
	v_mfma_f32_16x16x32_bf16 v[14:17], v[158:161], v[222:225], v[14:17]
	v_mfma_f32_16x16x32_bf16 v[14:17], v[154:157], v[218:221], v[14:17]
	v_mfma_f32_16x16x32_bf16 v[10:13], v[162:165], v[218:221], v[10:13]
	v_mfma_f32_16x16x32_bf16 v[10:13], v[166:169], v[222:225], v[10:13]
	v_mfma_f32_16x16x32_bf16 v[26:29], v[166:169], v[214:217], v[26:29]
	v_mfma_f32_16x16x32_bf16 v[26:29], v[162:165], v[210:213], v[26:29]
	v_mfma_f32_16x16x32_bf16 v[42:45], v[162:165], v[202:205], v[42:45]
	v_mfma_f32_16x16x32_bf16 v[42:45], v[166:169], v[206:209], v[42:45]
	v_mfma_f32_16x16x32_bf16 v[58:61], v[166:169], v[198:201], v[58:61]
	v_mfma_f32_16x16x32_bf16 v[58:61], v[162:165], v[188:191], v[58:61]
	v_mfma_f32_16x16x32_bf16 v[54:57], v[170:173], v[188:191], v[54:57]
	v_mfma_f32_16x16x32_bf16 v[54:57], v[174:177], v[198:201], v[54:57]
	v_mfma_f32_16x16x32_bf16 v[38:41], v[174:177], v[206:209], v[38:41]
	v_mfma_f32_16x16x32_bf16 v[38:41], v[170:173], v[202:205], v[38:41]
	v_mfma_f32_16x16x32_bf16 v[22:25], v[170:173], v[210:213], v[22:25]
	v_mfma_f32_16x16x32_bf16 v[22:25], v[174:177], v[214:217], v[22:25]
	v_mfma_f32_16x16x32_bf16 v[6:9], v[174:177], v[222:225], v[6:9]
	v_mfma_f32_16x16x32_bf16 v[6:9], v[170:173], v[218:221], v[6:9]
	v_mfma_f32_16x16x32_bf16 v[2:5], v[180:183], v[218:221], v[2:5]
	v_mfma_f32_16x16x32_bf16 v[2:5], v[184:187], v[222:225], v[2:5]
	v_mfma_f32_16x16x32_bf16 v[18:21], v[184:187], v[214:217], v[18:21]
	v_mfma_f32_16x16x32_bf16 v[18:21], v[180:183], v[210:213], v[18:21]
	v_mfma_f32_16x16x32_bf16 v[34:37], v[180:183], v[202:205], v[34:37]
	v_mfma_f32_16x16x32_bf16 v[34:37], v[184:187], v[206:209], v[34:37]
	v_mfma_f32_16x16x32_bf16 v[50:53], v[184:187], v[198:201], v[50:53]
	v_mfma_f32_16x16x32_bf16 v[50:53], v[180:183], v[188:191], v[50:53]
	s_barrier
	s_cbranch_scc0 .LBB0_757
	s_and_b64 vcc, exec, s[12:13]
	s_cbranch_vccz .LBB0_760
	s_barrier

;     __device__ __forceinline__ bool next(int i, Unit& u) const { if (i >= 2) return false; const int xcd = c & 7, off = c >> 3; u.pm = 16 * i + 4 * (xcd >> 1) + (off & 3); u.pn = 8 * (xcd & 1) + (off >> 2); return true; }
; #define PG8_STAGE(bufoff, gbase, voff) do { _Pragma("unroll") for (int _i = 0; _i < 2; ++_i) \
;         __builtin_amdgcn_global_load_lds((const unsigned*)((const char*)(gbase) + (voff)[_i]), (PG8_LAS unsigned*)(lds + (bufoff) + ldsw + _i * 8192), 16, 0, 0); } while (0)
; #define PG8_LDA(dst, b, h) do { _Pragma("unroll") for (int m = 0; m < 4; ++m) _Pragma("unroll") for (int k = 0; k < 2; ++k) dst[m][k] = *(const PG8_LAS bf16x8*)(lds + PG8_SA(b, h) + aoff + m * 2048 + k * 1024); } while (0)
; #define PG8_WAIT_V(n) asm volatile("s_waitcnt vmcnt(" #n ")" ::: "memory")
; #define PG8_BAR __builtin_amdgcn_s_barrier()
; template <class Epi, class Sched, bool ALIGN_EPI = false, bool SP2 = false>
; __device__ __forceinline__ void gemm_phase(PG8_LAS unsigned char* lds, const Gemm g, const Sched& S, const Epi& E) {
;     ...
;         const bool has_next = S.next(ui + 1, nxt);
;         const char* nA = has_next ? (const char*)g.A + (size_t)nxt.pm * tstep : cA; const char* nB = has_next ? (const char*)g.Bt + (size_t)nxt.pn * tstep : cB;
;         constexpr int NSEG = Epi::HAS_MID ? 2 : 1; int t = 0;
; #pragma unroll
;         for (int seg = 0; seg < NSEG; ++seg) { const int tend = (seg + 1 < NSEG) ? (nt >> 1) : nt;
;         for (; t < tend; t += 2) {
;             const bool last = (t == nt - 2);
;             const char* a1 = cA + (size_t)(t + 1) * kstep;
;             const char* a2 = last ? nA : cA + (size_t)(t + 2) * kstep; const char* b2 = last ? nB : cB + (size_t)(t + 2) * kstep;
;             const char* a3 = a2 + kstep; const char* b3 = b2 + kstep;
;             if (last && has_next) S.a_ready(nxt);
;             if constexpr (SP2) {
;             PG8_LDB(B0, 0, 0); PG8_LDB(B1, 0, 1); PG8_SCHED; PG8_LDA(At, 0, 0); PG8_STAGE(PG8_SA(1, 1), a1 + hstep, voffA);
;             PG8_WAIT_V(8); PG8_WAIT_L(0); PG8_BAR; PG8_MMA(0, 0, At, B0); PG8_MMA(0, 1, At, B1); PG8_BAR; PG8_SCHED;
;             PG8_LDA(At, 0, 1); PG8_STAGE(PG8_SB(0, 0), b2, voffB); PG8_STAGE(PG8_SB(0, 1), b2 + hstep, voffB); PG8_STAGE(PG8_SA(0, 0), a2, voffA);
;             PG8_WAIT_V(8); PG8_WAIT_L(0); PG8_BAR; PG8_MMA(1, 0, At, B0); PG8_MMA(1, 1, At, B1); PG8_BAR; PG8_SCHED;
.LBB0_839:
	s_ashr_i32 s23, s22, 31
	s_lshl_b64 s[36:37], s[22:23], 21
	s_add_u32 s36, s18, s36
	s_addc_u32 s37, s19, s37
	s_and_b64 s[38:39], s[0:1], exec
	s_cselect_b32 s23, s37, s41
	s_cselect_b32 s65, s36, s40
	s_ashr_i32 s17, s16, 31
	s_lshl_b64 s[38:39], s[16:17], 21
	v_readlane_b32 s17, v255, 13
	s_add_u32 s38, s17, s38
	v_readlane_b32 s17, v255, 14
	s_addc_u32 s39, s17, s39
	s_and_b64 s[44:45], s[0:1], exec
	s_cselect_b32 s17, s39, s43
	s_cselect_b32 s66, s38, s42
	s_add_u32 s40, s40, 0xc000
	s_addc_u32 s41, s41, 0
	s_add_u32 s67, s42, 0x10000
	s_addc_u32 s68, s43, 0
	s_mov_b32 s69, -2
	s_nop 3
	s_add_u32 s42, s40, 0x4000
	s_addc_u32 s43, s41, 0
	s_cmp_eq_u32 s69, 60
	s_cselect_b32 s46, s65, s42
	s_cselect_b32 s47, s23, s43
	s_cselect_b32 s44, s66, s67
	s_cselect_b32 s45, s17, s68
	s_add_u32 s42, s46, 0x8000
	s_addc_u32 s43, s47, 0
	s_sub_u32 s42, s40, 0x4000
	s_subb_u32 s43, s41, 0
	ds_read_b128 v[148:151], v153
	ds_read_b128 v[158:161], v153 offset:1024
	ds_read_b128 v[162:165], v153 offset:2048
	ds_read_b128 v[166:169], v153 offset:3072
	ds_read_b128 v[170:173], v154
	ds_read_b128 v[174:177], v154 offset:1024
	ds_read_b128 v[180:183], v154 offset:2048
	ds_read_b128 v[184:187], v154 offset:3072
	ds_read_b128 v[188:191], v155
	ds_read_b128 v[198:201], v155 offset:1024
	ds_read_b128 v[202:205], v155 offset:2048
	ds_read_b128 v[206:209], v155 offset:3072
	ds_read_b128 v[210:213], v155 offset:4096
	ds_read_b128 v[214:217], v155 offset:5120
	ds_read_b128 v[218:221], v155 offset:6144
	ds_read_b128 v[222:225], v155 offset:7168
	s_mov_b32 m0, s50
	s_nop 0
	global_load_lds_dwordx4 v130, s[42:43]
	s_mov_b32 m0, s51
	s_nop 0
	global_load_lds_dwordx4 v134, s[42:43]
	s_add_i32 m0, s28, 0xc000
	s_nop 0
	global_load_lds_dwordx4 v140, s[40:41]
	s_add_i32 m0, s28, 0xe000
	s_nop 0
	global_load_lds_dwordx4 v142, s[40:41]
	s_waitcnt vmcnt(8)
	s_waitcnt lgkmcnt(0)
	s_barrier
	s_waitcnt lgkmcnt(0)
	v_mfma_f32_16x16x32_bf16 v[126:129], v[148:151], v[188:191], 0
	v_mfma_f32_16x16x32_bf16 v[126:129], v[158:161], v[198:201], v[126:129]
	v_mfma_f32_16x16x32_bf16 v[110:113], v[158:161], v[206:209], 0
	v_mfma_f32_16x16x32_bf16 v[110:113], v[148:151], v[202:205], v[110:113]
	v_mfma_f32_16x16x32_bf16 v[94:97], v[148:151], v[210:213], 0
	v_mfma_f32_16x16x32_bf16 v[94:97], v[158:161], v[214:217], v[94:97]
	v_mfma_f32_16x16x32_bf16 v[78:81], v[158:161], v[222:225], 0
	v_mfma_f32_16x16x32_bf16 v[78:81], v[148:151], v[218:221], v[78:81]
	v_mfma_f32_16x16x32_bf16 v[74:77], v[162:165], v[218:221], 0
	v_mfma_f32_16x16x32_bf16 v[74:77], v[166:169], v[222:225], v[74:77]
	v_mfma_f32_16x16x32_bf16 v[90:93], v[166:169], v[214:217], 0
	v_mfma_f32_16x16x32_bf16 v[90:93], v[162:165], v[210:213], v[90:93]
	v_mfma_f32_16x16x32_bf16 v[106:109], v[162:165], v[202:205], 0
	v_mfma_f32_16x16x32_bf16 v[106:109], v[166:169], v[206:209], v[106:109]
	v_mfma_f32_16x16x32_bf16 v[122:125], v[166:169], v[198:201], 0
	v_mfma_f32_16x16x32_bf16 v[122:125], v[162:165], v[188:191], v[122:125]
	v_mfma_f32_16x16x32_bf16 v[118:121], v[170:173], v[188:191], 0
	v_mfma_f32_16x16x32_bf16 v[118:121], v[174:177], v[198:201], v[118:121]
	v_mfma_f32_16x16x32_bf16 v[102:105], v[174:177], v[206:209], 0
	v_mfma_f32_16x16x32_bf16 v[102:105], v[170:173], v[202:205], v[102:105]
	v_mfma_f32_16x16x32_bf16 v[86:89], v[170:173], v[210:213], 0
	v_mfma_f32_16x16x32_bf16 v[86:89], v[174:177], v[214:217], v[86:89]
	v_mfma_f32_16x16x32_bf16 v[70:73], v[174:177], v[222:225], 0
	v_mfma_f32_16x16x32_bf16 v[70:73], v[170:173], v[218:221], v[70:73]
	v_mfma_f32_16x16x32_bf16 v[66:69], v[180:183], v[218:221], 0
	v_mfma_f32_16x16x32_bf16 v[66:69], v[184:187], v[222:225], v[66:69]
	v_mfma_f32_16x16x32_bf16 v[82:85], v[184:187], v[214:217], 0
	v_mfma_f32_16x16x32_bf16 v[82:85], v[180:183], v[210:213], v[82:85]
	v_mfma_f32_16x16x32_bf16 v[98:101], v[180:183], v[202:205], 0
	v_mfma_f32_16x16x32_bf16 v[98:101], v[184:187], v[206:209], v[98:101]
	v_mfma_f32_16x16x32_bf16 v[114:117], v[184:187], v[198:201], 0
	v_mfma_f32_16x16x32_bf16 v[114:117], v[180:183], v[188:191], v[114:117]
	s_barrier
	s_add_i32 s70, s56, s3
	s_mov_b32 m0, s70
	ds_read_b128 v[188:191], v155 offset:16384
	ds_read_b128 v[198:201], v155 offset:17408
	ds_read_b128 v[202:205], v155 offset:18432
	ds_read_b128 v[206:209], v155 offset:19456
	ds_read_b128 v[210:213], v155 offset:20480
	ds_read_b128 v[214:217], v155 offset:21504
	ds_read_b128 v[218:221], v155 offset:22528
	ds_read_b128 v[222:225], v155 offset:23552
	global_load_lds_dwordx4 v132, s[44:45]
	s_add_i32 m0, s70, 0x2000
	s_add_u32 s70, s44, 0x4000
	s_addc_u32 s71, s45, 0
	s_add_i32 s72, s57, s3
	global_load_lds_dwordx4 v136, s[44:45]
	s_mov_b32 m0, s72
	s_nop 0
	global_load_lds_dwordx4 v132, s[70:71]
	s_add_i32 m0, s72, 0x2000
	s_nop 0
	global_load_lds_dwordx4 v136, s[70:71]
	s_waitcnt vmcnt(6)
	s_waitcnt lgkmcnt(0)
	s_barrier
; #define PG8_STAGE(bufoff, gbase, voff) do { _Pragma("unroll") for (int _i = 0; _i < 2; ++_i) \
;         __builtin_amdgcn_global_load_lds((const unsigned*)((const char*)(gbase) + (voff)[_i]), (PG8_LAS unsigned*)(lds + (bufoff) + ldsw + _i * 8192), 16, 0, 0); } while (0)
; #define PG8_LDA(dst, b, h) do { _Pragma("unroll") for (int m = 0; m < 4; ++m) _Pragma("unroll") for (int k = 0; k < 2; ++k) dst[m][k] = *(const PG8_LAS bf16x8*)(lds + PG8_SA(b, h) + aoff + m * 2048 + k * 1024); } while (0)
; #define PG8_LDB(dst, b, h) do { _Pragma("unroll") for (int n = 0; n < 2; ++n) _Pragma("unroll") for (int k = 0; k < 2; ++k) dst[n][k] = *(const PG8_LAS bf16x8*)(lds + PG8_SB(b, h) + boff + n * 2048 + k * 1024); } while (0)
; #define PG8_MMA(ai, bj, At, Bt) do { __builtin_amdgcn_s_setprio(1); _Pragma("unroll") for (int m = 0; m < 4; ++m) _Pragma("unroll") for (int n = 0; n < 2; ++n) _Pragma("unroll") for (int k = 0; k < 2; ++k) \
;         acc[ai][bj][m][n] = __builtin_amdgcn_mfma_f32_16x16x32_bf16(Bt[n][k], At[m][k], acc[ai][bj][m][n], 0, 0, 0); __builtin_amdgcn_s_setprio(0); } while (0)
; #define PG8_WAIT_V(n) asm volatile("s_waitcnt vmcnt(" #n ")" ::: "memory")
; #define PG8_WAIT_L(n) asm volatile("s_waitcnt lgkmcnt(" #n ")" ::: "memory")
; #define PG8_BAR __builtin_amdgcn_s_barrier()
; #define PG8_SCHED __builtin_amdgcn_sched_barrier(0)
; template <class Epi, class Sched, bool ALIGN_EPI = false, bool SP2 = false>
; __device__ __forceinline__ void gemm_phase(PG8_LAS unsigned char* lds, const Gemm g, const Sched& S, const Epi& E) {
;     ...
;             PG8_WAIT_V(8); PG8_WAIT_L(0); PG8_BAR; PG8_MMA(1, 0, At, B0); PG8_MMA(1, 1, At, B1); PG8_BAR; PG8_SCHED;
;             PG8_LDB(B0, 1, 0); PG8_LDB(B1, 1, 1); PG8_SCHED; PG8_LDA(At, 1, 0); PG8_STAGE(PG8_SA(0, 1), a2 + hstep, voffA);
;             PG8_WAIT_V(8); PG8_WAIT_L(0); PG8_BAR; PG8_MMA(0, 0, At, B0); PG8_MMA(0, 1, At, B1); PG8_BAR; PG8_SCHED;
	s_waitcnt lgkmcnt(0)
	v_mfma_f32_16x16x32_bf16 v[62:65], v[148:151], v[188:191], 0
	v_mfma_f32_16x16x32_bf16 v[62:65], v[158:161], v[198:201], v[62:65]
	v_mfma_f32_16x16x32_bf16 v[46:49], v[158:161], v[206:209], 0
	v_mfma_f32_16x16x32_bf16 v[46:49], v[148:151], v[202:205], v[46:49]
	v_mfma_f32_16x16x32_bf16 v[30:33], v[148:151], v[210:213], 0
	v_mfma_f32_16x16x32_bf16 v[30:33], v[158:161], v[214:217], v[30:33]
	v_mfma_f32_16x16x32_bf16 v[14:17], v[158:161], v[222:225], 0
	v_mfma_f32_16x16x32_bf16 v[14:17], v[148:151], v[218:221], v[14:17]
	v_mfma_f32_16x16x32_bf16 v[10:13], v[162:165], v[218:221], 0
	v_mfma_f32_16x16x32_bf16 v[10:13], v[166:169], v[222:225], v[10:13]
	v_mfma_f32_16x16x32_bf16 v[26:29], v[166:169], v[214:217], 0
	v_mfma_f32_16x16x32_bf16 v[26:29], v[162:165], v[210:213], v[26:29]
	v_mfma_f32_16x16x32_bf16 v[42:45], v[162:165], v[202:205], 0
	v_mfma_f32_16x16x32_bf16 v[42:45], v[166:169], v[206:209], v[42:45]
	v_mfma_f32_16x16x32_bf16 v[58:61], v[166:169], v[198:201], 0
	v_mfma_f32_16x16x32_bf16 v[58:61], v[162:165], v[188:191], v[58:61]
	v_mfma_f32_16x16x32_bf16 v[54:57], v[170:173], v[188:191], 0
	v_mfma_f32_16x16x32_bf16 v[54:57], v[174:177], v[198:201], v[54:57]
	v_mfma_f32_16x16x32_bf16 v[38:41], v[174:177], v[206:209], 0
	v_mfma_f32_16x16x32_bf16 v[38:41], v[170:173], v[202:205], v[38:41]
	v_mfma_f32_16x16x32_bf16 v[22:25], v[170:173], v[210:213], 0
	v_mfma_f32_16x16x32_bf16 v[22:25], v[174:177], v[214:217], v[22:25]
	v_mfma_f32_16x16x32_bf16 v[6:9], v[174:177], v[222:225], 0
	v_mfma_f32_16x16x32_bf16 v[6:9], v[170:173], v[218:221], v[6:9]
	v_mfma_f32_16x16x32_bf16 v[2:5], v[180:183], v[218:221], 0
	v_mfma_f32_16x16x32_bf16 v[2:5], v[184:187], v[222:225], v[2:5]
	v_mfma_f32_16x16x32_bf16 v[18:21], v[184:187], v[214:217], 0
	v_mfma_f32_16x16x32_bf16 v[18:21], v[180:183], v[210:213], v[18:21]
	v_mfma_f32_16x16x32_bf16 v[34:37], v[180:183], v[202:205], 0
	v_mfma_f32_16x16x32_bf16 v[34:37], v[184:187], v[206:209], v[34:37]
	v_mfma_f32_16x16x32_bf16 v[50:53], v[184:187], v[198:201], 0
	v_mfma_f32_16x16x32_bf16 v[50:53], v[180:183], v[188:191], v[50:53]
	s_barrier
	s_add_i32 s70, 0, 0x18000
	v_add_u32_e32 v138, s70, v1
	s_add_i32 s71, 0, 0x1c000
	ds_read_b128 v[148:151], v138
	ds_read_b128 v[158:161], v138 offset:1024
	ds_read_b128 v[162:165], v138 offset:2048
	ds_read_b128 v[166:169], v138 offset:3072
	v_add_u32_e32 v138, s71, v1
	ds_read_b128 v[170:173], v138
	ds_read_b128 v[174:177], v138 offset:1024
	ds_read_b128 v[180:183], v138 offset:2048
	ds_read_b128 v[184:187], v138 offset:3072
	ds_read_b128 v[188:191], v155 offset:32768
	ds_read_b128 v[198:201], v155 offset:33792
	ds_read_b128 v[202:205], v155 offset:34816
	ds_read_b128 v[206:209], v155 offset:35840
	ds_read_b128 v[210:213], v155 offset:36864
	ds_read_b128 v[214:217], v155 offset:37888
	ds_read_b128 v[218:221], v155 offset:38912
	ds_read_b128 v[222:225], v155 offset:39936
	s_mov_b32 m0, s28
	s_nop 0
	global_load_lds_dwordx4 v130, s[46:47]
	s_mov_b32 m0, s29
	s_nop 0
	global_load_lds_dwordx4 v134, s[46:47]
	s_add_u32 s46, s46, 0x4000
	s_addc_u32 s47, s47, 0
	s_mov_b32 m0, s30
	s_nop 0
	global_load_lds_dwordx4 v130, s[46:47]
	s_mov_b32 m0, s31
	s_nop 0
	global_load_lds_dwordx4 v134, s[46:47]
	s_waitcnt vmcnt(8)
	s_waitcnt lgkmcnt(0)
	s_barrier
	s_waitcnt lgkmcnt(0)
	v_mfma_f32_16x16x32_bf16 v[126:129], v[148:151], v[188:191], v[126:129]
	v_mfma_f32_16x16x32_bf16 v[126:129], v[158:161], v[198:201], v[126:129]
	v_mfma_f32_16x16x32_bf16 v[110:113], v[158:161], v[206:209], v[110:113]
	v_mfma_f32_16x16x32_bf16 v[110:113], v[148:151], v[202:205], v[110:113]
	v_mfma_f32_16x16x32_bf16 v[94:97], v[148:151], v[210:213], v[94:97]
	v_mfma_f32_16x16x32_bf16 v[94:97], v[158:161], v[214:217], v[94:97]
	v_mfma_f32_16x16x32_bf16 v[78:81], v[158:161], v[222:225], v[78:81]
	v_mfma_f32_16x16x32_bf16 v[78:81], v[148:151], v[218:221], v[78:81]
	v_mfma_f32_16x16x32_bf16 v[74:77], v[162:165], v[218:221], v[74:77]
	v_mfma_f32_16x16x32_bf16 v[74:77], v[166:169], v[222:225], v[74:77]
	v_mfma_f32_16x16x32_bf16 v[90:93], v[166:169], v[214:217], v[90:93]
	v_mfma_f32_16x16x32_bf16 v[90:93], v[162:165], v[210:213], v[90:93]
	v_mfma_f32_16x16x32_bf16 v[106:109], v[162:165], v[202:205], v[106:109]
	v_mfma_f32_16x16x32_bf16 v[106:109], v[166:169], v[206:209], v[106:109]
	v_mfma_f32_16x16x32_bf16 v[122:125], v[166:169], v[198:201], v[122:125]
	v_mfma_f32_16x16x32_bf16 v[122:125], v[162:165], v[188:191], v[122:125]
	v_mfma_f32_16x16x32_bf16 v[118:121], v[170:173], v[188:191], v[118:121]
	v_mfma_f32_16x16x32_bf16 v[118:121], v[174:177], v[198:201], v[118:121]
	v_mfma_f32_16x16x32_bf16 v[102:105], v[174:177], v[206:209], v[102:105]
	v_mfma_f32_16x16x32_bf16 v[102:105], v[170:173], v[202:205], v[102:105]
	v_mfma_f32_16x16x32_bf16 v[86:89], v[170:173], v[210:213], v[86:89]
	v_mfma_f32_16x16x32_bf16 v[86:89], v[174:177], v[214:217], v[86:89]
	v_mfma_f32_16x16x32_bf16 v[70:73], v[174:177], v[222:225], v[70:73]
	v_mfma_f32_16x16x32_bf16 v[70:73], v[170:173], v[218:221], v[70:73]
	v_mfma_f32_16x16x32_bf16 v[66:69], v[180:183], v[218:221], v[66:69]
	v_mfma_f32_16x16x32_bf16 v[66:69], v[184:187], v[222:225], v[66:69]
	v_mfma_f32_16x16x32_bf16 v[82:85], v[184:187], v[214:217], v[82:85]
	v_mfma_f32_16x16x32_bf16 v[82:85], v[180:183], v[210:213], v[82:85]
	v_mfma_f32_16x16x32_bf16 v[98:101], v[180:183], v[202:205], v[98:101]
	v_mfma_f32_16x16x32_bf16 v[98:101], v[184:187], v[206:209], v[98:101]
	v_mfma_f32_16x16x32_bf16 v[114:117], v[184:187], v[198:201], v[114:117]
	v_mfma_f32_16x16x32_bf16 v[114:117], v[180:183], v[188:191], v[114:117]
	s_barrier
; #define PG8_STAGE(bufoff, gbase, voff) do { _Pragma("unroll") for (int _i = 0; _i < 2; ++_i) \
;         __builtin_amdgcn_global_load_lds((const unsigned*)((const char*)(gbase) + (voff)[_i]), (PG8_LAS unsigned*)(lds + (bufoff) + ldsw + _i * 8192), 16, 0, 0); } while (0)
; #define PG8_LDA(dst, b, h) do { _Pragma("unroll") for (int m = 0; m < 4; ++m) _Pragma("unroll") for (int k = 0; k < 2; ++k) dst[m][k] = *(const PG8_LAS bf16x8*)(lds + PG8_SA(b, h) + aoff + m * 2048 + k * 1024); } while (0)
; #define PG8_LDB(dst, b, h) do { _Pragma("unroll") for (int n = 0; n < 2; ++n) _Pragma("unroll") for (int k = 0; k < 2; ++k) dst[n][k] = *(const PG8_LAS bf16x8*)(lds + PG8_SB(b, h) + boff + n * 2048 + k * 1024); } while (0)
; #define PG8_MMA(ai, bj, At, Bt) do { __builtin_amdgcn_s_setprio(1); _Pragma("unroll") for (int m = 0; m < 4; ++m) _Pragma("unroll") for (int n = 0; n < 2; ++n) _Pragma("unroll") for (int k = 0; k < 2; ++k) \
;         acc[ai][bj][m][n] = __builtin_amdgcn_mfma_f32_16x16x32_bf16(Bt[n][k], At[m][k], acc[ai][bj][m][n], 0, 0, 0); __builtin_amdgcn_s_setprio(0); } while (0)
; #define PG8_WAIT_V(n) asm volatile("s_waitcnt vmcnt(" #n ")" ::: "memory")
; template <class Epi, class Sched, bool ALIGN_EPI = false, bool SP2 = false>
; __device__ __forceinline__ void gemm_phase(PG8_LAS unsigned char* lds, const Gemm g, const Sched& S, const Epi& E) {
;     ...
;             PG8_LDB(B0, 0, 0); PG8_LDB(B1, 0, 1); PG8_SCHED; PG8_LDA(At, 0, 0); PG8_STAGE(PG8_SA(1, 1), a1 + hstep, voffA);
;             PG8_WAIT_V(8); PG8_WAIT_L(0); PG8_BAR; PG8_MMA(0, 0, At, B0); PG8_MMA(0, 1, At, B1); PG8_BAR; PG8_SCHED;
;             PG8_LDA(At, 0, 1); PG8_STAGE(PG8_SB(0, 0), b2, voffB); PG8_STAGE(PG8_SB(0, 1), b2 + hstep, voffB); PG8_STAGE(PG8_SA(0, 0), a2, voffA);
;             PG8_WAIT_V(8); PG8_WAIT_L(0); PG8_BAR; PG8_MMA(1, 0, At, B0); PG8_MMA(1, 1, At, B1); PG8_BAR; PG8_SCHED;
;             PG8_LDB(B0, 1, 0); PG8_LDB(B1, 1, 1); PG8_SCHED; PG8_LDA(At, 1, 0); PG8_STAGE(PG8_SA(0, 1), a2 + hstep, voffA);
;             PG8_WAIT_V(8); PG8_WAIT_L(0); PG8_BAR; PG8_MMA(0, 0, At, B0); PG8_MMA(0, 1, At, B1); PG8_BAR; PG8_SCHED;
;             PG8_LDA(At, 1, 1); PG8_STAGE(PG8_SB(1, 0), b3, voffB); PG8_STAGE(PG8_SB(1, 1), b3 + hstep, voffB); PG8_STAGE(PG8_SA(1, 0), a3, voffA);
;             PG8_WAIT_V(8); PG8_WAIT_L(0); PG8_BAR; PG8_MMA(1, 0, At, B0); PG8_MMA(1, 1, At, B1); PG8_BAR; PG8_SCHED;
	s_add_u32 s46, s44, 0x8000
	s_addc_u32 s47, s45, 0
	s_add_i32 s70, s70, s3
	s_mov_b32 m0, s70
	ds_read_b128 v[188:191], v155 offset:49152
	ds_read_b128 v[198:201], v155 offset:50176
	ds_read_b128 v[202:205], v155 offset:51200
	ds_read_b128 v[206:209], v155 offset:52224
	ds_read_b128 v[210:213], v155 offset:53248
	ds_read_b128 v[214:217], v155 offset:54272
	ds_read_b128 v[218:221], v155 offset:55296
	ds_read_b128 v[222:225], v155 offset:56320
	global_load_lds_dwordx4 v132, s[46:47]
	s_add_i32 m0, s70, 0x2000
	s_add_u32 s44, s44, 0xc000
	v_lshl_add_u64 v[226:227], s[46:47], 0, v[136:137]
	s_addc_u32 s45, s45, 0
	s_add_i32 s46, s71, s3
	global_load_lds_dwordx4 v[226:227], off
	s_mov_b32 m0, s46
	s_nop 0
	global_load_lds_dwordx4 v132, s[44:45]
	s_add_i32 m0, s46, 0x2000
	s_nop 0
	global_load_lds_dwordx4 v136, s[44:45]
	s_add_i32 s69, s69, 2
	s_add_u32 s40, s40, 0x10000
	s_addc_u32 s41, s41, 0
	s_add_u32 s67, s67, 0x10000
	s_addc_u32 s68, s68, 0
	s_add_u32 s42, s40, 0x4000
	s_addc_u32 s43, s41, 0
	s_cmp_eq_u32 s69, 60
	s_cselect_b32 s46, s65, s42
	s_cselect_b32 s47, s23, s43
	s_cselect_b32 s44, s66, s67
	s_cselect_b32 s45, s17, s68
	s_add_u32 s42, s46, 0x8000
	s_addc_u32 s43, s47, 0
	s_sub_u32 s42, s40, 0x4000
	s_subb_u32 s43, s41, 0
	s_cmp_gt_u32 s69, 61
	s_waitcnt vmcnt(6)
	s_waitcnt lgkmcnt(0)
	s_barrier
	s_waitcnt lgkmcnt(0)
	v_mfma_f32_16x16x32_bf16 v[62:65], v[148:151], v[188:191], v[62:65]
	v_mfma_f32_16x16x32_bf16 v[62:65], v[158:161], v[198:201], v[62:65]
	v_mfma_f32_16x16x32_bf16 v[46:49], v[158:161], v[206:209], v[46:49]
	v_mfma_f32_16x16x32_bf16 v[46:49], v[148:151], v[202:205], v[46:49]
	v_mfma_f32_16x16x32_bf16 v[30:33], v[148:151], v[210:213], v[30:33]
	v_mfma_f32_16x16x32_bf16 v[30:33], v[158:161], v[214:217], v[30:33]
	v_mfma_f32_16x16x32_bf16 v[14:17], v[158:161], v[222:225], v[14:17]
	v_mfma_f32_16x16x32_bf16 v[14:17], v[148:151], v[218:221], v[14:17]
	v_mfma_f32_16x16x32_bf16 v[10:13], v[162:165], v[218:221], v[10:13]
	v_mfma_f32_16x16x32_bf16 v[10:13], v[166:169], v[222:225], v[10:13]
	v_mfma_f32_16x16x32_bf16 v[26:29], v[166:169], v[214:217], v[26:29]
	v_mfma_f32_16x16x32_bf16 v[26:29], v[162:165], v[210:213], v[26:29]
	v_mfma_f32_16x16x32_bf16 v[42:45], v[162:165], v[202:205], v[42:45]
	v_mfma_f32_16x16x32_bf16 v[42:45], v[166:169], v[206:209], v[42:45]
	v_mfma_f32_16x16x32_bf16 v[58:61], v[166:169], v[198:201], v[58:61]
	v_mfma_f32_16x16x32_bf16 v[58:61], v[162:165], v[188:191], v[58:61]
	v_mfma_f32_16x16x32_bf16 v[54:57], v[170:173], v[188:191], v[54:57]
	v_mfma_f32_16x16x32_bf16 v[54:57], v[174:177], v[198:201], v[54:57]
	v_mfma_f32_16x16x32_bf16 v[38:41], v[174:177], v[206:209], v[38:41]
	v_mfma_f32_16x16x32_bf16 v[38:41], v[170:173], v[202:205], v[38:41]
	v_mfma_f32_16x16x32_bf16 v[22:25], v[170:173], v[210:213], v[22:25]
	v_mfma_f32_16x16x32_bf16 v[22:25], v[174:177], v[214:217], v[22:25]
	v_mfma_f32_16x16x32_bf16 v[6:9], v[174:177], v[222:225], v[6:9]
	v_mfma_f32_16x16x32_bf16 v[6:9], v[170:173], v[218:221], v[6:9]
	v_mfma_f32_16x16x32_bf16 v[2:5], v[180:183], v[218:221], v[2:5]
	v_mfma_f32_16x16x32_bf16 v[2:5], v[184:187], v[222:225], v[2:5]
	v_mfma_f32_16x16x32_bf16 v[18:21], v[184:187], v[214:217], v[18:21]
	v_mfma_f32_16x16x32_bf16 v[18:21], v[180:183], v[210:213], v[18:21]
	v_mfma_f32_16x16x32_bf16 v[34:37], v[180:183], v[202:205], v[34:37]
	v_mfma_f32_16x16x32_bf16 v[34:37], v[184:187], v[206:209], v[34:37]
	v_mfma_f32_16x16x32_bf16 v[50:53], v[184:187], v[198:201], v[50:53]
	v_mfma_f32_16x16x32_bf16 v[50:53], v[180:183], v[188:191], v[50:53]
	s_barrier
.LBB0_840:
	ds_read_b128 v[148:151], v153
	ds_read_b128 v[158:161], v153 offset:1024
	ds_read_b128 v[162:165], v153 offset:2048
	ds_read_b128 v[166:169], v153 offset:3072
	ds_read_b128 v[170:173], v154
	ds_read_b128 v[174:177], v154 offset:1024
	ds_read_b128 v[180:183], v154 offset:2048
	ds_read_b128 v[184:187], v154 offset:3072
	ds_read_b128 v[188:191], v155
	ds_read_b128 v[198:201], v155 offset:1024
	ds_read_b128 v[202:205], v155 offset:2048
	ds_read_b128 v[206:209], v155 offset:3072
	ds_read_b128 v[210:213], v155 offset:4096
	ds_read_b128 v[214:217], v155 offset:5120
	ds_read_b128 v[218:221], v155 offset:6144
	ds_read_b128 v[222:225], v155 offset:7168
	s_mov_b32 m0, s50
	s_nop 0
	global_load_lds_dwordx4 v130, s[42:43]
	s_mov_b32 m0, s51
	s_nop 0
	global_load_lds_dwordx4 v134, s[42:43]
	s_add_i32 m0, s28, 0xc000
	s_nop 0
	global_load_lds_dwordx4 v140, s[40:41]
	s_add_i32 m0, s28, 0xe000
	s_nop 0
	global_load_lds_dwordx4 v142, s[40:41]
	s_waitcnt vmcnt(8)
	s_waitcnt lgkmcnt(0)
	s_barrier
; #define PG8_STAGE(bufoff, gbase, voff) do { _Pragma("unroll") for (int _i = 0; _i < 2; ++_i) \
;         __builtin_amdgcn_global_load_lds((const unsigned*)((const char*)(gbase) + (voff)[_i]), (PG8_LAS unsigned*)(lds + (bufoff) + ldsw + _i * 8192), 16, 0, 0); } while (0)
; #define PG8_LDA(dst, b, h) do { _Pragma("unroll") for (int m = 0; m < 4; ++m) _Pragma("unroll") for (int k = 0; k < 2; ++k) dst[m][k] = *(const PG8_LAS bf16x8*)(lds + PG8_SA(b, h) + aoff + m * 2048 + k * 1024); } while (0)
; #define PG8_MMA(ai, bj, At, Bt) do { __builtin_amdgcn_s_setprio(1); _Pragma("unroll") for (int m = 0; m < 4; ++m) _Pragma("unroll") for (int n = 0; n < 2; ++n) _Pragma("unroll") for (int k = 0; k < 2; ++k) \
;         acc[ai][bj][m][n] = __builtin_amdgcn_mfma_f32_16x16x32_bf16(Bt[n][k], At[m][k], acc[ai][bj][m][n], 0, 0, 0); __builtin_amdgcn_s_setprio(0); } while (0)
; #define PG8_WAIT_V(n) asm volatile("s_waitcnt vmcnt(" #n ")" ::: "memory")
; #define PG8_WAIT_L(n) asm volatile("s_waitcnt lgkmcnt(" #n ")" ::: "memory")
; #define PG8_BAR __builtin_amdgcn_s_barrier()
; #define PG8_SCHED __builtin_amdgcn_sched_barrier(0)
; template <class Epi, class Sched, bool ALIGN_EPI = false, bool SP2 = false>
; __device__ __forceinline__ void gemm_phase(PG8_LAS unsigned char* lds, const Gemm g, const Sched& S, const Epi& E) {
;     ...
;             PG8_WAIT_V(8); PG8_WAIT_L(0); PG8_BAR; PG8_MMA(0, 0, At, B0); PG8_MMA(0, 1, At, B1); PG8_BAR; PG8_SCHED;
;             PG8_LDA(At, 0, 1); PG8_STAGE(PG8_SB(0, 0), b2, voffB); PG8_STAGE(PG8_SB(0, 1), b2 + hstep, voffB); PG8_STAGE(PG8_SA(0, 0), a2, voffA);
;             PG8_WAIT_V(8); PG8_WAIT_L(0); PG8_BAR; PG8_MMA(1, 0, At, B0); PG8_MMA(1, 1, At, B1); PG8_BAR; PG8_SCHED;
	s_waitcnt lgkmcnt(0)
	v_mfma_f32_16x16x32_bf16 v[126:129], v[148:151], v[188:191], v[126:129]
	v_mfma_f32_16x16x32_bf16 v[126:129], v[158:161], v[198:201], v[126:129]
	v_mfma_f32_16x16x32_bf16 v[110:113], v[158:161], v[206:209], v[110:113]
	v_mfma_f32_16x16x32_bf16 v[110:113], v[148:151], v[202:205], v[110:113]
	v_mfma_f32_16x16x32_bf16 v[94:97], v[148:151], v[210:213], v[94:97]
	v_mfma_f32_16x16x32_bf16 v[94:97], v[158:161], v[214:217], v[94:97]
	v_mfma_f32_16x16x32_bf16 v[78:81], v[158:161], v[222:225], v[78:81]
	v_mfma_f32_16x16x32_bf16 v[78:81], v[148:151], v[218:221], v[78:81]
	v_mfma_f32_16x16x32_bf16 v[74:77], v[162:165], v[218:221], v[74:77]
	v_mfma_f32_16x16x32_bf16 v[74:77], v[166:169], v[222:225], v[74:77]
	v_mfma_f32_16x16x32_bf16 v[90:93], v[166:169], v[214:217], v[90:93]
	v_mfma_f32_16x16x32_bf16 v[90:93], v[162:165], v[210:213], v[90:93]
	v_mfma_f32_16x16x32_bf16 v[106:109], v[162:165], v[202:205], v[106:109]
	v_mfma_f32_16x16x32_bf16 v[106:109], v[166:169], v[206:209], v[106:109]
	v_mfma_f32_16x16x32_bf16 v[122:125], v[166:169], v[198:201], v[122:125]
	v_mfma_f32_16x16x32_bf16 v[122:125], v[162:165], v[188:191], v[122:125]
	v_mfma_f32_16x16x32_bf16 v[118:121], v[170:173], v[188:191], v[118:121]
	v_mfma_f32_16x16x32_bf16 v[118:121], v[174:177], v[198:201], v[118:121]
	v_mfma_f32_16x16x32_bf16 v[102:105], v[174:177], v[206:209], v[102:105]
	v_mfma_f32_16x16x32_bf16 v[102:105], v[170:173], v[202:205], v[102:105]
	v_mfma_f32_16x16x32_bf16 v[86:89], v[170:173], v[210:213], v[86:89]
	v_mfma_f32_16x16x32_bf16 v[86:89], v[174:177], v[214:217], v[86:89]
	v_mfma_f32_16x16x32_bf16 v[70:73], v[174:177], v[222:225], v[70:73]
	v_mfma_f32_16x16x32_bf16 v[70:73], v[170:173], v[218:221], v[70:73]
	v_mfma_f32_16x16x32_bf16 v[66:69], v[180:183], v[218:221], v[66:69]
	v_mfma_f32_16x16x32_bf16 v[66:69], v[184:187], v[222:225], v[66:69]
	v_mfma_f32_16x16x32_bf16 v[82:85], v[184:187], v[214:217], v[82:85]
	v_mfma_f32_16x16x32_bf16 v[82:85], v[180:183], v[210:213], v[82:85]
	v_mfma_f32_16x16x32_bf16 v[98:101], v[180:183], v[202:205], v[98:101]
	v_mfma_f32_16x16x32_bf16 v[98:101], v[184:187], v[206:209], v[98:101]
	v_mfma_f32_16x16x32_bf16 v[114:117], v[184:187], v[198:201], v[114:117]
	v_mfma_f32_16x16x32_bf16 v[114:117], v[180:183], v[188:191], v[114:117]
	s_barrier
	s_add_i32 s70, s56, s3
	s_mov_b32 m0, s70
	ds_read_b128 v[188:191], v155 offset:16384
	ds_read_b128 v[198:201], v155 offset:17408
	ds_read_b128 v[202:205], v155 offset:18432
	ds_read_b128 v[206:209], v155 offset:19456
	ds_read_b128 v[210:213], v155 offset:20480
	ds_read_b128 v[214:217], v155 offset:21504
	ds_read_b128 v[218:221], v155 offset:22528
	ds_read_b128 v[222:225], v155 offset:23552
	global_load_lds_dwordx4 v132, s[44:45]
	s_add_i32 m0, s70, 0x2000
	s_add_u32 s70, s44, 0x4000
	s_addc_u32 s71, s45, 0
	s_add_i32 s72, s57, s3
	global_load_lds_dwordx4 v136, s[44:45]
	s_mov_b32 m0, s72
	s_nop 0
	global_load_lds_dwordx4 v132, s[70:71]
	s_add_i32 m0, s72, 0x2000
	s_nop 0
	global_load_lds_dwordx4 v136, s[70:71]
	s_waitcnt vmcnt(6)
	s_waitcnt lgkmcnt(0)
	s_barrier
	s_waitcnt lgkmcnt(0)
	v_mfma_f32_16x16x32_bf16 v[62:65], v[148:151], v[188:191], v[62:65]
	v_mfma_f32_16x16x32_bf16 v[62:65], v[158:161], v[198:201], v[62:65]
	v_mfma_f32_16x16x32_bf16 v[46:49], v[158:161], v[206:209], v[46:49]
	v_mfma_f32_16x16x32_bf16 v[46:49], v[148:151], v[202:205], v[46:49]
	v_mfma_f32_16x16x32_bf16 v[30:33], v[148:151], v[210:213], v[30:33]
	v_mfma_f32_16x16x32_bf16 v[30:33], v[158:161], v[214:217], v[30:33]
	v_mfma_f32_16x16x32_bf16 v[14:17], v[158:161], v[222:225], v[14:17]
	v_mfma_f32_16x16x32_bf16 v[14:17], v[148:151], v[218:221], v[14:17]
	v_mfma_f32_16x16x32_bf16 v[10:13], v[162:165], v[218:221], v[10:13]
	v_mfma_f32_16x16x32_bf16 v[10:13], v[166:169], v[222:225], v[10:13]
	v_mfma_f32_16x16x32_bf16 v[26:29], v[166:169], v[214:217], v[26:29]
	v_mfma_f32_16x16x32_bf16 v[26:29], v[162:165], v[210:213], v[26:29]
	v_mfma_f32_16x16x32_bf16 v[42:45], v[162:165], v[202:205], v[42:45]
	v_mfma_f32_16x16x32_bf16 v[42:45], v[166:169], v[206:209], v[42:45]
	v_mfma_f32_16x16x32_bf16 v[58:61], v[166:169], v[198:201], v[58:61]
	v_mfma_f32_16x16x32_bf16 v[58:61], v[162:165], v[188:191], v[58:61]
	v_mfma_f32_16x16x32_bf16 v[54:57], v[170:173], v[188:191], v[54:57]
	v_mfma_f32_16x16x32_bf16 v[54:57], v[174:177], v[198:201], v[54:57]
	v_mfma_f32_16x16x32_bf16 v[38:41], v[174:177], v[206:209], v[38:41]
	v_mfma_f32_16x16x32_bf16 v[38:41], v[170:173], v[202:205], v[38:41]
	v_mfma_f32_16x16x32_bf16 v[22:25], v[170:173], v[210:213], v[22:25]
	v_mfma_f32_16x16x32_bf16 v[22:25], v[174:177], v[214:217], v[22:25]
	v_mfma_f32_16x16x32_bf16 v[6:9], v[174:177], v[222:225], v[6:9]
	v_mfma_f32_16x16x32_bf16 v[6:9], v[170:173], v[218:221], v[6:9]
	v_mfma_f32_16x16x32_bf16 v[2:5], v[180:183], v[218:221], v[2:5]
	v_mfma_f32_16x16x32_bf16 v[2:5], v[184:187], v[222:225], v[2:5]
	v_mfma_f32_16x16x32_bf16 v[18:21], v[184:187], v[214:217], v[18:21]
	v_mfma_f32_16x16x32_bf16 v[18:21], v[180:183], v[210:213], v[18:21]
	v_mfma_f32_16x16x32_bf16 v[34:37], v[180:183], v[202:205], v[34:37]
	v_mfma_f32_16x16x32_bf16 v[34:37], v[184:187], v[206:209], v[34:37]
	v_mfma_f32_16x16x32_bf16 v[50:53], v[184:187], v[198:201], v[50:53]
	v_mfma_f32_16x16x32_bf16 v[50:53], v[180:183], v[188:191], v[50:53]
	s_barrier
; #define PG8_STAGE(bufoff, gbase, voff) do { _Pragma("unroll") for (int _i = 0; _i < 2; ++_i) \
;         __builtin_amdgcn_global_load_lds((const unsigned*)((const char*)(gbase) + (voff)[_i]), (PG8_LAS unsigned*)(lds + (bufoff) + ldsw + _i * 8192), 16, 0, 0); } while (0)
; #define PG8_LDA(dst, b, h) do { _Pragma("unroll") for (int m = 0; m < 4; ++m) _Pragma("unroll") for (int k = 0; k < 2; ++k) dst[m][k] = *(const PG8_LAS bf16x8*)(lds + PG8_SA(b, h) + aoff + m * 2048 + k * 1024); } while (0)
; #define PG8_LDB(dst, b, h) do { _Pragma("unroll") for (int n = 0; n < 2; ++n) _Pragma("unroll") for (int k = 0; k < 2; ++k) dst[n][k] = *(const PG8_LAS bf16x8*)(lds + PG8_SB(b, h) + boff + n * 2048 + k * 1024); } while (0)
; #define PG8_MMA(ai, bj, At, Bt) do { __builtin_amdgcn_s_setprio(1); _Pragma("unroll") for (int m = 0; m < 4; ++m) _Pragma("unroll") for (int n = 0; n < 2; ++n) _Pragma("unroll") for (int k = 0; k < 2; ++k) \
;         acc[ai][bj][m][n] = __builtin_amdgcn_mfma_f32_16x16x32_bf16(Bt[n][k], At[m][k], acc[ai][bj][m][n], 0, 0, 0); __builtin_amdgcn_s_setprio(0); } while (0)
; #define PG8_WAIT_V(n) asm volatile("s_waitcnt vmcnt(" #n ")" ::: "memory")
; #define PG8_WAIT_L(n) asm volatile("s_waitcnt lgkmcnt(" #n ")" ::: "memory")
; #define PG8_BAR __builtin_amdgcn_s_barrier()
; #define PG8_SCHED __builtin_amdgcn_sched_barrier(0)
; template <class Epi, class Sched, bool ALIGN_EPI = false, bool SP2 = false>
; __device__ __forceinline__ void gemm_phase(PG8_LAS unsigned char* lds, const Gemm g, const Sched& S, const Epi& E) {
;     ...
;             PG8_LDB(B0, 1, 0); PG8_LDB(B1, 1, 1); PG8_SCHED; PG8_LDA(At, 1, 0); PG8_STAGE(PG8_SA(0, 1), a2 + hstep, voffA);
;             PG8_WAIT_V(8); PG8_WAIT_L(0); PG8_BAR; PG8_MMA(0, 0, At, B0); PG8_MMA(0, 1, At, B1); PG8_BAR; PG8_SCHED;
	s_add_i32 s70, 0, 0x18000
	v_add_u32_e32 v138, s70, v1
	s_add_i32 s71, 0, 0x1c000
	ds_read_b128 v[148:151], v138
	ds_read_b128 v[158:161], v138 offset:1024
	ds_read_b128 v[162:165], v138 offset:2048
	ds_read_b128 v[166:169], v138 offset:3072
	v_add_u32_e32 v138, s71, v1
	ds_read_b128 v[170:173], v138
	ds_read_b128 v[174:177], v138 offset:1024
	ds_read_b128 v[180:183], v138 offset:2048
	ds_read_b128 v[184:187], v138 offset:3072
	ds_read_b128 v[188:191], v155 offset:32768
	ds_read_b128 v[198:201], v155 offset:33792
	ds_read_b128 v[202:205], v155 offset:34816
	ds_read_b128 v[206:209], v155 offset:35840
	ds_read_b128 v[210:213], v155 offset:36864
	ds_read_b128 v[214:217], v155 offset:37888
	ds_read_b128 v[218:221], v155 offset:38912
	ds_read_b128 v[222:225], v155 offset:39936
	s_mov_b32 m0, s28
	s_nop 0
	global_load_lds_dwordx4 v130, s[46:47]
	s_mov_b32 m0, s29
	s_nop 0
	global_load_lds_dwordx4 v134, s[46:47]
	s_add_u32 s46, s46, 0x4000
	s_addc_u32 s47, s47, 0
	s_mov_b32 m0, s30
	s_nop 0
	global_load_lds_dwordx4 v130, s[46:47]
	s_mov_b32 m0, s31
	s_nop 0
	global_load_lds_dwordx4 v134, s[46:47]
	s_waitcnt vmcnt(8)
	s_waitcnt lgkmcnt(0)
	s_barrier
	s_waitcnt lgkmcnt(0)
	v_mfma_f32_16x16x32_bf16 v[126:129], v[148:151], v[188:191], v[126:129]
	v_mfma_f32_16x16x32_bf16 v[126:129], v[158:161], v[198:201], v[126:129]
	v_mfma_f32_16x16x32_bf16 v[110:113], v[158:161], v[206:209], v[110:113]
	v_mfma_f32_16x16x32_bf16 v[110:113], v[148:151], v[202:205], v[110:113]
	v_mfma_f32_16x16x32_bf16 v[94:97], v[148:151], v[210:213], v[94:97]
	v_mfma_f32_16x16x32_bf16 v[94:97], v[158:161], v[214:217], v[94:97]
	v_mfma_f32_16x16x32_bf16 v[78:81], v[158:161], v[222:225], v[78:81]
	v_mfma_f32_16x16x32_bf16 v[78:81], v[148:151], v[218:221], v[78:81]
	v_mfma_f32_16x16x32_bf16 v[74:77], v[162:165], v[218:221], v[74:77]
	v_mfma_f32_16x16x32_bf16 v[74:77], v[166:169], v[222:225], v[74:77]
	v_mfma_f32_16x16x32_bf16 v[90:93], v[166:169], v[214:217], v[90:93]
	v_mfma_f32_16x16x32_bf16 v[90:93], v[162:165], v[210:213], v[90:93]
	v_mfma_f32_16x16x32_bf16 v[106:109], v[162:165], v[202:205], v[106:109]
	v_mfma_f32_16x16x32_bf16 v[106:109], v[166:169], v[206:209], v[106:109]
	v_mfma_f32_16x16x32_bf16 v[122:125], v[166:169], v[198:201], v[122:125]
	v_mfma_f32_16x16x32_bf16 v[122:125], v[162:165], v[188:191], v[122:125]
	v_mfma_f32_16x16x32_bf16 v[118:121], v[170:173], v[188:191], v[118:121]
	v_mfma_f32_16x16x32_bf16 v[118:121], v[174:177], v[198:201], v[118:121]
	v_mfma_f32_16x16x32_bf16 v[102:105], v[174:177], v[206:209], v[102:105]
	v_mfma_f32_16x16x32_bf16 v[102:105], v[170:173], v[202:205], v[102:105]
	v_mfma_f32_16x16x32_bf16 v[86:89], v[170:173], v[210:213], v[86:89]
	v_mfma_f32_16x16x32_bf16 v[86:89], v[174:177], v[214:217], v[86:89]
	v_mfma_f32_16x16x32_bf16 v[70:73], v[174:177], v[222:225], v[70:73]
	v_mfma_f32_16x16x32_bf16 v[70:73], v[170:173], v[218:221], v[70:73]
	v_mfma_f32_16x16x32_bf16 v[66:69], v[180:183], v[218:221], v[66:69]
	v_mfma_f32_16x16x32_bf16 v[66:69], v[184:187], v[222:225], v[66:69]
	v_mfma_f32_16x16x32_bf16 v[82:85], v[184:187], v[214:217], v[82:85]
	v_mfma_f32_16x16x32_bf16 v[82:85], v[180:183], v[210:213], v[82:85]
	v_mfma_f32_16x16x32_bf16 v[98:101], v[180:183], v[202:205], v[98:101]
	v_mfma_f32_16x16x32_bf16 v[98:101], v[184:187], v[206:209], v[98:101]
	v_mfma_f32_16x16x32_bf16 v[114:117], v[184:187], v[198:201], v[114:117]
	v_mfma_f32_16x16x32_bf16 v[114:117], v[180:183], v[188:191], v[114:117]
	s_barrier
; #define PG8_STAGE(bufoff, gbase, voff) do { _Pragma("unroll") for (int _i = 0; _i < 2; ++_i) \
;         __builtin_amdgcn_global_load_lds((const unsigned*)((const char*)(gbase) + (voff)[_i]), (PG8_LAS unsigned*)(lds + (bufoff) + ldsw + _i * 8192), 16, 0, 0); } while (0)
; #define PG8_LDA(dst, b, h) do { _Pragma("unroll") for (int m = 0; m < 4; ++m) _Pragma("unroll") for (int k = 0; k < 2; ++k) dst[m][k] = *(const PG8_LAS bf16x8*)(lds + PG8_SA(b, h) + aoff + m * 2048 + k * 1024); } while (0)
; #define PG8_LDB(dst, b, h) do { _Pragma("unroll") for (int n = 0; n < 2; ++n) _Pragma("unroll") for (int k = 0; k < 2; ++k) dst[n][k] = *(const PG8_LAS bf16x8*)(lds + PG8_SB(b, h) + boff + n * 2048 + k * 1024); } while (0)
; template <class Epi, class Sched, bool ALIGN_EPI = false, bool SP2 = false>
; __device__ __forceinline__ void gemm_phase(PG8_LAS unsigned char* lds, const Gemm g, const Sched& S, const Epi& E) {
;     ...
;         for (; t < tend; t += 2) {
;             const bool last = (t == nt - 2);
;             const char* a1 = cA + (size_t)(t + 1) * kstep;
;             const char* a2 = last ? nA : cA + (size_t)(t + 2) * kstep; const char* b2 = last ? nB : cB + (size_t)(t + 2) * kstep;
;             const char* a3 = a2 + kstep; const char* b3 = b2 + kstep;
;             if (last && has_next) S.a_ready(nxt);
;             if constexpr (SP2) {
;             PG8_LDB(B0, 0, 0); PG8_LDB(B1, 0, 1); PG8_SCHED; PG8_LDA(At, 0, 0); PG8_STAGE(PG8_SA(1, 1), a1 + hstep, voffA);
;             PG8_WAIT_V(8); PG8_WAIT_L(0); PG8_BAR; PG8_MMA(0, 0, At, B0); PG8_MMA(0, 1, At, B1); PG8_BAR; PG8_SCHED;
;             PG8_LDA(At, 0, 1); PG8_STAGE(PG8_SB(0, 0), b2, voffB); PG8_STAGE(PG8_SB(0, 1), b2 + hstep, voffB); PG8_STAGE(PG8_SA(0, 0), a2, voffA);
;             PG8_WAIT_V(8); PG8_WAIT_L(0); PG8_BAR; PG8_MMA(1, 0, At, B0); PG8_MMA(1, 1, At, B1); PG8_BAR; PG8_SCHED;
;             PG8_LDB(B0, 1, 0); PG8_LDB(B1, 1, 1); PG8_SCHED; PG8_LDA(At, 1, 0); PG8_STAGE(PG8_SA(0, 1), a2 + hstep, voffA);
;             PG8_WAIT_V(8); PG8_WAIT_L(0); PG8_BAR; PG8_MMA(0, 0, At, B0); PG8_MMA(0, 1, At, B1); PG8_BAR; PG8_SCHED;
;             PG8_LDA(At, 1, 1); PG8_STAGE(PG8_SB(1, 0), b3, voffB); PG8_STAGE(PG8_SB(1, 1), b3 + hstep, voffB); PG8_STAGE(PG8_SA(1, 0), a3, voffA);
;             PG8_WAIT_V(8); PG8_WAIT_L(0); PG8_BAR; PG8_MMA(1, 0, At, B0); PG8_MMA(1, 1, At, B1); PG8_BAR; PG8_SCHED;
	s_add_u32 s46, s44, 0x8000
	s_addc_u32 s47, s45, 0
	s_add_i32 s70, s70, s3
	s_mov_b32 m0, s70
	ds_read_b128 v[188:191], v155 offset:49152
	ds_read_b128 v[198:201], v155 offset:50176
	ds_read_b128 v[202:205], v155 offset:51200
	ds_read_b128 v[206:209], v155 offset:52224
	ds_read_b128 v[210:213], v155 offset:53248
	ds_read_b128 v[214:217], v155 offset:54272
	ds_read_b128 v[218:221], v155 offset:55296
	ds_read_b128 v[222:225], v155 offset:56320
	global_load_lds_dwordx4 v132, s[46:47]
	s_add_i32 m0, s70, 0x2000
	s_add_u32 s44, s44, 0xc000
	v_lshl_add_u64 v[226:227], s[46:47], 0, v[136:137]
	s_addc_u32 s45, s45, 0
	s_add_i32 s46, s71, s3
	global_load_lds_dwordx4 v[226:227], off
	s_mov_b32 m0, s46
	s_nop 0
	global_load_lds_dwordx4 v132, s[44:45]
	s_add_i32 m0, s46, 0x2000
	s_nop 0
	global_load_lds_dwordx4 v136, s[44:45]
	s_add_i32 s69, s69, 2
	s_add_u32 s40, s40, 0x10000
	s_addc_u32 s41, s41, 0
	s_add_u32 s67, s67, 0x10000
	s_addc_u32 s68, s68, 0
	s_add_u32 s42, s40, 0x4000
	s_addc_u32 s43, s41, 0
	s_cmp_eq_u32 s69, 60
	s_cselect_b32 s46, s65, s42
	s_cselect_b32 s47, s23, s43
	s_cselect_b32 s44, s66, s67
	s_cselect_b32 s45, s17, s68
	s_add_u32 s42, s46, 0x8000
	s_addc_u32 s43, s47, 0
	s_sub_u32 s42, s40, 0x4000
	s_subb_u32 s43, s41, 0
	s_cmp_gt_u32 s69, 61
	s_waitcnt vmcnt(6)
	s_waitcnt lgkmcnt(0)
	s_barrier
	s_waitcnt lgkmcnt(0)
	v_mfma_f32_16x16x32_bf16 v[62:65], v[148:151], v[188:191], v[62:65]
	v_mfma_f32_16x16x32_bf16 v[62:65], v[158:161], v[198:201], v[62:65]
	v_mfma_f32_16x16x32_bf16 v[46:49], v[158:161], v[206:209], v[46:49]
	v_mfma_f32_16x16x32_bf16 v[46:49], v[148:151], v[202:205], v[46:49]
	v_mfma_f32_16x16x32_bf16 v[30:33], v[148:151], v[210:213], v[30:33]
	v_mfma_f32_16x16x32_bf16 v[30:33], v[158:161], v[214:217], v[30:33]
	v_mfma_f32_16x16x32_bf16 v[14:17], v[158:161], v[222:225], v[14:17]
	v_mfma_f32_16x16x32_bf16 v[14:17], v[148:151], v[218:221], v[14:17]
	v_mfma_f32_16x16x32_bf16 v[10:13], v[162:165], v[218:221], v[10:13]
	v_mfma_f32_16x16x32_bf16 v[10:13], v[166:169], v[222:225], v[10:13]
	v_mfma_f32_16x16x32_bf16 v[26:29], v[166:169], v[214:217], v[26:29]
	v_mfma_f32_16x16x32_bf16 v[26:29], v[162:165], v[210:213], v[26:29]
	v_mfma_f32_16x16x32_bf16 v[42:45], v[162:165], v[202:205], v[42:45]
	v_mfma_f32_16x16x32_bf16 v[42:45], v[166:169], v[206:209], v[42:45]
	v_mfma_f32_16x16x32_bf16 v[58:61], v[166:169], v[198:201], v[58:61]
	v_mfma_f32_16x16x32_bf16 v[58:61], v[162:165], v[188:191], v[58:61]
	v_mfma_f32_16x16x32_bf16 v[54:57], v[170:173], v[188:191], v[54:57]
	v_mfma_f32_16x16x32_bf16 v[54:57], v[174:177], v[198:201], v[54:57]
	v_mfma_f32_16x16x32_bf16 v[38:41], v[174:177], v[206:209], v[38:41]
	v_mfma_f32_16x16x32_bf16 v[38:41], v[170:173], v[202:205], v[38:41]
	v_mfma_f32_16x16x32_bf16 v[22:25], v[170:173], v[210:213], v[22:25]
	v_mfma_f32_16x16x32_bf16 v[22:25], v[174:177], v[214:217], v[22:25]
	v_mfma_f32_16x16x32_bf16 v[6:9], v[174:177], v[222:225], v[6:9]
	v_mfma_f32_16x16x32_bf16 v[6:9], v[170:173], v[218:221], v[6:9]
	v_mfma_f32_16x16x32_bf16 v[2:5], v[180:183], v[218:221], v[2:5]
	v_mfma_f32_16x16x32_bf16 v[2:5], v[184:187], v[222:225], v[2:5]
	v_mfma_f32_16x16x32_bf16 v[18:21], v[184:187], v[214:217], v[18:21]
	v_mfma_f32_16x16x32_bf16 v[18:21], v[180:183], v[210:213], v[18:21]
	v_mfma_f32_16x16x32_bf16 v[34:37], v[180:183], v[202:205], v[34:37]
	v_mfma_f32_16x16x32_bf16 v[34:37], v[184:187], v[206:209], v[34:37]
	v_mfma_f32_16x16x32_bf16 v[50:53], v[184:187], v[198:201], v[50:53]
	v_mfma_f32_16x16x32_bf16 v[50:53], v[180:183], v[188:191], v[50:53]
	s_barrier
	s_cbranch_scc0 .LBB0_840
	s_and_b64 vcc, exec, s[14:15]
	s_cbranch_vccz .LBB0_843
	s_barrier
